# gmlp: the 16 spatial-weight MFMA operand loads pre-issued before the LayerNorm part into idle registers (MFMA B operands retargeted), removing ~10 serialized waits per item; on top of v38
# baseline (speedup 1.0000x reference)
; #define LAS __attribute__((address_space(3)))
; __device__ __forceinline__ float bf_lo(unsigned w) { return __uint_as_float(w << 16); }
; __device__ __forceinline__ float bf_hi(unsigned w) { return __uint_as_float(w & 0xffff0000u); }
; __device__ __forceinline__ float gelu_tanh(float x) { const float z = 0.7978845608028654f * (x + 0.044715f * x * x * x); return x * sigmoidf_(2.0f * z); }
; __device__ __forceinline__ void gmlp_conv_item(const Params& p, int l, int hs, int chunk, LAS unsigned char* lds) {
;     ...
;           for (int i = 0; i < 8; ++i) w[i] = *(const u32x2*)(P + (size_t)(v0 + wid * 16 + hb * 8 + i) * PROJ + OFF_GV + 4 * lane);
; #pragma unroll
;           for (int i = 0; i < 8; ++i) { x[i][0] = gelu_tanh(bf_lo(w[i].x)); x[i][1] = gelu_tanh(bf_hi(w[i].x)); x[i][2] = gelu_tanh(bf_lo(w[i].y)); x[i][3] = gelu_tanh(bf_hi(w[i].y));
;               sm[i] = (x[i][0] + x[i][1]) + (x[i][2] + x[i][3]); }
;     ...
;       const bf16_t* wsb = (const bf16_t*)(p.ws + WS_WT) + (size_t)l * W_LAYER + W_GWS + (size_t)g * 128 * 128;
;       f32x4 acc[4][4];
; #pragma unroll
;       for (int a = 0; a < 4; ++a)
; #pragma unroll
;           for (int b = 0; b < 4; ++b) acc[a][b] = (f32x4){0.f, 0.f, 0.f, 0.f};
; #pragma unroll
;       for (int kk = 0; kk < 4; ++kk) {
;           bf16x8 af[4], bfr[4];
; #pragma unroll
;           for (int db = 0; db < 4; ++db) af[db] = *(const LAS bf16x8*)(vT + (g * 64 + db * 16 + fr) * 136 + kk * 32 + fq * 8);
; #pragma unroll
;           for (int pb = 0; pb < 4; ++pb) bfr[pb] = *(const bf16x8*)(wsb + (size_t)((ph * 4 + pb) * 16 + fr) * 128 + kk * 32 + fq * 8);
.LBB0_173:
	v_lshrrev_b32_e32 v188, 7, v88
	v_lshlrev_b32_e32 v188, 15, v188
	v_and_b32_e32 v189, 48, v88
	v_add_u32_e32 v188, v188, v189
	v_bfe_u32 v189, v88, 6, 1
	v_lshl_add_u32 v188, v189, 14, v188
	v_and_b32_e32 v189, 15, v88
	v_lshl_add_u32 v188, v189, 8, v188
	v_mov_b32_e32 v189, 0
	v_lshl_add_u64 v[186:187], s[16:17], 0, v[188:189]
	v_mov_b32_e32 v196, 0x1000
	v_mov_b32_e32 v197, 0
	v_lshl_add_u64 v[190:191], v[186:187], 0, v[196:197]
	v_lshl_add_u64 v[192:193], v[190:191], 0, v[196:197]
	v_lshl_add_u64 v[194:195], v[192:193], 0, v[196:197]
	global_load_dwordx4 v[122:125], v[186:187], off
	global_load_dwordx4 v[126:129], v[190:191], off
	global_load_dwordx4 v[130:133], v[192:193], off
	global_load_dwordx4 v[134:137], v[194:195], off
	global_load_dwordx4 v[138:141], v[190:191], off offset:64
	global_load_dwordx4 v[142:145], v[192:193], off offset:64
	global_load_dwordx4 v[146:149], v[194:195], off offset:64
	global_load_dwordx4 v[150:153], v[186:187], off offset:64
	global_load_dwordx4 v[154:157], v[186:187], off offset:128
	global_load_dwordx4 v[158:161], v[192:193], off offset:128
	global_load_dwordx4 v[162:165], v[190:191], off offset:128
	global_load_dwordx4 v[166:169], v[194:195], off offset:128
	global_load_dwordx4 v[170:173], v[186:187], off offset:192
	global_load_dwordx4 v[174:177], v[190:191], off offset:192
	global_load_dwordx4 v[178:181], v[192:193], off offset:192
	global_load_dwordx4 v[182:185], v[194:195], off offset:192
	v_ashrrev_i32_e32 v89, 6, v88
	v_and_b32_e32 v96, 63, v88
	v_lshl_add_u32 v97, v89, 4, s20
	v_mov_b64_e32 v[66:67], s[52:53]
	v_mad_i64_i32 v[2:3], s[0:1], v97, s97, v[66:67]
	v_lshlrev_b32_e32 v0, 3, v96
	v_lshl_add_u64 v[2:3], v[2:3], 0, v[0:1]
	global_load_dwordx2 v[14:15], v[2:3], off offset:2048
	v_or_b32_e32 v2, 1, v97
	v_mad_i64_i32 v[2:3], s[0:1], v2, s97, v[66:67]
	v_lshl_add_u64 v[2:3], v[2:3], 0, v[0:1]
	global_load_dwordx2 v[20:21], v[2:3], off offset:2048
	v_or_b32_e32 v10, 2, v97
	v_or_b32_e32 v12, 3, v97
	v_or_b32_e32 v16, 4, v97
	v_or_b32_e32 v18, 5, v97
	v_or_b32_e32 v22, 6, v97
	v_or_b32_e32 v24, 7, v97
	v_mad_i64_i32 v[10:11], s[0:1], v10, s97, v[66:67]
	v_lshlrev_b32_e32 v6, 4, v96
	v_mad_i64_i32 v[12:13], s[0:1], v12, s97, v[66:67]
	v_mad_i64_i32 v[16:17], s[0:1], v16, s97, v[66:67]
	v_mad_i64_i32 v[18:19], s[0:1], v18, s97, v[66:67]
	v_mad_i64_i32 v[22:23], s[0:1], v22, s97, v[66:67]
	v_mad_i64_i32 v[24:25], s[0:1], v24, s97, v[66:67]
	v_lshl_add_u64 v[10:11], v[10:11], 0, v[0:1]
	global_load_dwordx4 v[2:5], v6, s[10:11]
	s_nop 0
	global_load_dwordx4 v[6:9], v6, s[12:13]
	v_lshl_add_u64 v[12:13], v[12:13], 0, v[0:1]
	v_lshl_add_u64 v[16:17], v[16:17], 0, v[0:1]
	v_lshl_add_u64 v[18:19], v[18:19], 0, v[0:1]
	v_lshl_add_u64 v[22:23], v[22:23], 0, v[0:1]
	v_lshl_add_u64 v[24:25], v[24:25], 0, v[0:1]
	global_load_dwordx2 v[30:31], v[10:11], off offset:2048
	global_load_dwordx2 v[40:41], v[12:13], off offset:2048
	global_load_dwordx2 v[50:51], v[16:17], off offset:2048
	global_load_dwordx2 v[48:49], v[18:19], off offset:2048
	global_load_dwordx2 v[36:37], v[22:23], off offset:2048
	global_load_dwordx2 v[26:27], v[24:25], off offset:2048
	v_lshlrev_b32_e32 v72, 2, v96
	v_xor_b32_e32 v90, 4, v72
	v_lshlrev_b32_e32 v98, 5, v89
	s_add_i32 s14, s14, s4
	s_cmp_ge_i32 s14, s5
	s_waitcnt vmcnt(9)
	v_lshlrev_b32_e32 v10, 16, v14
	v_and_b32_e32 v11, 0xffff0000, v14
	v_lshlrev_b32_e32 v13, 16, v15
	v_and_b32_e32 v12, 0xffff0000, v15
	v_mul_f32_e32 v16, 0x3d372713, v10
	v_mul_f32_e32 v17, 0x3d372713, v11
	v_mul_f32_e32 v18, 0x3d372713, v13
	v_mul_f32_e32 v19, 0x3d372713, v12
	v_mul_f32_e32 v16, v16, v10
	v_mul_f32_e32 v17, v17, v11
	v_mul_f32_e32 v18, v18, v13
	v_mul_f32_e32 v19, v19, v12
	v_fma_f32 v16, v16, v10, v10
	v_fma_f32 v17, v17, v11, v11
	v_fma_f32 v18, v18, v13, v13
	v_fma_f32 v19, v19, v12, v12
	v_mul_f32_e32 v16, 0x3f4c422a, v16
	v_mul_f32_e32 v17, 0x3f4c422a, v17
	v_mul_f32_e32 v18, 0x3f4c422a, v18
	v_mul_f32_e32 v19, 0x3f4c422a, v19
	v_add_f32_e32 v16, v16, v16
	v_add_f32_e32 v17, v17, v17
	v_add_f32_e32 v18, v18, v18
	v_add_f32_e32 v19, v19, v19
	v_mul_f32_e32 v16, 0xbfb8aa3b, v16
	v_mul_f32_e32 v17, 0xbfb8aa3b, v17
	v_mul_f32_e32 v18, 0xbfb8aa3b, v18
	v_mul_f32_e32 v19, 0xbfb8aa3b, v19
	v_exp_f32_e32 v16, v16
	v_exp_f32_e32 v17, v17
	v_exp_f32_e32 v18, v18
	v_exp_f32_e32 v19, v19
	s_waitcnt vmcnt(8)
	v_and_b32_e32 v15, 0xffff0000, v20
	v_add_f32_e32 v16, 1.0, v16
	v_add_f32_e32 v17, 1.0, v17
	v_add_f32_e32 v22, 1.0, v18
	v_add_f32_e32 v23, 1.0, v19
	v_mul_f32_e32 v32, 0x3d372713, v15
	v_rcp_f32_e32 v18, v16
	v_rcp_f32_e32 v19, v17
	v_rcp_f32_e32 v17, v22
	v_rcp_f32_e32 v16, v23
	v_mul_f32_e32 v32, v32, v15
	v_fma_f32 v32, v32, v15, v15
	v_mul_f32_e32 v32, 0x3f4c422a, v32
	v_add_f32_e32 v32, v32, v32
	v_pk_mul_f32 v[22:23], v[18:19], v[10:11]
	v_pk_mul_f32 v[24:25], v[16:17], v[12:13]
	v_mul_f32_e32 v32, 0xbfb8aa3b, v32
	v_exp_f32_e32 v34, v32
	v_pk_mov_b32 v[32:33], v[22:23], v[24:25] op_sel:[1,0]
	v_lshlrev_b32_e32 v23, 16, v21
	v_mov_b32_e32 v28, v22
	v_mul_f32_e32 v22, 0x3d372713, v23
	v_mul_f32_e32 v22, v22, v23
	v_fma_f32 v22, v22, v23, v23
	v_mul_f32_e32 v22, 0x3f4c422a, v22
	v_add_f32_e32 v22, v22, v22
	v_mul_f32_e32 v22, 0xbfb8aa3b, v22
	v_lshlrev_b32_e32 v14, 16, v20
	v_mov_b32_e32 v29, v25
	v_exp_f32_e32 v25, v22
	v_and_b32_e32 v22, 0xffff0000, v21
	v_mul_f32_e32 v20, 0x3d372713, v14
	v_mul_f32_e32 v21, 0x3d372713, v22
	v_mul_f32_e32 v20, v20, v14
	v_mul_f32_e32 v21, v21, v22
	v_fma_f32 v20, v20, v14, v14
	v_fma_f32 v21, v21, v22, v22
	v_mul_f32_e32 v20, 0x3f4c422a, v20
	v_mul_f32_e32 v21, 0x3f4c422a, v21
	v_add_f32_e32 v20, v20, v20
	v_add_f32_e32 v21, v21, v21
	v_mul_f32_e32 v20, 0xbfb8aa3b, v20
	v_mul_f32_e32 v21, 0xbfb8aa3b, v21
	v_exp_f32_e32 v20, v20
	v_add_f32_e32 v24, 1.0, v34
	v_exp_f32_e32 v34, v21
	v_rcp_f32_e32 v21, v24
	v_add_f32_e32 v24, 1.0, v25
	v_add_f32_e32 v20, 1.0, v20
	v_rcp_f32_e32 v25, v24
	v_add_f32_e32 v24, 1.0, v34
	v_rcp_f32_e32 v20, v20
	v_rcp_f32_e32 v24, v24
	v_pk_add_f32 v[28:29], v[28:29], v[32:33]
	s_waitcnt vmcnt(0)
; __device__ __forceinline__ float bf_lo(unsigned w) { return __uint_as_float(w << 16); }
; __device__ __forceinline__ float bf_hi(unsigned w) { return __uint_as_float(w & 0xffff0000u); }
; __device__ __forceinline__ float fast_rcp(float x) { return __builtin_amdgcn_rcpf(x); }
; __device__ __forceinline__ float fast_exp2(float x) { return __builtin_amdgcn_exp2f(x); }
; __device__ __forceinline__ float gelu_tanh(float x) { const float z = 0.7978845608028654f * (x + 0.044715f * x * x * x); return x * sigmoidf_(2.0f * z); }
; __device__ __forceinline__ float shx(float v, int m, int lane) { return __int_as_float(__builtin_amdgcn_ds_bpermute((lane ^ m) << 2, __float_as_int(v))); }
; __device__ __forceinline__ float sigmoidf_(float x) { return fast_rcp(1.0f + fast_exp2(-x * LOG2E)); }
; __device__ __forceinline__ float siluf_(float x) { return x * sigmoidf_(x); }
; __device__ __forceinline__ void gmlp_conv_item(const Params& p, int l, int hs, int chunk, LAS unsigned char* lds) {
;     ...
;           for (int i = 0; i < 8; ++i) w[i] = *(const u32x2*)(P + (size_t)(v0 + wid * 16 + hb * 8 + i) * PROJ + OFF_GV + 4 * lane);
; #pragma unroll
;           for (int i = 0; i < 8; ++i) { x[i][0] = gelu_tanh(bf_lo(w[i].x)); x[i][1] = gelu_tanh(bf_hi(w[i].x)); x[i][2] = gelu_tanh(bf_lo(w[i].y)); x[i][3] = gelu_tanh(bf_hi(w[i].y));
;               sm[i] = (x[i][0] + x[i][1]) + (x[i][2] + x[i][3]); }
; #pragma unroll
;           for (int st = 1; st < 64; st <<= 1)
; #pragma unroll
;               for (int i = 0; i < 8; ++i) sm[i] += shx(sm[i], st, lane);
	v_lshlrev_b32_e32 v79, 16, v27
	v_add_f32_e32 v73, v28, v29
	v_lshlrev_b32_e32 v28, 16, v30
	v_pk_mul_f32 v[32:33], v[20:21], v[14:15]
	v_pk_mul_f32 v[34:35], v[24:25], v[22:23]
	v_mul_f32_e32 v29, 0x3d372713, v28
	v_mul_f32_e32 v29, v29, v28
	v_pk_mov_b32 v[42:43], v[32:33], v[34:35] op_sel:[1,0]
	v_lshlrev_b32_e32 v33, 16, v31
	v_mov_b32_e32 v38, v32
	v_fma_f32 v29, v29, v28, v28
	v_mul_f32_e32 v32, 0x3d372713, v33
	v_mul_f32_e32 v29, 0x3f4c422a, v29
	v_mul_f32_e32 v32, v32, v33
	v_add_f32_e32 v29, v29, v29
	v_fma_f32 v32, v32, v33, v33
	v_mul_f32_e32 v29, 0xbfb8aa3b, v29
	v_mul_f32_e32 v32, 0x3f4c422a, v32
	v_exp_f32_e32 v44, v29
	v_and_b32_e32 v29, 0xffff0000, v30
	v_add_f32_e32 v32, v32, v32
	v_mul_f32_e32 v30, 0x3d372713, v29
	v_mul_f32_e32 v32, 0xbfb8aa3b, v32
	v_mov_b32_e32 v39, v35
	v_mul_f32_e32 v30, v30, v29
	v_exp_f32_e32 v35, v32
	v_and_b32_e32 v32, 0xffff0000, v31
	v_fma_f32 v30, v30, v29, v29
	v_mul_f32_e32 v31, 0x3d372713, v32
	v_mul_f32_e32 v30, 0x3f4c422a, v30
	v_mul_f32_e32 v31, v31, v32
	v_add_f32_e32 v30, v30, v30
	v_fma_f32 v31, v31, v32, v32
	v_mul_f32_e32 v30, 0xbfb8aa3b, v30
	v_mul_f32_e32 v31, 0x3f4c422a, v31
	v_exp_f32_e32 v45, v30
	v_add_f32_e32 v31, v31, v31
	v_mul_f32_e32 v31, 0xbfb8aa3b, v31
	v_add_f32_e32 v30, 1.0, v44
	v_exp_f32_e32 v44, v31
	v_add_f32_e32 v34, 1.0, v45
	v_rcp_f32_e32 v31, v34
	v_add_f32_e32 v34, 1.0, v35
	v_rcp_f32_e32 v35, v34
	v_add_f32_e32 v34, 1.0, v44
	v_rcp_f32_e32 v30, v30
	v_rcp_f32_e32 v34, v34
	v_pk_add_f32 v[38:39], v[38:39], v[42:43]
	v_pk_mul_f32 v[42:43], v[30:31], v[28:29]
	v_add_f32_e32 v84, v38, v39
	v_lshlrev_b32_e32 v38, 16, v40
	v_pk_mul_f32 v[44:45], v[34:35], v[32:33]
	v_mul_f32_e32 v39, 0x3d372713, v38
	v_mul_f32_e32 v39, v39, v38
	v_pk_mov_b32 v[52:53], v[42:43], v[44:45] op_sel:[1,0]
	v_lshlrev_b32_e32 v43, 16, v41
	v_mov_b32_e32 v46, v42
	v_fma_f32 v39, v39, v38, v38
	v_mul_f32_e32 v42, 0x3d372713, v43
	v_mul_f32_e32 v39, 0x3f4c422a, v39
	v_mul_f32_e32 v42, v42, v43
	v_add_f32_e32 v39, v39, v39
	v_fma_f32 v42, v42, v43, v43
	v_mul_f32_e32 v39, 0xbfb8aa3b, v39
	v_mul_f32_e32 v42, 0x3f4c422a, v42
	v_exp_f32_e32 v54, v39
	v_and_b32_e32 v39, 0xffff0000, v40
	v_add_f32_e32 v42, v42, v42
	v_mul_f32_e32 v40, 0x3d372713, v39
	v_mul_f32_e32 v42, 0xbfb8aa3b, v42
	v_mov_b32_e32 v47, v45
	v_mul_f32_e32 v40, v40, v39
	v_exp_f32_e32 v45, v42
	v_and_b32_e32 v42, 0xffff0000, v41
	v_fma_f32 v40, v40, v39, v39
	v_mul_f32_e32 v41, 0x3d372713, v42
	v_mul_f32_e32 v40, 0x3f4c422a, v40
	v_mul_f32_e32 v41, v41, v42
	v_add_f32_e32 v40, v40, v40
	v_fma_f32 v41, v41, v42, v42
	v_mul_f32_e32 v40, 0xbfb8aa3b, v40
	v_mul_f32_e32 v41, 0x3f4c422a, v41
	v_exp_f32_e32 v55, v40
	v_add_f32_e32 v41, v41, v41
	v_mul_f32_e32 v41, 0xbfb8aa3b, v41
	v_add_f32_e32 v40, 1.0, v54
	v_exp_f32_e32 v54, v41
	v_add_f32_e32 v44, 1.0, v55
	v_rcp_f32_e32 v41, v44
	v_add_f32_e32 v44, 1.0, v45
	v_rcp_f32_e32 v45, v44
	v_add_f32_e32 v44, 1.0, v54
	v_rcp_f32_e32 v40, v40
	v_rcp_f32_e32 v44, v44
	v_pk_add_f32 v[46:47], v[46:47], v[52:53]
	v_pk_mul_f32 v[52:53], v[40:41], v[38:39]
	v_add_f32_e32 v85, v46, v47
	v_lshlrev_b32_e32 v46, 16, v50
	v_pk_mul_f32 v[54:55], v[44:45], v[42:43]
	v_mul_f32_e32 v47, 0x3d372713, v46
	v_mul_f32_e32 v47, v47, v46
	v_pk_mov_b32 v[58:59], v[52:53], v[54:55] op_sel:[1,0]
	v_lshlrev_b32_e32 v53, 16, v51
	v_mov_b32_e32 v56, v52
	v_fma_f32 v47, v47, v46, v46
	v_mul_f32_e32 v52, 0x3d372713, v53
	v_mul_f32_e32 v47, 0x3f4c422a, v47
	v_mul_f32_e32 v52, v52, v53
	v_add_f32_e32 v47, v47, v47
	v_fma_f32 v52, v52, v53, v53
	v_mul_f32_e32 v47, 0xbfb8aa3b, v47
	v_mul_f32_e32 v52, 0x3f4c422a, v52
	v_exp_f32_e32 v60, v47
	v_and_b32_e32 v47, 0xffff0000, v50
	v_add_f32_e32 v52, v52, v52
	v_mul_f32_e32 v50, 0x3d372713, v47
	v_mul_f32_e32 v52, 0xbfb8aa3b, v52
	v_mov_b32_e32 v57, v55
	v_mul_f32_e32 v50, v50, v47
	v_exp_f32_e32 v55, v52
	v_and_b32_e32 v52, 0xffff0000, v51
	v_fma_f32 v50, v50, v47, v47
	v_mul_f32_e32 v51, 0x3d372713, v52
	v_mul_f32_e32 v50, 0x3f4c422a, v50
	v_mul_f32_e32 v51, v51, v52
	v_add_f32_e32 v50, v50, v50
	v_fma_f32 v51, v51, v52, v52
	v_mul_f32_e32 v50, 0xbfb8aa3b, v50
	v_mul_f32_e32 v51, 0x3f4c422a, v51
	v_exp_f32_e32 v61, v50
	v_add_f32_e32 v51, v51, v51
	v_mul_f32_e32 v51, 0xbfb8aa3b, v51
	v_add_f32_e32 v50, 1.0, v60
	v_exp_f32_e32 v60, v51
	v_add_f32_e32 v54, 1.0, v61
	v_rcp_f32_e32 v51, v54
	v_add_f32_e32 v54, 1.0, v55
	v_rcp_f32_e32 v55, v54
	v_add_f32_e32 v54, 1.0, v60
	v_rcp_f32_e32 v50, v50
	v_rcp_f32_e32 v54, v54
	v_pk_add_f32 v[56:57], v[56:57], v[58:59]
	ds_bpermute_b32 v93, v90, v85
	v_add_f32_e32 v86, v56, v57
	v_lshlrev_b32_e32 v56, 16, v48
	v_pk_mul_f32 v[58:59], v[50:51], v[46:47]
	v_pk_mul_f32 v[60:61], v[54:55], v[52:53]
	v_mul_f32_e32 v57, 0x3d372713, v56
	v_mul_f32_e32 v57, v57, v56
	v_pk_mov_b32 v[64:65], v[58:59], v[60:61] op_sel:[1,0]
	v_lshlrev_b32_e32 v59, 16, v49
	v_mov_b32_e32 v62, v58
	v_fma_f32 v57, v57, v56, v56
	v_mul_f32_e32 v58, 0x3d372713, v59
	v_mul_f32_e32 v57, 0x3f4c422a, v57
	v_mul_f32_e32 v58, v58, v59
	v_add_f32_e32 v57, v57, v57
	v_fma_f32 v58, v58, v59, v59
	v_mul_f32_e32 v57, 0xbfb8aa3b, v57
	v_mul_f32_e32 v58, 0x3f4c422a, v58
	v_exp_f32_e32 v68, v57
	v_and_b32_e32 v57, 0xffff0000, v48
	v_add_f32_e32 v58, v58, v58
	v_mul_f32_e32 v48, 0x3d372713, v57
	v_mul_f32_e32 v58, 0xbfb8aa3b, v58
	v_mov_b32_e32 v63, v61
	v_mul_f32_e32 v48, v48, v57
	v_exp_f32_e32 v61, v58
	v_and_b32_e32 v58, 0xffff0000, v49
	v_fma_f32 v48, v48, v57, v57
	v_mul_f32_e32 v49, 0x3d372713, v58
	v_mul_f32_e32 v48, 0x3f4c422a, v48
	v_mul_f32_e32 v49, v49, v58
	v_add_f32_e32 v48, v48, v48
	v_fma_f32 v49, v49, v58, v58
	v_mul_f32_e32 v48, 0xbfb8aa3b, v48
	v_mul_f32_e32 v49, 0x3f4c422a, v49
; __device__ __forceinline__ float bf_lo(unsigned w) { return __uint_as_float(w << 16); }
; __device__ __forceinline__ float bf_hi(unsigned w) { return __uint_as_float(w & 0xffff0000u); }
; __device__ __forceinline__ float gelu_tanh(float x) { const float z = 0.7978845608028654f * (x + 0.044715f * x * x * x); return x * sigmoidf_(2.0f * z); }
; __device__ __forceinline__ float shx(float v, int m, int lane) { return __int_as_float(__builtin_amdgcn_ds_bpermute((lane ^ m) << 2, __float_as_int(v))); }
; __device__ __forceinline__ void gmlp_conv_item(const Params& p, int l, int hs, int chunk, LAS unsigned char* lds) {
;     ...
;           for (int i = 0; i < 8; ++i) { x[i][0] = gelu_tanh(bf_lo(w[i].x)); x[i][1] = gelu_tanh(bf_hi(w[i].x)); x[i][2] = gelu_tanh(bf_lo(w[i].y)); x[i][3] = gelu_tanh(bf_hi(w[i].y));
;               sm[i] = (x[i][0] + x[i][1]) + (x[i][2] + x[i][3]); }
; #pragma unroll
;           for (int st = 1; st < 64; st <<= 1)
; #pragma unroll
;               for (int i = 0; i < 8; ++i) sm[i] += shx(sm[i], st, lane);
	v_exp_f32_e32 v69, v48
	v_add_f32_e32 v49, v49, v49
	v_mul_f32_e32 v49, 0xbfb8aa3b, v49
	v_add_f32_e32 v48, 1.0, v68
	v_exp_f32_e32 v68, v49
	v_add_f32_e32 v60, 1.0, v69
	v_rcp_f32_e32 v49, v60
	v_add_f32_e32 v60, 1.0, v61
	v_rcp_f32_e32 v61, v60
	v_add_f32_e32 v60, 1.0, v68
	v_rcp_f32_e32 v48, v48
	v_rcp_f32_e32 v60, v60
	v_pk_add_f32 v[62:63], v[62:63], v[64:65]
	v_pk_mul_f32 v[64:65], v[48:49], v[56:57]
	v_add_f32_e32 v87, v62, v63
	v_lshlrev_b32_e32 v62, 16, v36
	v_pk_mul_f32 v[68:69], v[60:61], v[58:59]
	v_mul_f32_e32 v63, 0x3d372713, v62
	v_mul_f32_e32 v63, v63, v62
	v_pk_mov_b32 v[74:75], v[64:65], v[68:69] op_sel:[1,0]
	v_lshlrev_b32_e32 v65, 16, v37
	v_mov_b32_e32 v70, v64
	v_fma_f32 v63, v63, v62, v62
	v_mul_f32_e32 v64, 0x3d372713, v65
	v_mul_f32_e32 v63, 0x3f4c422a, v63
	v_mul_f32_e32 v64, v64, v65
	v_add_f32_e32 v63, v63, v63
	v_fma_f32 v64, v64, v65, v65
	v_mul_f32_e32 v63, 0xbfb8aa3b, v63
	v_mul_f32_e32 v64, 0x3f4c422a, v64
	v_exp_f32_e32 v76, v63
	v_and_b32_e32 v63, 0xffff0000, v36
	v_add_f32_e32 v64, v64, v64
	v_mul_f32_e32 v36, 0x3d372713, v63
	v_mul_f32_e32 v64, 0xbfb8aa3b, v64
	v_mov_b32_e32 v71, v69
	v_mul_f32_e32 v36, v36, v63
	v_exp_f32_e32 v69, v64
	v_and_b32_e32 v64, 0xffff0000, v37
	v_fma_f32 v36, v36, v63, v63
	v_mul_f32_e32 v37, 0x3d372713, v64
	v_mul_f32_e32 v36, 0x3f4c422a, v36
	v_mul_f32_e32 v37, v37, v64
	v_add_f32_e32 v36, v36, v36
	v_fma_f32 v37, v37, v64, v64
	v_mul_f32_e32 v36, 0xbfb8aa3b, v36
	v_mul_f32_e32 v37, 0x3f4c422a, v37
	v_exp_f32_e32 v77, v36
	v_add_f32_e32 v37, v37, v37
	v_pk_add_f32 v[70:71], v[70:71], v[74:75]
	v_mul_f32_e32 v37, 0xbfb8aa3b, v37
	v_add_f32_e32 v91, v70, v71
	v_lshlrev_b32_e32 v70, 16, v26
	v_add_f32_e32 v36, 1.0, v76
	v_exp_f32_e32 v76, v37
	v_mul_f32_e32 v71, 0x3d372713, v70
	v_mul_f32_e32 v71, v71, v70
	v_add_f32_e32 v68, 1.0, v77
	v_fma_f32 v71, v71, v70, v70
	v_rcp_f32_e32 v37, v68
	v_add_f32_e32 v68, 1.0, v69
	v_mul_f32_e32 v71, 0x3f4c422a, v71
	v_rcp_f32_e32 v69, v68
	v_add_f32_e32 v68, 1.0, v76
	v_add_f32_e32 v71, v71, v71
	v_rcp_f32_e32 v36, v36
	v_rcp_f32_e32 v68, v68
	v_mul_f32_e32 v71, 0xbfb8aa3b, v71
	v_exp_f32_e32 v78, v71
	v_and_b32_e32 v71, 0xffff0000, v26
	v_pk_mul_f32 v[74:75], v[36:37], v[62:63]
	v_pk_mul_f32 v[76:77], v[68:69], v[64:65]
	v_mul_f32_e32 v26, 0x3d372713, v71
	v_mov_b32_e32 v80, v74
	v_mov_b32_e32 v81, v77
	v_mul_f32_e32 v26, v26, v71
	v_pk_mov_b32 v[76:77], v[74:75], v[76:77] op_sel:[1,0]
	v_add_f32_e32 v74, 1.0, v78
	v_mul_f32_e32 v75, 0x3d372713, v79
	v_and_b32_e32 v78, 0xffff0000, v27
	v_fma_f32 v26, v26, v71, v71
	v_mul_f32_e32 v75, v75, v79
	v_mul_f32_e32 v27, 0x3d372713, v78
	v_mul_f32_e32 v26, 0x3f4c422a, v26
	v_fma_f32 v75, v75, v79, v79
	v_mul_f32_e32 v27, v27, v78
	v_add_f32_e32 v26, v26, v26
	v_mul_f32_e32 v75, 0x3f4c422a, v75
	v_fma_f32 v27, v27, v78, v78
	v_mul_f32_e32 v26, 0xbfb8aa3b, v26
	v_add_f32_e32 v75, v75, v75
	v_mul_f32_e32 v27, 0x3f4c422a, v27
	v_exp_f32_e32 v26, v26
	v_mul_f32_e32 v75, 0xbfb8aa3b, v75
	v_add_f32_e32 v27, v27, v27
	v_exp_f32_e32 v82, v75
	v_mul_f32_e32 v27, 0xbfb8aa3b, v27
	v_exp_f32_e32 v27, v27
	v_add_f32_e32 v26, 1.0, v26
	v_rcp_f32_e32 v75, v26
	v_add_f32_e32 v26, 1.0, v82
	v_rcp_f32_e32 v83, v26
	v_add_f32_e32 v26, 1.0, v27
	v_rcp_f32_e32 v74, v74
	v_rcp_f32_e32 v82, v26
	v_pk_add_f32 v[26:27], v[80:81], v[76:77]
	v_pk_mul_f32 v[76:77], v[82:83], v[78:79]
	v_add_f32_e32 v92, v26, v27
	v_pk_mul_f32 v[26:27], v[74:75], v[70:71]
	v_mov_b32_e32 v81, v77
	v_mov_b32_e32 v80, v26
	v_pk_mov_b32 v[26:27], v[26:27], v[76:77] op_sel:[1,0]
	ds_bpermute_b32 v76, v90, v73
	ds_bpermute_b32 v77, v90, v84
	v_pk_add_f32 v[26:27], v[80:81], v[26:27]
	ds_bpermute_b32 v81, v90, v91
	v_add_f32_e32 v26, v26, v27
	s_waitcnt lgkmcnt(2)
	v_add_f32_e32 v27, v73, v76
	s_waitcnt lgkmcnt(1)
	v_add_f32_e32 v73, v84, v77
	ds_bpermute_b32 v77, v90, v86
	v_add_f32_e32 v76, v85, v93
	ds_bpermute_b32 v80, v90, v87
	ds_bpermute_b32 v84, v90, v92
	ds_bpermute_b32 v85, v90, v26
	s_waitcnt lgkmcnt(3)
	v_add_f32_e32 v77, v86, v77
	v_add_f32_e32 v81, v91, v81
	v_xor_b32_e32 v91, 8, v72
	s_waitcnt lgkmcnt(2)
	v_add_f32_e32 v80, v87, v80
	s_waitcnt lgkmcnt(1)
	v_add_f32_e32 v84, v92, v84
	s_waitcnt lgkmcnt(0)
	v_add_f32_e32 v26, v26, v85
	ds_bpermute_b32 v85, v91, v27
	ds_bpermute_b32 v92, v91, v77
	ds_bpermute_b32 v86, v91, v73
	ds_bpermute_b32 v93, v91, v80
	ds_bpermute_b32 v87, v91, v76
	s_waitcnt lgkmcnt(4)
	v_add_f32_e32 v27, v27, v85
	s_waitcnt lgkmcnt(3)
	v_add_f32_e32 v77, v77, v92
	ds_bpermute_b32 v85, v91, v81
	v_xor_b32_e32 v92, 16, v72
	s_waitcnt lgkmcnt(3)
	v_add_f32_e32 v73, v73, v86
	s_waitcnt lgkmcnt(2)
	v_add_f32_e32 v80, v80, v93
	ds_bpermute_b32 v86, v91, v84
	ds_bpermute_b32 v93, v92, v27
	ds_bpermute_b32 v94, v92, v73
	s_waitcnt lgkmcnt(4)
	v_add_f32_e32 v76, v76, v87
	ds_bpermute_b32 v87, v91, v26
	s_waitcnt lgkmcnt(4)
	v_add_f32_e32 v81, v81, v85
	s_waitcnt lgkmcnt(3)
	v_add_f32_e32 v84, v84, v86
	s_waitcnt lgkmcnt(2)
	v_add_f32_e32 v27, v27, v93
	ds_bpermute_b32 v85, v92, v76
	ds_bpermute_b32 v86, v92, v77
	ds_bpermute_b32 v93, v92, v81
	s_waitcnt lgkmcnt(4)
	v_add_f32_e32 v73, v73, v94
	ds_bpermute_b32 v94, v92, v84
	s_waitcnt lgkmcnt(4)
	v_add_f32_e32 v26, v26, v87
	ds_bpermute_b32 v87, v92, v80
	s_waitcnt lgkmcnt(4)
	v_add_f32_e32 v76, v76, v85
	s_waitcnt lgkmcnt(3)
	v_add_f32_e32 v77, v77, v86
	s_waitcnt lgkmcnt(2)
	v_add_f32_e32 v81, v81, v93
	ds_bpermute_b32 v85, v92, v26
	v_xor_b32_e32 v93, 32, v72
	s_waitcnt lgkmcnt(2)
	v_add_f32_e32 v84, v84, v94
	ds_bpermute_b32 v86, v93, v27
	ds_bpermute_b32 v94, v93, v76
	ds_bpermute_b32 v95, v93, v77
	s_waitcnt lgkmcnt(4)
	v_add_f32_e32 v80, v80, v87
	ds_bpermute_b32 v87, v93, v73
	s_waitcnt lgkmcnt(4)
; __device__ __forceinline__ float shx(float v, int m, int lane) { return __int_as_float(__builtin_amdgcn_ds_bpermute((lane ^ m) << 2, __float_as_int(v))); }
; __device__ __forceinline__ void gmlp_conv_item(const Params& p, int l, int hs, int chunk, LAS unsigned char* lds) {
;     ...
;           for (int st = 1; st < 64; st <<= 1)
; #pragma unroll
;               for (int i = 0; i < 8; ++i) sm[i] += shx(sm[i], st, lane);
; #pragma unroll
;           for (int i = 0; i < 8; ++i) { const float mu = sm[i] * (1.0f / 256); float q = 0.f;
; #pragma unroll
;               for (int e = 0; e < 4; ++e) { x[i][e] -= mu; q += x[i][e] * x[i][e]; }
;               qv[i] = q; }
; #pragma unroll
;           for (int st = 1; st < 64; st <<= 1)
; #pragma unroll
;               for (int i = 0; i < 8; ++i) qv[i] += shx(qv[i], st, lane);
	v_add_f32_e32 v26, v26, v85
	ds_bpermute_b32 v85, v93, v80
	s_waitcnt lgkmcnt(4)
	v_add_f32_e32 v27, v27, v86
	s_waitcnt lgkmcnt(3)
	v_add_f32_e32 v76, v76, v94
	s_waitcnt lgkmcnt(2)
	v_add_f32_e32 v77, v77, v95
	ds_bpermute_b32 v86, v93, v81
	ds_bpermute_b32 v95, v93, v26
	v_xor_b32_e32 v94, 64, v72
	s_waitcnt lgkmcnt(3)
	v_add_f32_e32 v73, v73, v87
	ds_bpermute_b32 v87, v93, v84
	ds_bpermute_b32 v99, v94, v27
	s_waitcnt lgkmcnt(4)
	v_add_f32_e32 v80, v80, v85
	s_waitcnt lgkmcnt(3)
	v_add_f32_e32 v81, v81, v86
	s_waitcnt lgkmcnt(2)
	v_add_f32_e32 v26, v26, v95
	ds_bpermute_b32 v85, v94, v73
	ds_bpermute_b32 v86, v94, v76
	ds_bpermute_b32 v95, v94, v80
	s_waitcnt lgkmcnt(4)
	v_add_f32_e32 v84, v84, v87
	s_waitcnt lgkmcnt(3)
	v_add_f32_e32 v27, v27, v99
	ds_bpermute_b32 v87, v94, v77
	ds_bpermute_b32 v99, v94, v81
	s_waitcnt lgkmcnt(4)
	v_add_f32_e32 v73, v73, v85
	s_waitcnt lgkmcnt(3)
	v_add_f32_e32 v76, v76, v86
	s_waitcnt lgkmcnt(2)
	v_add_f32_e32 v80, v80, v95
	ds_bpermute_b32 v86, v94, v26
	v_xor_b32_e32 v95, 0x80, v72
	s_waitcnt lgkmcnt(2)
	v_add_f32_e32 v77, v77, v87
	s_waitcnt lgkmcnt(1)
	v_add_f32_e32 v81, v81, v99
	ds_bpermute_b32 v85, v94, v84
	ds_bpermute_b32 v72, v95, v27
	ds_bpermute_b32 v87, v95, v73
	ds_bpermute_b32 v99, v95, v76
	s_waitcnt lgkmcnt(4)
	v_add_f32_e32 v26, v26, v86
	s_waitcnt lgkmcnt(3)
	v_add_f32_e32 v84, v84, v85
	s_waitcnt lgkmcnt(2)
	v_add_f32_e32 v27, v27, v72
	s_waitcnt lgkmcnt(1)
	v_add_f32_e32 v72, v73, v87
	s_waitcnt lgkmcnt(0)
	v_add_f32_e32 v73, v76, v99
	ds_bpermute_b32 v99, v95, v26
	ds_bpermute_b32 v86, v95, v81
	ds_bpermute_b32 v87, v95, v84
	ds_bpermute_b32 v85, v95, v80
	ds_bpermute_b32 v76, v95, v77
	s_waitcnt lgkmcnt(4)
	v_add_f32_e32 v99, v26, v99
	v_mul_f32_e32 v26, 0x3b800000, v27
	s_waitcnt lgkmcnt(3)
	v_add_f32_e32 v102, v81, v86
	s_waitcnt lgkmcnt(2)
	v_add_f32_e32 v103, v84, v87
	v_pk_fma_f32 v[86:87], v[18:19], v[10:11], v[26:27] op_sel_hi:[1,1,0] neg_lo:[0,0,1] neg_hi:[0,0,1]
	s_waitcnt lgkmcnt(1)
	v_add_f32_e32 v101, v80, v85
	v_pk_mul_f32 v[10:11], v[86:87], v[86:87]
	v_pk_fma_f32 v[84:85], v[16:17], v[12:13], v[26:27] op_sel_hi:[1,1,0] neg_lo:[0,0,1] neg_hi:[0,0,1]
	v_add_f32_e32 v10, v10, v11
	v_pk_mul_f32 v[12:13], v[84:85], v[84:85]
	s_waitcnt lgkmcnt(0)
	v_add_f32_e32 v100, v77, v76
	v_add_f32_e32 v10, v13, v10
	v_add_f32_e32 v104, v12, v10
	v_mul_f32_e32 v10, 0x3b800000, v72
	v_pk_fma_f32 v[80:81], v[20:21], v[14:15], v[10:11] op_sel_hi:[1,1,0] neg_lo:[0,0,1] neg_hi:[0,0,1]
	v_pk_fma_f32 v[76:77], v[24:25], v[22:23], v[10:11] op_sel_hi:[1,1,0] neg_lo:[0,0,1] neg_hi:[0,0,1]
	v_pk_mul_f32 v[12:13], v[80:81], v[80:81]
	v_pk_mul_f32 v[10:11], v[76:77], v[76:77]
	v_add_f32_e32 v12, v12, v13
	v_add_f32_e32 v11, v11, v12
	v_add_f32_e32 v105, v10, v11
	v_mul_f32_e32 v10, 0x3b800000, v73
	v_pk_fma_f32 v[72:73], v[30:31], v[28:29], v[10:11] op_sel_hi:[1,1,0] neg_lo:[0,0,1] neg_hi:[0,0,1]
	v_pk_fma_f32 v[30:31], v[34:35], v[32:33], v[10:11] op_sel_hi:[1,1,0] neg_lo:[0,0,1] neg_hi:[0,0,1]
	v_pk_mul_f32 v[12:13], v[72:73], v[72:73]
	v_pk_mul_f32 v[10:11], v[30:31], v[30:31]
	v_add_f32_e32 v12, v12, v13
	v_add_f32_e32 v11, v11, v12
	v_add_f32_e32 v106, v10, v11
	v_mul_f32_e32 v10, 0x3b800000, v100
	v_pk_fma_f32 v[28:29], v[40:41], v[38:39], v[10:11] op_sel_hi:[1,1,0] neg_lo:[0,0,1] neg_hi:[0,0,1]
	v_pk_fma_f32 v[26:27], v[44:45], v[42:43], v[10:11] op_sel_hi:[1,1,0] neg_lo:[0,0,1] neg_hi:[0,0,1]
	v_pk_mul_f32 v[12:13], v[28:29], v[28:29]
	v_pk_mul_f32 v[10:11], v[26:27], v[26:27]
	v_add_f32_e32 v12, v12, v13
	v_add_f32_e32 v11, v11, v12
	v_add_f32_e32 v38, v10, v11
	v_mul_f32_e32 v10, 0x3b800000, v101
	v_pk_fma_f32 v[24:25], v[50:51], v[46:47], v[10:11] op_sel_hi:[1,1,0] neg_lo:[0,0,1] neg_hi:[0,0,1]
	v_pk_fma_f32 v[22:23], v[54:55], v[52:53], v[10:11] op_sel_hi:[1,1,0] neg_lo:[0,0,1] neg_hi:[0,0,1]
	v_pk_mul_f32 v[12:13], v[24:25], v[24:25]
	v_pk_mul_f32 v[10:11], v[22:23], v[22:23]
	v_add_f32_e32 v12, v12, v13
	v_add_f32_e32 v11, v11, v12
	v_add_f32_e32 v39, v10, v11
	v_mul_f32_e32 v10, 0x3b800000, v102
	v_pk_fma_f32 v[20:21], v[48:49], v[56:57], v[10:11] op_sel_hi:[1,1,0] neg_lo:[0,0,1] neg_hi:[0,0,1]
	v_pk_fma_f32 v[18:19], v[60:61], v[58:59], v[10:11] op_sel_hi:[1,1,0] neg_lo:[0,0,1] neg_hi:[0,0,1]
	v_pk_mul_f32 v[12:13], v[20:21], v[20:21]
	v_pk_mul_f32 v[10:11], v[18:19], v[18:19]
	v_add_f32_e32 v12, v12, v13
	v_add_f32_e32 v11, v11, v12
	v_add_f32_e32 v40, v10, v11
	v_mul_f32_e32 v10, 0x3b800000, v103
	v_pk_fma_f32 v[16:17], v[36:37], v[62:63], v[10:11] op_sel_hi:[1,1,0] neg_lo:[0,0,1] neg_hi:[0,0,1]
	v_pk_fma_f32 v[14:15], v[68:69], v[64:65], v[10:11] op_sel_hi:[1,1,0] neg_lo:[0,0,1] neg_hi:[0,0,1]
	v_pk_mul_f32 v[12:13], v[16:17], v[16:17]
	v_pk_mul_f32 v[10:11], v[14:15], v[14:15]
	v_add_f32_e32 v12, v12, v13
	v_add_f32_e32 v11, v11, v12
	v_add_f32_e32 v36, v10, v11
	v_mul_f32_e32 v10, 0x3b800000, v99
	v_pk_fma_f32 v[12:13], v[74:75], v[70:71], v[10:11] op_sel_hi:[1,1,0] neg_lo:[0,0,1] neg_hi:[0,0,1]
	ds_bpermute_b32 v37, v90, v38
	v_pk_mul_f32 v[32:33], v[12:13], v[12:13]
	ds_bpermute_b32 v41, v90, v39
	v_add_f32_e32 v32, v32, v33
	ds_bpermute_b32 v33, v90, v104
	v_pk_fma_f32 v[10:11], v[82:83], v[78:79], v[10:11] op_sel_hi:[1,1,0] neg_lo:[0,0,1] neg_hi:[0,0,1]
	s_waitcnt lgkmcnt(2)
	v_add_f32_e32 v37, v38, v37
	v_pk_mul_f32 v[34:35], v[10:11], v[10:11]
	s_waitcnt lgkmcnt(1)
	v_add_f32_e32 v38, v39, v41
	v_add_f32_e32 v32, v35, v32
	ds_bpermute_b32 v35, v90, v106
	ds_bpermute_b32 v39, v90, v40
	s_waitcnt lgkmcnt(2)
	v_add_f32_e32 v33, v104, v33
	v_add_f32_e32 v32, v34, v32
	ds_bpermute_b32 v34, v90, v105
	ds_bpermute_b32 v43, v91, v33
	s_waitcnt lgkmcnt(3)
; __device__ __forceinline__ unsigned cvt_pk_bf16(float lo, float hi) { unsigned r; asm volatile("v_cvt_pk_bf16_f32 %0, %1, %2" : "=v"(r) : "v"(lo), "v"(hi)); return r; }
; __device__ __forceinline__ float shx(float v, int m, int lane) { return __int_as_float(__builtin_amdgcn_ds_bpermute((lane ^ m) << 2, __float_as_int(v))); }
; __device__ __forceinline__ void gmlp_conv_item(const Params& p, int l, int hs, int chunk, LAS unsigned char* lds) {
;     ...
;           for (int st = 1; st < 64; st <<= 1)
; #pragma unroll
;               for (int i = 0; i < 8; ++i) qv[i] += shx(qv[i], st, lane);
; #pragma unroll
;           for (int i = 0; i < 8; ++i) { const float rstd = rsqrtf(qv[i] * (1.0f / 256) + EPS); const int pt = wid * 16 + hb * 8 + i;
; #pragma unroll
;               for (int e = 0; e < 4; ++e) { const float y = x[i][e] * rstd * g4[e] + b4[e]; vT[(4 * lane + e) * 136 + pt] = (bf16_t)(cvt_pk_bf16(y, 0.f) & 0xffffu); } }
	v_add_f32_e32 v35, v106, v35
	ds_bpermute_b32 v42, v90, v32
	s_waitcnt lgkmcnt(3)
	v_add_f32_e32 v39, v40, v39
	ds_bpermute_b32 v40, v91, v35
	ds_bpermute_b32 v41, v90, v36
	s_waitcnt lgkmcnt(4)
	v_add_f32_e32 v34, v105, v34
	s_waitcnt lgkmcnt(3)
	v_add_f32_e32 v33, v33, v43
	ds_bpermute_b32 v43, v91, v39
	ds_bpermute_b32 v44, v91, v34
	s_waitcnt lgkmcnt(4)
	v_add_f32_e32 v32, v32, v42
	ds_bpermute_b32 v42, v91, v38
	s_waitcnt lgkmcnt(4)
	v_add_f32_e32 v35, v35, v40
	ds_bpermute_b32 v40, v91, v32
	s_waitcnt lgkmcnt(4)
	v_add_f32_e32 v36, v36, v41
	ds_bpermute_b32 v41, v91, v37
	s_waitcnt lgkmcnt(4)
	v_add_f32_e32 v39, v39, v43
	ds_bpermute_b32 v43, v92, v35
	s_waitcnt lgkmcnt(4)
	v_add_f32_e32 v34, v34, v44
	ds_bpermute_b32 v44, v91, v36
	s_waitcnt lgkmcnt(4)
	v_add_f32_e32 v38, v38, v42
	ds_bpermute_b32 v42, v92, v34
	s_waitcnt lgkmcnt(4)
	v_add_f32_e32 v32, v32, v40
	ds_bpermute_b32 v40, v92, v38
	s_waitcnt lgkmcnt(4)
	v_add_f32_e32 v37, v37, v41
	ds_bpermute_b32 v41, v92, v33
	s_waitcnt lgkmcnt(4)
	v_add_f32_e32 v35, v35, v43
	ds_bpermute_b32 v43, v92, v32
	s_waitcnt lgkmcnt(4)
	v_add_f32_e32 v36, v36, v44
	ds_bpermute_b32 v44, v92, v37
	s_waitcnt lgkmcnt(4)
	v_add_f32_e32 v34, v34, v42
	ds_bpermute_b32 v42, v92, v36
	s_waitcnt lgkmcnt(4)
	v_add_f32_e32 v38, v38, v40
	ds_bpermute_b32 v40, v93, v34
	s_waitcnt lgkmcnt(4)
	v_add_f32_e32 v33, v33, v41
	ds_bpermute_b32 v41, v92, v39
	s_waitcnt lgkmcnt(4)
	v_add_f32_e32 v32, v32, v43
	ds_bpermute_b32 v43, v93, v38
	s_waitcnt lgkmcnt(4)
	v_add_f32_e32 v37, v37, v44
	ds_bpermute_b32 v44, v93, v33
	s_waitcnt lgkmcnt(4)
	v_add_f32_e32 v36, v36, v42
	ds_bpermute_b32 v42, v93, v37
	s_waitcnt lgkmcnt(4)
	v_add_f32_e32 v34, v34, v40
	ds_bpermute_b32 v40, v93, v36
	s_waitcnt lgkmcnt(4)
	v_add_f32_e32 v39, v39, v41
	ds_bpermute_b32 v41, v93, v35
	s_waitcnt lgkmcnt(4)
	v_add_f32_e32 v38, v38, v43
	ds_bpermute_b32 v43, v94, v34
	s_waitcnt lgkmcnt(4)
	v_add_f32_e32 v33, v33, v44
	s_waitcnt lgkmcnt(3)
	v_add_f32_e32 v37, v37, v42
	ds_bpermute_b32 v42, v94, v33
	s_waitcnt lgkmcnt(3)
	v_add_f32_e32 v36, v36, v40
	ds_bpermute_b32 v40, v94, v37
	ds_bpermute_b32 v44, v93, v39
	s_waitcnt lgkmcnt(4)
	v_add_f32_e32 v35, v35, v41
	ds_bpermute_b32 v41, v93, v32
	s_waitcnt lgkmcnt(4)
	v_add_f32_e32 v34, v34, v43
	ds_bpermute_b32 v43, v94, v36
	s_waitcnt lgkmcnt(4)
	v_add_f32_e32 v33, v33, v42
	s_waitcnt lgkmcnt(3)
	v_add_f32_e32 v37, v37, v40
	ds_bpermute_b32 v40, v95, v33
	s_waitcnt lgkmcnt(3)
	v_add_f32_e32 v39, v39, v44
	s_waitcnt lgkmcnt(2)
	v_add_f32_e32 v32, v32, v41
	ds_bpermute_b32 v41, v94, v38
	ds_bpermute_b32 v42, v94, v39
	s_waitcnt lgkmcnt(3)
	v_add_f32_e32 v36, v36, v43
	ds_bpermute_b32 v43, v95, v37
	s_waitcnt lgkmcnt(3)
	v_add_f32_e32 v33, v33, v40
	s_waitcnt lgkmcnt(2)
	v_add_f32_e32 v38, v38, v41
	ds_bpermute_b32 v41, v95, v34
	v_fmamk_f32 v33, v33, 0x3b800000, v220
	s_waitcnt lgkmcnt(2)
	v_add_f32_e32 v39, v39, v42
	s_waitcnt lgkmcnt(1)
	v_add_f32_e32 v37, v37, v43
	v_cmp_gt_f32_e32 vcc, s84, v33
	v_mul_f32_e32 v43, 0x4b800000, v33
	ds_bpermute_b32 v40, v95, v39
	v_cndmask_b32_e32 v33, v33, v43, vcc
	v_rsq_f32_e32 v33, v33
	s_waitcnt lgkmcnt(1)
	v_add_f32_e32 v34, v34, v41
	ds_bpermute_b32 v41, v95, v36
	s_waitcnt lgkmcnt(1)
	v_add_f32_e32 v39, v39, v40
	v_mul_f32_e32 v40, 0x45800000, v33
	v_cndmask_b32_e32 v33, v33, v40, vcc
	v_mul_f32_e32 v40, v86, v33
	s_waitcnt lgkmcnt(0)
	v_add_f32_e32 v36, v36, v41
	v_fma_f32 v40, v2, v40, v6
	v_mul_u32_u24_e32 v41, 0x440, v96
	v_cvt_pk_bf16_f32 v40, v40, v1
	v_add3_u32 v96, 0, v98, v41
	ds_write_b16 v96, v40
	v_mul_f32_e32 v40, v87, v33
	v_fma_f32 v40, v3, v40, v7
	v_cvt_pk_bf16_f32 v40, v40, v1
	ds_write_b16 v96, v40 offset:272
	v_mul_f32_e32 v40, v85, v33
	v_fma_f32 v40, v4, v40, v8
	v_cvt_pk_bf16_f32 v40, v40, v1
	v_fmamk_f32 v34, v34, 0x3b800000, v220
	ds_write_b16 v96, v40 offset:544
	v_cmp_gt_f32_e32 vcc, s84, v34
	v_mul_f32_e32 v40, 0x4b800000, v34
	v_mul_f32_e32 v33, v84, v33
	v_cndmask_b32_e32 v34, v34, v40, vcc
	v_rsq_f32_e32 v34, v34
	v_fma_f32 v33, v5, v33, v9
	ds_bpermute_b32 v44, v94, v35
	v_cvt_pk_bf16_f32 v33, v33, v1
	ds_write_b16 v96, v33 offset:816
	v_mul_f32_e32 v33, 0x45800000, v34
	v_cndmask_b32_e32 v33, v34, v33, vcc
	v_mul_f32_e32 v34, v80, v33
	v_fma_f32 v34, v2, v34, v6
	s_waitcnt lgkmcnt(1)
	v_add_f32_e32 v35, v35, v44
	v_cvt_pk_bf16_f32 v34, v34, v1
	ds_bpermute_b32 v42, v95, v35
	ds_write_b16 v96, v34 offset:2
	v_mul_f32_e32 v34, v81, v33
	v_fma_f32 v34, v3, v34, v7
	v_cvt_pk_bf16_f32 v34, v34, v1
	ds_write_b16 v96, v34 offset:274
	v_mul_f32_e32 v34, v77, v33
	v_fma_f32 v34, v4, v34, v8
	s_waitcnt lgkmcnt(2)
	v_add_f32_e32 v35, v35, v42
	v_cvt_pk_bf16_f32 v34, v34, v1
	ds_write_b16 v96, v34 offset:546
	v_fmamk_f32 v34, v35, 0x3b800000, v220
	v_cmp_gt_f32_e32 vcc, s84, v34
	v_mul_f32_e32 v35, 0x4b800000, v34
	v_mul_f32_e32 v33, v76, v33
	v_cndmask_b32_e32 v34, v34, v35, vcc
	v_rsq_f32_e32 v34, v34
	v_fma_f32 v33, v5, v33, v9
	v_cvt_pk_bf16_f32 v33, v33, v1
	ds_write_b16 v96, v33 offset:818
	v_mul_f32_e32 v33, 0x45800000, v34
	v_cndmask_b32_e32 v33, v34, v33, vcc
	v_mul_f32_e32 v34, v72, v33
	v_fma_f32 v34, v2, v34, v6
	v_cvt_pk_bf16_f32 v34, v34, v1
	ds_write_b16 v96, v34 offset:4
	v_mul_f32_e32 v34, v73, v33
	v_mul_f32_e32 v31, v31, v33
	v_fma_f32 v34, v3, v34, v7
	v_fma_f32 v31, v4, v31, v8
	v_cvt_pk_bf16_f32 v34, v34, v1
	ds_write_b16 v96, v34 offset:276
	v_cvt_pk_bf16_f32 v31, v31, v1
	ds_write_b16 v96, v31 offset:548
	v_fmamk_f32 v31, v37, 0x3b800000, v220
	v_mul_f32_e32 v30, v30, v33
	v_cmp_gt_f32_e32 vcc, s84, v31
	v_mul_f32_e32 v33, 0x4b800000, v31
	ds_bpermute_b32 v44, v94, v32
	v_cndmask_b32_e32 v31, v31, v33, vcc
	v_rsq_f32_e32 v31, v31
	v_fma_f32 v30, v5, v30, v9
	v_cvt_pk_bf16_f32 v30, v30, v1
	ds_write_b16 v96, v30 offset:820
	v_mul_f32_e32 v30, 0x45800000, v31
	v_cndmask_b32_e32 v30, v31, v30, vcc
	s_waitcnt lgkmcnt(1)
; __device__ __forceinline__ unsigned cvt_pk_bf16(float lo, float hi) { unsigned r; asm volatile("v_cvt_pk_bf16_f32 %0, %1, %2" : "=v"(r) : "v"(lo), "v"(hi)); return r; }
; __device__ __forceinline__ float bf_lo(unsigned w) { return __uint_as_float(w << 16); }
; __device__ __forceinline__ float bf_hi(unsigned w) { return __uint_as_float(w & 0xffff0000u); }
; __device__ __forceinline__ float gelu_tanh(float x) { const float z = 0.7978845608028654f * (x + 0.044715f * x * x * x); return x * sigmoidf_(2.0f * z); }
; __device__ __forceinline__ float shx(float v, int m, int lane) { return __int_as_float(__builtin_amdgcn_ds_bpermute((lane ^ m) << 2, __float_as_int(v))); }
; __device__ __forceinline__ void gmlp_conv_item(const Params& p, int l, int hs, int chunk, LAS unsigned char* lds) {
;     ...
;           for (int i = 0; i < 8; ++i) w[i] = *(const u32x2*)(P + (size_t)(v0 + wid * 16 + hb * 8 + i) * PROJ + OFF_GV + 4 * lane);
; #pragma unroll
;           for (int i = 0; i < 8; ++i) { x[i][0] = gelu_tanh(bf_lo(w[i].x)); x[i][1] = gelu_tanh(bf_hi(w[i].x)); x[i][2] = gelu_tanh(bf_lo(w[i].y)); x[i][3] = gelu_tanh(bf_hi(w[i].y));
;               sm[i] = (x[i][0] + x[i][1]) + (x[i][2] + x[i][3]); }
; #pragma unroll
;           for (int st = 1; st < 64; st <<= 1)
; #pragma unroll
;               for (int i = 0; i < 8; ++i) sm[i] += shx(sm[i], st, lane);
; #pragma unroll
;           for (int i = 0; i < 8; ++i) { const float mu = sm[i] * (1.0f / 256); float q = 0.f;
; #pragma unroll
;               for (int e = 0; e < 4; ++e) { x[i][e] -= mu; q += x[i][e] * x[i][e]; }
;               qv[i] = q; }
; #pragma unroll
;           for (int st = 1; st < 64; st <<= 1)
; #pragma unroll
;               for (int i = 0; i < 8; ++i) qv[i] += shx(qv[i], st, lane);
; #pragma unroll
;           for (int i = 0; i < 8; ++i) { const float rstd = rsqrtf(qv[i] * (1.0f / 256) + EPS); const int pt = wid * 16 + hb * 8 + i;
; #pragma unroll
;               for (int e = 0; e < 4; ++e) { const float y = x[i][e] * rstd * g4[e] + b4[e]; vT[(4 * lane + e) * 136 + pt] = (bf16_t)(cvt_pk_bf16(y, 0.f) & 0xffffu); } }
	v_add_f32_e32 v32, v32, v44
	ds_bpermute_b32 v44, v95, v38
	v_mul_f32_e32 v28, v28, v30
	v_fma_f32 v28, v2, v28, v6
	v_cvt_pk_bf16_f32 v28, v28, v1
	ds_write_b16 v96, v28 offset:6
	v_mul_f32_e32 v28, v29, v30
	v_mul_f32_e32 v27, v27, v30
	v_fma_f32 v28, v3, v28, v7
	v_fma_f32 v27, v4, v27, v8
	s_waitcnt lgkmcnt(1)
	v_add_f32_e32 v38, v38, v44
	v_cvt_pk_bf16_f32 v28, v28, v1
	ds_write_b16 v96, v28 offset:278
	v_cvt_pk_bf16_f32 v27, v27, v1
	ds_write_b16 v96, v27 offset:550
	v_fmamk_f32 v27, v38, 0x3b800000, v220
	v_cmp_gt_f32_e32 vcc, s84, v27
	v_mul_f32_e32 v28, 0x4b800000, v27
	v_mul_f32_e32 v26, v26, v30
	v_cndmask_b32_e32 v27, v27, v28, vcc
	v_rsq_f32_e32 v27, v27
	v_fma_f32 v26, v5, v26, v9
	v_cvt_pk_bf16_f32 v26, v26, v1
	ds_write_b16 v96, v26 offset:822
	v_mul_f32_e32 v26, 0x45800000, v27
	v_cndmask_b32_e32 v26, v27, v26, vcc
	v_mul_f32_e32 v24, v24, v26
	v_fma_f32 v24, v2, v24, v6
	v_cvt_pk_bf16_f32 v24, v24, v1
	ds_write_b16 v96, v24 offset:8
	v_mul_f32_e32 v24, v25, v26
	v_mul_f32_e32 v23, v23, v26
	v_fma_f32 v24, v3, v24, v7
	v_fma_f32 v23, v4, v23, v8
	v_cvt_pk_bf16_f32 v24, v24, v1
	ds_write_b16 v96, v24 offset:280
	v_cvt_pk_bf16_f32 v23, v23, v1
	ds_write_b16 v96, v23 offset:552
	v_fmamk_f32 v23, v39, 0x3b800000, v220
	v_cmp_gt_f32_e32 vcc, s84, v23
	v_mul_f32_e32 v24, 0x4b800000, v23
	v_mul_f32_e32 v22, v22, v26
	v_cndmask_b32_e32 v23, v23, v24, vcc
	v_rsq_f32_e32 v23, v23
	v_fma_f32 v22, v5, v22, v9
	v_cvt_pk_bf16_f32 v22, v22, v1
	ds_write_b16 v96, v22 offset:824
	v_mul_f32_e32 v22, 0x45800000, v23
	v_cndmask_b32_e32 v22, v23, v22, vcc
	v_mul_f32_e32 v20, v20, v22
	v_fma_f32 v20, v2, v20, v6
	v_cvt_pk_bf16_f32 v20, v20, v1
	ds_write_b16 v96, v20 offset:10
	v_mul_f32_e32 v20, v21, v22
	v_mul_f32_e32 v19, v19, v22
	v_fma_f32 v20, v3, v20, v7
	v_fma_f32 v19, v4, v19, v8
	v_cvt_pk_bf16_f32 v20, v20, v1
	ds_write_b16 v96, v20 offset:282
	v_cvt_pk_bf16_f32 v19, v19, v1
	ds_write_b16 v96, v19 offset:554
	v_fmamk_f32 v19, v36, 0x3b800000, v220
	v_cmp_gt_f32_e32 vcc, s84, v19
	v_mul_f32_e32 v20, 0x4b800000, v19
	v_mul_f32_e32 v18, v18, v22
	v_cndmask_b32_e32 v19, v19, v20, vcc
	v_rsq_f32_e32 v19, v19
	v_fma_f32 v18, v5, v18, v9
	v_cvt_pk_bf16_f32 v18, v18, v1
	ds_write_b16 v96, v18 offset:826
	v_mul_f32_e32 v18, 0x45800000, v19
	v_cndmask_b32_e32 v18, v19, v18, vcc
	ds_bpermute_b32 v42, v95, v32
	v_mul_f32_e32 v16, v16, v18
	v_fma_f32 v16, v2, v16, v6
	v_cvt_pk_bf16_f32 v16, v16, v1
	ds_write_b16 v96, v16 offset:12
	v_mul_f32_e32 v16, v17, v18
	v_mul_f32_e32 v15, v15, v18
	v_fma_f32 v16, v3, v16, v7
	v_fma_f32 v15, v4, v15, v8
	s_waitcnt lgkmcnt(1)
	v_add_f32_e32 v32, v32, v42
	v_cvt_pk_bf16_f32 v16, v16, v1
	ds_write_b16 v96, v16 offset:284
	v_cvt_pk_bf16_f32 v15, v15, v1
	ds_write_b16 v96, v15 offset:556
	v_fmamk_f32 v15, v32, 0x3b800000, v220
	v_cmp_gt_f32_e32 vcc, s84, v15
	v_mul_f32_e32 v16, 0x4b800000, v15
	v_mul_f32_e32 v14, v14, v18
	v_cndmask_b32_e32 v15, v15, v16, vcc
	v_rsq_f32_e32 v15, v15
	v_fma_f32 v14, v5, v14, v9
	v_cvt_pk_bf16_f32 v14, v14, v1
	ds_write_b16 v96, v14 offset:828
	v_mul_f32_e32 v14, 0x45800000, v15
	v_cndmask_b32_e32 v14, v15, v14, vcc
	v_mul_f32_e32 v12, v12, v14
	v_fma_f32 v12, v2, v12, v6
	v_cvt_pk_bf16_f32 v12, v12, v1
	ds_write_b16 v96, v12 offset:14
	v_mul_f32_e32 v12, v13, v14
	v_mul_f32_e32 v11, v11, v14
	v_mul_f32_e32 v10, v10, v14
	v_fma_f32 v12, v3, v12, v7
	v_fma_f32 v11, v4, v11, v8
	v_fma_f32 v10, v5, v10, v9
	v_cvt_pk_bf16_f32 v12, v12, v1
	ds_write_b16 v96, v12 offset:286
	v_cvt_pk_bf16_f32 v11, v11, v1
	ds_write_b16 v96, v11 offset:558
	v_cvt_pk_bf16_f32 v14, v10, v1
	v_or_b32_e32 v10, 8, v97
	v_mad_i64_i32 v[10:11], s[0:1], v10, s97, v[66:67]
	v_lshl_add_u64 v[10:11], v[10:11], 0, v[0:1]
	global_load_dwordx2 v[12:13], v[10:11], off offset:2048
	ds_write_b16 v96, v14 offset:830
	v_or_b32_e32 v14, 15, v97
	v_mad_i64_i32 v[18:19], s[0:1], v14, s97, v[66:67]
	v_lshl_add_u64 v[18:19], v[18:19], 0, v[0:1]
	global_load_dwordx2 v[44:45], v[18:19], off offset:2048
	v_or_b32_e32 v10, 9, v97
	v_mad_i64_i32 v[10:11], s[0:1], v10, s97, v[66:67]
	v_lshl_add_u64 v[10:11], v[10:11], 0, v[0:1]
	global_load_dwordx2 v[20:21], v[10:11], off offset:2048
	v_or_b32_e32 v10, 10, v97
	v_mad_i64_i32 v[10:11], s[0:1], v10, s97, v[66:67]
	v_lshl_add_u64 v[10:11], v[10:11], 0, v[0:1]
	global_load_dwordx2 v[28:29], v[10:11], off offset:2048
	v_or_b32_e32 v10, 11, v97
	v_mad_i64_i32 v[10:11], s[0:1], v10, s97, v[66:67]
	v_lshl_add_u64 v[10:11], v[10:11], 0, v[0:1]
	global_load_dwordx2 v[36:37], v[10:11], off offset:2048
	v_or_b32_e32 v10, 12, v97
	v_mad_i64_i32 v[10:11], s[0:1], v10, s97, v[66:67]
	v_lshl_add_u64 v[10:11], v[10:11], 0, v[0:1]
	global_load_dwordx2 v[48:49], v[10:11], off offset:2048
	v_or_b32_e32 v10, 13, v97
	v_mad_i64_i32 v[10:11], s[0:1], v10, s97, v[66:67]
	v_lshl_add_u64 v[10:11], v[10:11], 0, v[0:1]
	global_load_dwordx2 v[56:57], v[10:11], off offset:2048
	v_or_b32_e32 v10, 14, v97
	v_mad_i64_i32 v[10:11], s[0:1], v10, s97, v[66:67]
	v_lshl_add_u64 v[10:11], v[10:11], 0, v[0:1]
	global_load_dwordx2 v[46:47], v[10:11], off offset:2048
	v_and_b32_e32 v86, 15, v88
	s_movk_i32 s0, 0x110
	s_waitcnt vmcnt(7)
; __device__ __forceinline__ float bf_lo(unsigned w) { return __uint_as_float(w << 16); }
; __device__ __forceinline__ float bf_hi(unsigned w) { return __uint_as_float(w & 0xffff0000u); }
; __device__ __forceinline__ float gelu_tanh(float x) { const float z = 0.7978845608028654f * (x + 0.044715f * x * x * x); return x * sigmoidf_(2.0f * z); }
; __device__ __forceinline__ void gmlp_conv_item(const Params& p, int l, int hs, int chunk, LAS unsigned char* lds) {
;     ...
;           for (int i = 0; i < 8; ++i) { x[i][0] = gelu_tanh(bf_lo(w[i].x)); x[i][1] = gelu_tanh(bf_hi(w[i].x)); x[i][2] = gelu_tanh(bf_lo(w[i].y)); x[i][3] = gelu_tanh(bf_hi(w[i].y));
;               sm[i] = (x[i][0] + x[i][1]) + (x[i][2] + x[i][3]); }
	v_lshlrev_b32_e32 v10, 16, v12
	v_mul_f32_e32 v11, 0x3d372713, v10
	v_mul_f32_e32 v11, v11, v10
	v_fma_f32 v11, v11, v10, v10
	v_mul_f32_e32 v11, 0x3f4c422a, v11
	v_add_f32_e32 v11, v11, v11
	v_mul_f32_e32 v11, 0xbfb8aa3b, v11
	v_exp_f32_e32 v15, v11
	v_and_b32_e32 v11, 0xffff0000, v12
	v_mul_f32_e32 v12, 0x3d372713, v11
	v_mul_f32_e32 v12, v12, v11
	v_fma_f32 v12, v12, v11, v11
	v_mul_f32_e32 v12, 0x3f4c422a, v12
	v_add_f32_e32 v12, v12, v12
	v_mul_f32_e32 v12, 0xbfb8aa3b, v12
	v_exp_f32_e32 v16, v12
	v_add_f32_e32 v12, 1.0, v15
	v_lshlrev_b32_e32 v15, 16, v13
	v_mul_f32_e32 v14, 0x3d372713, v15
	v_mul_f32_e32 v14, v14, v15
	v_fma_f32 v14, v14, v15, v15
	v_mul_f32_e32 v14, 0x3f4c422a, v14
	v_add_f32_e32 v14, v14, v14
	v_mul_f32_e32 v14, 0xbfb8aa3b, v14
	v_exp_f32_e32 v17, v14
	v_and_b32_e32 v14, 0xffff0000, v13
	v_mul_f32_e32 v13, 0x3d372713, v14
	v_mul_f32_e32 v13, v13, v14
	v_fma_f32 v13, v13, v14, v14
	v_mul_f32_e32 v13, 0x3f4c422a, v13
	v_add_f32_e32 v13, v13, v13
	v_mul_f32_e32 v13, 0xbfb8aa3b, v13
	v_exp_f32_e32 v22, v13
	v_add_f32_e32 v16, 1.0, v16
	v_rcp_f32_e32 v13, v16
	v_add_f32_e32 v16, 1.0, v17
	v_rcp_f32_e32 v17, v16
	v_add_f32_e32 v16, 1.0, v22
	v_rcp_f32_e32 v12, v12
	v_rcp_f32_e32 v16, v16
	s_waitcnt vmcnt(5)
	v_lshlrev_b32_e32 v18, 16, v20
	v_mul_f32_e32 v0, 0x3d372713, v18
	v_pk_mul_f32 v[22:23], v[12:13], v[10:11]
	v_pk_mul_f32 v[24:25], v[16:17], v[14:15]
	v_mov_b32_e32 v26, v22
	v_pk_mov_b32 v[30:31], v[22:23], v[24:25] op_sel:[1,0]
	v_lshlrev_b32_e32 v23, 16, v21
	v_mul_f32_e32 v22, 0x3d372713, v23
	v_mul_f32_e32 v22, v22, v23
	v_and_b32_e32 v19, 0xffff0000, v20
	v_fma_f32 v22, v22, v23, v23
	v_mul_f32_e32 v0, v0, v18
	v_mul_f32_e32 v20, 0x3d372713, v19
	v_mul_f32_e32 v22, 0x3f4c422a, v22
	v_fma_f32 v0, v0, v18, v18
	v_mul_f32_e32 v20, v20, v19
	v_add_f32_e32 v22, v22, v22
	v_mul_f32_e32 v0, 0x3f4c422a, v0
	v_fma_f32 v20, v20, v19, v19
	v_mul_f32_e32 v22, 0xbfb8aa3b, v22
	v_add_f32_e32 v0, v0, v0
	v_mul_f32_e32 v20, 0x3f4c422a, v20
	v_exp_f32_e32 v24, v22
	v_and_b32_e32 v22, 0xffff0000, v21
	v_mul_f32_e32 v0, 0xbfb8aa3b, v0
	v_add_f32_e32 v20, v20, v20
	v_mul_f32_e32 v21, 0x3d372713, v22
	v_exp_f32_e32 v0, v0
	v_mul_f32_e32 v20, 0xbfb8aa3b, v20
	v_mul_f32_e32 v21, v21, v22
	v_exp_f32_e32 v32, v20
	v_fma_f32 v21, v21, v22, v22
	v_mul_f32_e32 v21, 0x3f4c422a, v21
	v_add_f32_e32 v21, v21, v21
	v_add_f32_e32 v0, 1.0, v0
	v_mul_f32_e32 v21, 0xbfb8aa3b, v21
	v_rcp_f32_e32 v20, v0
	v_add_f32_e32 v0, 1.0, v32
	v_exp_f32_e32 v32, v21
	v_rcp_f32_e32 v21, v0
	v_add_f32_e32 v0, 1.0, v24
	v_mov_b32_e32 v27, v25
	v_rcp_f32_e32 v25, v0
	v_add_f32_e32 v0, 1.0, v32
	v_rcp_f32_e32 v24, v0
	v_pk_add_f32 v[26:27], v[26:27], v[30:31]
	v_pk_mul_f32 v[30:31], v[20:21], v[18:19]
	v_add_f32_e32 v0, v26, v27
	s_waitcnt vmcnt(4)
	v_lshlrev_b32_e32 v26, 16, v28
	v_pk_mul_f32 v[32:33], v[24:25], v[22:23]
	v_mul_f32_e32 v27, 0x3d372713, v26
	v_mul_f32_e32 v27, v27, v26
	v_pk_mov_b32 v[38:39], v[30:31], v[32:33] op_sel:[1,0]
	v_lshlrev_b32_e32 v31, 16, v29
	v_mov_b32_e32 v34, v30
	v_fma_f32 v27, v27, v26, v26
	v_mul_f32_e32 v30, 0x3d372713, v31
	v_mul_f32_e32 v27, 0x3f4c422a, v27
	v_mul_f32_e32 v30, v30, v31
	v_add_f32_e32 v27, v27, v27
	v_fma_f32 v30, v30, v31, v31
	v_mul_f32_e32 v27, 0xbfb8aa3b, v27
	v_mul_f32_e32 v30, 0x3f4c422a, v30
	v_exp_f32_e32 v40, v27
	v_and_b32_e32 v27, 0xffff0000, v28
	v_add_f32_e32 v30, v30, v30
	v_mul_f32_e32 v28, 0x3d372713, v27
	v_mul_f32_e32 v30, 0xbfb8aa3b, v30
	v_mov_b32_e32 v35, v33
	v_mul_f32_e32 v28, v28, v27
	v_exp_f32_e32 v33, v30
	v_and_b32_e32 v30, 0xffff0000, v29
	v_fma_f32 v28, v28, v27, v27
	v_mul_f32_e32 v29, 0x3d372713, v30
	v_mul_f32_e32 v28, 0x3f4c422a, v28
	v_mul_f32_e32 v29, v29, v30
	v_add_f32_e32 v28, v28, v28
	v_fma_f32 v29, v29, v30, v30
	v_mul_f32_e32 v28, 0xbfb8aa3b, v28
	v_mul_f32_e32 v29, 0x3f4c422a, v29
	v_exp_f32_e32 v41, v28
	v_add_f32_e32 v29, v29, v29
	v_mul_f32_e32 v29, 0xbfb8aa3b, v29
	v_add_f32_e32 v28, 1.0, v40
	v_exp_f32_e32 v40, v29
	v_add_f32_e32 v32, 1.0, v41
	v_rcp_f32_e32 v29, v32
	v_add_f32_e32 v32, 1.0, v33
	v_rcp_f32_e32 v33, v32
	v_add_f32_e32 v32, 1.0, v40
	v_rcp_f32_e32 v28, v28
	v_rcp_f32_e32 v32, v32
	v_pk_add_f32 v[34:35], v[34:35], v[38:39]
	v_lshlrev_b32_e32 v79, 16, v45
	v_add_f32_e32 v80, v34, v35
	s_waitcnt vmcnt(3)
	v_lshlrev_b32_e32 v34, 16, v36
	v_pk_mul_f32 v[38:39], v[28:29], v[26:27]
	v_pk_mul_f32 v[40:41], v[32:33], v[30:31]
	v_mul_f32_e32 v35, 0x3d372713, v34
	v_mul_f32_e32 v35, v35, v34
	v_pk_mov_b32 v[50:51], v[38:39], v[40:41] op_sel:[1,0]
	v_lshlrev_b32_e32 v39, 16, v37
	v_mov_b32_e32 v42, v38
	v_fma_f32 v35, v35, v34, v34
	v_mul_f32_e32 v38, 0x3d372713, v39
	v_mul_f32_e32 v35, 0x3f4c422a, v35
	v_mul_f32_e32 v38, v38, v39
	v_add_f32_e32 v35, v35, v35
	v_fma_f32 v38, v38, v39, v39
	v_mul_f32_e32 v35, 0xbfb8aa3b, v35
	v_mul_f32_e32 v38, 0x3f4c422a, v38
	v_exp_f32_e32 v52, v35
	v_and_b32_e32 v35, 0xffff0000, v36
	v_add_f32_e32 v38, v38, v38
	v_mul_f32_e32 v36, 0x3d372713, v35
	v_mul_f32_e32 v38, 0xbfb8aa3b, v38
	v_mov_b32_e32 v43, v41
	v_mul_f32_e32 v36, v36, v35
	v_exp_f32_e32 v41, v38
	v_and_b32_e32 v38, 0xffff0000, v37
	v_fma_f32 v36, v36, v35, v35
	v_mul_f32_e32 v37, 0x3d372713, v38
	v_mul_f32_e32 v36, 0x3f4c422a, v36
	v_mul_f32_e32 v37, v37, v38
	v_add_f32_e32 v36, v36, v36
	v_fma_f32 v37, v37, v38, v38
	v_mul_f32_e32 v36, 0xbfb8aa3b, v36
	v_mul_f32_e32 v37, 0x3f4c422a, v37
	v_exp_f32_e32 v53, v36
	v_add_f32_e32 v37, v37, v37
	v_mul_f32_e32 v37, 0xbfb8aa3b, v37
	v_add_f32_e32 v36, 1.0, v52
	v_exp_f32_e32 v52, v37
	v_add_f32_e32 v40, 1.0, v53
	v_rcp_f32_e32 v37, v40
	v_add_f32_e32 v40, 1.0, v41
	v_rcp_f32_e32 v41, v40
	v_add_f32_e32 v40, 1.0, v52
	v_rcp_f32_e32 v36, v36
	v_rcp_f32_e32 v40, v40
	v_pk_add_f32 v[42:43], v[42:43], v[50:51]
	v_pk_mul_f32 v[50:51], v[36:37], v[34:35]
	v_add_f32_e32 v81, v42, v43
	s_waitcnt vmcnt(2)
; __device__ __forceinline__ float bf_lo(unsigned w) { return __uint_as_float(w << 16); }
; __device__ __forceinline__ float bf_hi(unsigned w) { return __uint_as_float(w & 0xffff0000u); }
; __device__ __forceinline__ float gelu_tanh(float x) { const float z = 0.7978845608028654f * (x + 0.044715f * x * x * x); return x * sigmoidf_(2.0f * z); }
; __device__ __forceinline__ float shx(float v, int m, int lane) { return __int_as_float(__builtin_amdgcn_ds_bpermute((lane ^ m) << 2, __float_as_int(v))); }
; __device__ __forceinline__ void gmlp_conv_item(const Params& p, int l, int hs, int chunk, LAS unsigned char* lds) {
;     ...
;           for (int i = 0; i < 8; ++i) { x[i][0] = gelu_tanh(bf_lo(w[i].x)); x[i][1] = gelu_tanh(bf_hi(w[i].x)); x[i][2] = gelu_tanh(bf_lo(w[i].y)); x[i][3] = gelu_tanh(bf_hi(w[i].y));
;               sm[i] = (x[i][0] + x[i][1]) + (x[i][2] + x[i][3]); }
; #pragma unroll
;           for (int st = 1; st < 64; st <<= 1)
; #pragma unroll
;               for (int i = 0; i < 8; ++i) sm[i] += shx(sm[i], st, lane);
	v_lshlrev_b32_e32 v42, 16, v48
	v_pk_mul_f32 v[52:53], v[40:41], v[38:39]
	v_mul_f32_e32 v43, 0x3d372713, v42
	v_mul_f32_e32 v43, v43, v42
	v_pk_mov_b32 v[58:59], v[50:51], v[52:53] op_sel:[1,0]
	v_lshlrev_b32_e32 v51, 16, v49
	v_mov_b32_e32 v54, v50
	v_fma_f32 v43, v43, v42, v42
	v_mul_f32_e32 v50, 0x3d372713, v51
	v_mul_f32_e32 v43, 0x3f4c422a, v43
	v_mul_f32_e32 v50, v50, v51
	v_add_f32_e32 v43, v43, v43
	v_fma_f32 v50, v50, v51, v51
	v_mul_f32_e32 v43, 0xbfb8aa3b, v43
	v_mul_f32_e32 v50, 0x3f4c422a, v50
	v_exp_f32_e32 v60, v43
	v_and_b32_e32 v43, 0xffff0000, v48
	v_add_f32_e32 v50, v50, v50
	v_mul_f32_e32 v48, 0x3d372713, v43
	v_mul_f32_e32 v50, 0xbfb8aa3b, v50
	v_mov_b32_e32 v55, v53
	v_mul_f32_e32 v48, v48, v43
	v_exp_f32_e32 v53, v50
	v_and_b32_e32 v50, 0xffff0000, v49
	v_fma_f32 v48, v48, v43, v43
	v_mul_f32_e32 v49, 0x3d372713, v50
	v_mul_f32_e32 v48, 0x3f4c422a, v48
	v_mul_f32_e32 v49, v49, v50
	v_add_f32_e32 v48, v48, v48
	v_fma_f32 v49, v49, v50, v50
	v_mul_f32_e32 v48, 0xbfb8aa3b, v48
	v_mul_f32_e32 v49, 0x3f4c422a, v49
	v_exp_f32_e32 v61, v48
	v_add_f32_e32 v49, v49, v49
	v_mul_f32_e32 v49, 0xbfb8aa3b, v49
	v_add_f32_e32 v48, 1.0, v60
	v_exp_f32_e32 v60, v49
	v_add_f32_e32 v52, 1.0, v61
	v_rcp_f32_e32 v49, v52
	v_add_f32_e32 v52, 1.0, v53
	v_rcp_f32_e32 v53, v52
	v_add_f32_e32 v52, 1.0, v60
	v_rcp_f32_e32 v48, v48
	v_rcp_f32_e32 v52, v52
	v_pk_add_f32 v[54:55], v[54:55], v[58:59]
	ds_bpermute_b32 v98, v90, v81
	v_add_f32_e32 v84, v54, v55
	s_waitcnt vmcnt(1)
	v_lshlrev_b32_e32 v54, 16, v56
	v_pk_mul_f32 v[58:59], v[48:49], v[42:43]
	v_pk_mul_f32 v[60:61], v[52:53], v[50:51]
	v_mul_f32_e32 v55, 0x3d372713, v54
	v_mul_f32_e32 v55, v55, v54
	v_pk_mov_b32 v[64:65], v[58:59], v[60:61] op_sel:[1,0]
	v_lshlrev_b32_e32 v59, 16, v57
	v_mov_b32_e32 v62, v58
	v_fma_f32 v55, v55, v54, v54
	v_mul_f32_e32 v58, 0x3d372713, v59
	v_mul_f32_e32 v55, 0x3f4c422a, v55
	v_mul_f32_e32 v58, v58, v59
	v_add_f32_e32 v55, v55, v55
	v_fma_f32 v58, v58, v59, v59
	v_mul_f32_e32 v55, 0xbfb8aa3b, v55
	v_mul_f32_e32 v58, 0x3f4c422a, v58
	v_exp_f32_e32 v68, v55
	v_and_b32_e32 v55, 0xffff0000, v56
	v_add_f32_e32 v58, v58, v58
	v_mul_f32_e32 v56, 0x3d372713, v55
	v_mul_f32_e32 v58, 0xbfb8aa3b, v58
	v_mov_b32_e32 v63, v61
	v_mul_f32_e32 v56, v56, v55
	v_exp_f32_e32 v61, v58
	v_and_b32_e32 v58, 0xffff0000, v57
	v_fma_f32 v56, v56, v55, v55
	v_mul_f32_e32 v57, 0x3d372713, v58
	v_mul_f32_e32 v56, 0x3f4c422a, v56
	v_mul_f32_e32 v57, v57, v58
	v_add_f32_e32 v56, v56, v56
	v_fma_f32 v57, v57, v58, v58
	v_mul_f32_e32 v56, 0xbfb8aa3b, v56
	v_mul_f32_e32 v57, 0x3f4c422a, v57
	v_exp_f32_e32 v69, v56
	v_add_f32_e32 v57, v57, v57
	v_mul_f32_e32 v57, 0xbfb8aa3b, v57
	v_add_f32_e32 v56, 1.0, v68
	v_exp_f32_e32 v68, v57
	v_add_f32_e32 v60, 1.0, v69
	v_rcp_f32_e32 v57, v60
	v_add_f32_e32 v60, 1.0, v61
	v_rcp_f32_e32 v61, v60
	v_add_f32_e32 v60, 1.0, v68
	v_rcp_f32_e32 v56, v56
	v_rcp_f32_e32 v60, v60
	v_pk_add_f32 v[62:63], v[62:63], v[64:65]
	v_pk_mul_f32 v[64:65], v[56:57], v[54:55]
	v_add_f32_e32 v85, v62, v63
	s_waitcnt vmcnt(0)
	v_lshlrev_b32_e32 v62, 16, v46
	v_pk_mul_f32 v[68:69], v[60:61], v[58:59]
	v_mul_f32_e32 v63, 0x3d372713, v62
	v_mul_f32_e32 v63, v63, v62
	v_pk_mov_b32 v[72:73], v[64:65], v[68:69] op_sel:[1,0]
	v_lshlrev_b32_e32 v65, 16, v47
	v_mov_b32_e32 v70, v64
	v_fma_f32 v63, v63, v62, v62
	v_mul_f32_e32 v64, 0x3d372713, v65
	v_mul_f32_e32 v63, 0x3f4c422a, v63
	v_mul_f32_e32 v64, v64, v65
	v_add_f32_e32 v63, v63, v63
	v_fma_f32 v64, v64, v65, v65
	v_mul_f32_e32 v63, 0xbfb8aa3b, v63
	v_mul_f32_e32 v64, 0x3f4c422a, v64
	v_exp_f32_e32 v74, v63
	v_and_b32_e32 v63, 0xffff0000, v46
	v_add_f32_e32 v64, v64, v64
	v_mul_f32_e32 v46, 0x3d372713, v63
	v_mul_f32_e32 v64, 0xbfb8aa3b, v64
	v_mov_b32_e32 v71, v69
	v_mul_f32_e32 v46, v46, v63
	v_exp_f32_e32 v69, v64
	v_and_b32_e32 v64, 0xffff0000, v47
	v_fma_f32 v46, v46, v63, v63
	v_mul_f32_e32 v47, 0x3d372713, v64
	v_mul_f32_e32 v46, 0x3f4c422a, v46
	v_mul_f32_e32 v47, v47, v64
	v_add_f32_e32 v46, v46, v46
	v_fma_f32 v47, v47, v64, v64
	v_mul_f32_e32 v46, 0xbfb8aa3b, v46
	v_mul_f32_e32 v47, 0x3f4c422a, v47
	v_exp_f32_e32 v75, v46
	v_add_f32_e32 v47, v47, v47
	v_pk_add_f32 v[70:71], v[70:71], v[72:73]
	v_mul_f32_e32 v47, 0xbfb8aa3b, v47
	v_add_f32_e32 v87, v70, v71
	v_lshlrev_b32_e32 v70, 16, v44
	v_add_f32_e32 v46, 1.0, v74
	v_exp_f32_e32 v74, v47
	v_mul_f32_e32 v71, 0x3d372713, v70
	v_mul_f32_e32 v71, v71, v70
	v_add_f32_e32 v68, 1.0, v75
	v_fma_f32 v71, v71, v70, v70
	v_rcp_f32_e32 v47, v68
	v_add_f32_e32 v68, 1.0, v69
	v_mul_f32_e32 v71, 0x3f4c422a, v71
	v_rcp_f32_e32 v69, v68
	v_add_f32_e32 v68, 1.0, v74
	v_add_f32_e32 v71, v71, v71
	v_rcp_f32_e32 v46, v46
	v_rcp_f32_e32 v68, v68
	v_mul_f32_e32 v71, 0xbfb8aa3b, v71
	v_exp_f32_e32 v78, v71
	v_and_b32_e32 v71, 0xffff0000, v44
	v_pk_mul_f32 v[72:73], v[46:47], v[62:63]
	v_pk_mul_f32 v[74:75], v[68:69], v[64:65]
	v_mul_f32_e32 v44, 0x3d372713, v71
	v_mov_b32_e32 v76, v72
	v_mov_b32_e32 v77, v75
	v_mul_f32_e32 v44, v44, v71
	v_pk_mov_b32 v[74:75], v[72:73], v[74:75] op_sel:[1,0]
	v_add_f32_e32 v72, 1.0, v78
	v_mul_f32_e32 v73, 0x3d372713, v79
	v_and_b32_e32 v78, 0xffff0000, v45
	v_fma_f32 v44, v44, v71, v71
	v_mul_f32_e32 v73, v73, v79
	v_mul_f32_e32 v45, 0x3d372713, v78
	v_mul_f32_e32 v44, 0x3f4c422a, v44
	v_fma_f32 v73, v73, v79, v79
	v_mul_f32_e32 v45, v45, v78
	v_add_f32_e32 v44, v44, v44
	v_mul_f32_e32 v73, 0x3f4c422a, v73
	v_fma_f32 v45, v45, v78, v78
	v_mul_f32_e32 v44, 0xbfb8aa3b, v44
	v_add_f32_e32 v73, v73, v73
	v_mul_f32_e32 v45, 0x3f4c422a, v45
	v_exp_f32_e32 v44, v44
	v_mul_f32_e32 v73, 0xbfb8aa3b, v73
	v_add_f32_e32 v45, v45, v45
	v_exp_f32_e32 v82, v73
	v_mul_f32_e32 v45, 0xbfb8aa3b, v45
	v_exp_f32_e32 v45, v45
	v_add_f32_e32 v44, 1.0, v44
	v_rcp_f32_e32 v73, v44
	v_add_f32_e32 v44, 1.0, v82
	v_rcp_f32_e32 v83, v44
	v_add_f32_e32 v44, 1.0, v45
	v_rcp_f32_e32 v72, v72
	v_rcp_f32_e32 v82, v44
	v_pk_add_f32 v[44:45], v[76:77], v[74:75]
	v_pk_mul_f32 v[74:75], v[82:83], v[78:79]
	v_add_f32_e32 v97, v44, v45
	v_pk_mul_f32 v[44:45], v[72:73], v[70:71]
	v_mov_b32_e32 v77, v75
	v_mov_b32_e32 v76, v44
	v_pk_mov_b32 v[44:45], v[44:45], v[74:75] op_sel:[1,0]
	ds_bpermute_b32 v74, v90, v0
	ds_bpermute_b32 v75, v90, v80
	v_pk_add_f32 v[44:45], v[76:77], v[44:45]
	ds_bpermute_b32 v76, v90, v85
	v_add_f32_e32 v44, v44, v45
	s_waitcnt lgkmcnt(2)
; __device__ __forceinline__ float shx(float v, int m, int lane) { return __int_as_float(__builtin_amdgcn_ds_bpermute((lane ^ m) << 2, __float_as_int(v))); }
; __device__ __forceinline__ void gmlp_conv_item(const Params& p, int l, int hs, int chunk, LAS unsigned char* lds) {
;     ...
;           for (int st = 1; st < 64; st <<= 1)
; #pragma unroll
;               for (int i = 0; i < 8; ++i) sm[i] += shx(sm[i], st, lane);
; #pragma unroll
;           for (int i = 0; i < 8; ++i) { const float mu = sm[i] * (1.0f / 256); float q = 0.f;
; #pragma unroll
;               for (int e = 0; e < 4; ++e) { x[i][e] -= mu; q += x[i][e] * x[i][e]; }
;               qv[i] = q; }
	v_add_f32_e32 v0, v0, v74
	v_add_f32_e32 v74, v81, v98
	ds_bpermute_b32 v81, v90, v44
	s_waitcnt lgkmcnt(2)
	v_add_f32_e32 v45, v80, v75
	ds_bpermute_b32 v75, v90, v84
	ds_bpermute_b32 v77, v90, v87
	ds_bpermute_b32 v80, v90, v97
	s_waitcnt lgkmcnt(3)
	v_add_f32_e32 v44, v44, v81
	ds_bpermute_b32 v81, v91, v0
	s_waitcnt lgkmcnt(3)
	v_add_f32_e32 v75, v84, v75
	v_add_f32_e32 v76, v85, v76
	ds_bpermute_b32 v84, v91, v45
	ds_bpermute_b32 v85, v91, v74
	s_waitcnt lgkmcnt(4)
	v_add_f32_e32 v77, v87, v77
	s_waitcnt lgkmcnt(3)
	v_add_f32_e32 v80, v97, v80
	ds_bpermute_b32 v87, v91, v75
	ds_bpermute_b32 v97, v91, v76
	s_waitcnt lgkmcnt(4)
	v_add_f32_e32 v0, v0, v81
	ds_bpermute_b32 v81, v91, v77
	s_waitcnt lgkmcnt(4)
	v_add_f32_e32 v45, v45, v84
	s_waitcnt lgkmcnt(3)
	v_add_f32_e32 v74, v74, v85
	ds_bpermute_b32 v84, v91, v80
	ds_bpermute_b32 v85, v91, v44
	s_waitcnt lgkmcnt(4)
	v_add_f32_e32 v75, v75, v87
	s_waitcnt lgkmcnt(3)
	v_add_f32_e32 v76, v76, v97
	ds_bpermute_b32 v87, v92, v0
	ds_bpermute_b32 v97, v92, v45
	s_waitcnt lgkmcnt(4)
	v_add_f32_e32 v77, v77, v81
	ds_bpermute_b32 v81, v92, v74
	s_waitcnt lgkmcnt(4)
	v_add_f32_e32 v80, v80, v84
	s_waitcnt lgkmcnt(3)
	v_add_f32_e32 v44, v44, v85
	ds_bpermute_b32 v84, v92, v75
	ds_bpermute_b32 v85, v92, v76
	s_waitcnt lgkmcnt(4)
	v_add_f32_e32 v0, v0, v87
	s_waitcnt lgkmcnt(3)
	v_add_f32_e32 v45, v45, v97
	ds_bpermute_b32 v87, v92, v77
	ds_bpermute_b32 v97, v92, v80
	s_waitcnt lgkmcnt(4)
	v_add_f32_e32 v74, v74, v81
	ds_bpermute_b32 v81, v92, v44
	s_waitcnt lgkmcnt(4)
	v_add_f32_e32 v75, v75, v84
	s_waitcnt lgkmcnt(3)
	v_add_f32_e32 v76, v76, v85
	ds_bpermute_b32 v84, v93, v0
	ds_bpermute_b32 v85, v93, v45
	s_waitcnt lgkmcnt(4)
	v_add_f32_e32 v77, v77, v87
	s_waitcnt lgkmcnt(3)
	v_add_f32_e32 v80, v80, v97
	ds_bpermute_b32 v87, v93, v74
	ds_bpermute_b32 v97, v93, v75
	s_waitcnt lgkmcnt(4)
	v_add_f32_e32 v44, v44, v81
	ds_bpermute_b32 v81, v93, v76
	s_waitcnt lgkmcnt(4)
	v_add_f32_e32 v0, v0, v84
	s_waitcnt lgkmcnt(3)
	v_add_f32_e32 v45, v45, v85
	ds_bpermute_b32 v84, v93, v77
	ds_bpermute_b32 v85, v93, v80
	s_waitcnt lgkmcnt(4)
	v_add_f32_e32 v74, v74, v87
	s_waitcnt lgkmcnt(3)
	v_add_f32_e32 v75, v75, v97
	ds_bpermute_b32 v87, v93, v44
	ds_bpermute_b32 v97, v94, v0
	s_waitcnt lgkmcnt(4)
	v_add_f32_e32 v76, v76, v81
	ds_bpermute_b32 v81, v94, v45
	s_waitcnt lgkmcnt(4)
	v_add_f32_e32 v77, v77, v84
	s_waitcnt lgkmcnt(3)
	v_add_f32_e32 v80, v80, v85
	ds_bpermute_b32 v84, v94, v74
	ds_bpermute_b32 v85, v94, v75
	s_waitcnt lgkmcnt(4)
	v_add_f32_e32 v44, v44, v87
	s_waitcnt lgkmcnt(3)
	v_add_f32_e32 v0, v0, v97
	ds_bpermute_b32 v97, v94, v77
	s_waitcnt lgkmcnt(3)
	v_add_f32_e32 v45, v45, v81
	ds_bpermute_b32 v81, v94, v80
	ds_bpermute_b32 v87, v94, v76
	s_waitcnt lgkmcnt(4)
	v_add_f32_e32 v74, v74, v84
	s_waitcnt lgkmcnt(3)
	v_add_f32_e32 v75, v75, v85
	ds_bpermute_b32 v84, v94, v44
	ds_bpermute_b32 v85, v95, v0
	s_waitcnt lgkmcnt(4)
	v_add_f32_e32 v77, v77, v97
	s_waitcnt lgkmcnt(3)
	v_add_f32_e32 v80, v80, v81
	s_waitcnt lgkmcnt(2)
	v_add_f32_e32 v76, v76, v87
	s_waitcnt lgkmcnt(1)
	v_add_f32_e32 v44, v44, v84
	s_waitcnt lgkmcnt(0)
	v_add_f32_e32 v0, v0, v85
	ds_bpermute_b32 v84, v95, v77
	ds_bpermute_b32 v85, v95, v80
	ds_bpermute_b32 v87, v95, v45
	ds_bpermute_b32 v97, v95, v74
	ds_bpermute_b32 v81, v95, v76
	v_mul_f32_e32 v0, 0x3b800000, v0
	s_waitcnt lgkmcnt(4)
	v_add_f32_e32 v100, v77, v84
	s_waitcnt lgkmcnt(3)
	v_add_f32_e32 v101, v80, v85
	v_pk_fma_f32 v[84:85], v[12:13], v[10:11], v[0:1] op_sel_hi:[1,1,0] neg_lo:[0,0,1] neg_hi:[0,0,1]
	s_waitcnt lgkmcnt(2)
	v_add_f32_e32 v45, v45, v87
	s_waitcnt lgkmcnt(1)
	v_add_f32_e32 v87, v74, v97
	ds_bpermute_b32 v74, v95, v75
	s_waitcnt lgkmcnt(1)
	v_add_f32_e32 v99, v76, v81
	v_pk_mul_f32 v[10:11], v[84:85], v[84:85]
	v_pk_fma_f32 v[80:81], v[16:17], v[14:15], v[0:1] op_sel_hi:[1,1,0] neg_lo:[0,0,1] neg_hi:[0,0,1]
	v_add_f32_e32 v0, v10, v11
	v_pk_mul_f32 v[12:13], v[80:81], v[80:81]
	ds_bpermute_b32 v97, v95, v44
	v_add_f32_e32 v0, v13, v0
	v_add_f32_e32 v102, v12, v0
	v_mul_f32_e32 v0, 0x3b800000, v45
	v_pk_fma_f32 v[76:77], v[20:21], v[18:19], v[0:1] op_sel_hi:[1,1,0] neg_lo:[0,0,1] neg_hi:[0,0,1]
	s_waitcnt lgkmcnt(1)
	v_add_f32_e32 v98, v75, v74
	v_pk_mul_f32 v[10:11], v[76:77], v[76:77]
	v_pk_fma_f32 v[74:75], v[24:25], v[22:23], v[0:1] op_sel_hi:[1,1,0] neg_lo:[0,0,1] neg_hi:[0,0,1]
	v_add_f32_e32 v0, v10, v11
	v_pk_mul_f32 v[12:13], v[74:75], v[74:75]
	s_waitcnt lgkmcnt(0)
; __device__ __forceinline__ float shx(float v, int m, int lane) { return __int_as_float(__builtin_amdgcn_ds_bpermute((lane ^ m) << 2, __float_as_int(v))); }
; __device__ __forceinline__ void gmlp_conv_item(const Params& p, int l, int hs, int chunk, LAS unsigned char* lds) {
;     ...
;           for (int i = 0; i < 8; ++i) { const float mu = sm[i] * (1.0f / 256); float q = 0.f;
; #pragma unroll
;               for (int e = 0; e < 4; ++e) { x[i][e] -= mu; q += x[i][e] * x[i][e]; }
;               qv[i] = q; }
; #pragma unroll
;           for (int st = 1; st < 64; st <<= 1)
; #pragma unroll
;               for (int i = 0; i < 8; ++i) qv[i] += shx(qv[i], st, lane);
	v_add_f32_e32 v97, v44, v97
	v_add_f32_e32 v0, v13, v0
	v_add_f32_e32 v103, v12, v0
	v_mul_f32_e32 v0, 0x3b800000, v87
	v_pk_fma_f32 v[44:45], v[28:29], v[26:27], v[0:1] op_sel_hi:[1,1,0] neg_lo:[0,0,1] neg_hi:[0,0,1]
	v_pk_fma_f32 v[30:31], v[32:33], v[30:31], v[0:1] op_sel_hi:[1,1,0] neg_lo:[0,0,1] neg_hi:[0,0,1]
	v_pk_mul_f32 v[10:11], v[44:45], v[44:45]
	v_pk_mul_f32 v[12:13], v[30:31], v[30:31]
	v_add_f32_e32 v0, v10, v11
	v_add_f32_e32 v0, v13, v0
	v_add_f32_e32 v87, v12, v0
	v_mul_f32_e32 v0, 0x3b800000, v98
	v_pk_fma_f32 v[28:29], v[36:37], v[34:35], v[0:1] op_sel_hi:[1,1,0] neg_lo:[0,0,1] neg_hi:[0,0,1]
	v_pk_fma_f32 v[26:27], v[40:41], v[38:39], v[0:1] op_sel_hi:[1,1,0] neg_lo:[0,0,1] neg_hi:[0,0,1]
	v_pk_mul_f32 v[10:11], v[28:29], v[28:29]
	v_pk_mul_f32 v[12:13], v[26:27], v[26:27]
	v_add_f32_e32 v0, v10, v11
	v_add_f32_e32 v0, v13, v0
	v_add_f32_e32 v36, v12, v0
	v_mul_f32_e32 v0, 0x3b800000, v99
	v_pk_fma_f32 v[24:25], v[48:49], v[42:43], v[0:1] op_sel_hi:[1,1,0] neg_lo:[0,0,1] neg_hi:[0,0,1]
	v_pk_fma_f32 v[22:23], v[52:53], v[50:51], v[0:1] op_sel_hi:[1,1,0] neg_lo:[0,0,1] neg_hi:[0,0,1]
	v_pk_mul_f32 v[10:11], v[24:25], v[24:25]
	v_pk_mul_f32 v[12:13], v[22:23], v[22:23]
	v_add_f32_e32 v0, v10, v11
	v_add_f32_e32 v0, v13, v0
	v_add_f32_e32 v37, v12, v0
	v_mul_f32_e32 v0, 0x3b800000, v100
	v_pk_fma_f32 v[20:21], v[56:57], v[54:55], v[0:1] op_sel_hi:[1,1,0] neg_lo:[0,0,1] neg_hi:[0,0,1]
	v_pk_fma_f32 v[18:19], v[60:61], v[58:59], v[0:1] op_sel_hi:[1,1,0] neg_lo:[0,0,1] neg_hi:[0,0,1]
	v_pk_mul_f32 v[10:11], v[20:21], v[20:21]
	v_pk_mul_f32 v[12:13], v[18:19], v[18:19]
	v_add_f32_e32 v0, v10, v11
	v_add_f32_e32 v0, v13, v0
	v_add_f32_e32 v38, v12, v0
	v_mul_f32_e32 v0, 0x3b800000, v101
	v_pk_fma_f32 v[16:17], v[46:47], v[62:63], v[0:1] op_sel_hi:[1,1,0] neg_lo:[0,0,1] neg_hi:[0,0,1]
	v_pk_fma_f32 v[14:15], v[68:69], v[64:65], v[0:1] op_sel_hi:[1,1,0] neg_lo:[0,0,1] neg_hi:[0,0,1]
	v_pk_mul_f32 v[10:11], v[16:17], v[16:17]
	v_pk_mul_f32 v[12:13], v[14:15], v[14:15]
	v_add_f32_e32 v0, v10, v11
	v_add_f32_e32 v0, v13, v0
	v_add_f32_e32 v39, v12, v0
	v_mul_f32_e32 v0, 0x3b800000, v97
	v_pk_fma_f32 v[12:13], v[72:73], v[70:71], v[0:1] op_sel_hi:[1,1,0] neg_lo:[0,0,1] neg_hi:[0,0,1]
	v_pk_fma_f32 v[10:11], v[82:83], v[78:79], v[0:1] op_sel_hi:[1,1,0] neg_lo:[0,0,1] neg_hi:[0,0,1]
	v_pk_mul_f32 v[32:33], v[12:13], v[12:13]
	v_pk_mul_f32 v[34:35], v[10:11], v[10:11]
	v_add_f32_e32 v0, v32, v33
	v_add_f32_e32 v0, v35, v0
	ds_bpermute_b32 v35, v90, v36
	ds_bpermute_b32 v40, v90, v37
	ds_bpermute_b32 v32, v90, v102
	v_add_f32_e32 v0, v34, v0
	ds_bpermute_b32 v34, v90, v87
	s_waitcnt lgkmcnt(3)
	v_add_f32_e32 v35, v36, v35
	s_waitcnt lgkmcnt(2)
	v_add_f32_e32 v36, v37, v40
	ds_bpermute_b32 v37, v90, v38
	ds_bpermute_b32 v40, v90, v39
	s_waitcnt lgkmcnt(3)
	v_add_f32_e32 v32, v102, v32
	ds_bpermute_b32 v33, v90, v103
	ds_bpermute_b32 v42, v91, v32
	s_waitcnt lgkmcnt(4)
	v_add_f32_e32 v34, v87, v34
	ds_bpermute_b32 v41, v90, v0
	s_waitcnt lgkmcnt(4)
	v_add_f32_e32 v37, v38, v37
	s_waitcnt lgkmcnt(3)
	v_add_f32_e32 v38, v39, v40
	ds_bpermute_b32 v39, v91, v34
	s_waitcnt lgkmcnt(3)
	v_add_f32_e32 v33, v103, v33
	s_waitcnt lgkmcnt(2)
	v_add_f32_e32 v32, v32, v42
	ds_bpermute_b32 v42, v91, v37
	ds_bpermute_b32 v43, v91, v33
	s_waitcnt lgkmcnt(3)
	v_add_f32_e32 v0, v0, v41
	ds_bpermute_b32 v41, v91, v36
	s_waitcnt lgkmcnt(3)
	v_add_f32_e32 v34, v34, v39
	ds_bpermute_b32 v39, v91, v0
	ds_bpermute_b32 v40, v91, v35
	s_waitcnt lgkmcnt(4)
	v_add_f32_e32 v37, v37, v42
	ds_bpermute_b32 v42, v92, v34
	s_waitcnt lgkmcnt(4)
	v_add_f32_e32 v33, v33, v43
	ds_bpermute_b32 v43, v91, v38
	s_waitcnt lgkmcnt(4)
	v_add_f32_e32 v36, v36, v41
	ds_bpermute_b32 v41, v92, v33
	s_waitcnt lgkmcnt(4)
	v_add_f32_e32 v0, v0, v39
	ds_bpermute_b32 v39, v92, v36
	s_waitcnt lgkmcnt(4)
	v_add_f32_e32 v35, v35, v40
	ds_bpermute_b32 v40, v92, v32
	s_waitcnt lgkmcnt(4)
	v_add_f32_e32 v34, v34, v42
	ds_bpermute_b32 v42, v92, v0
	s_waitcnt lgkmcnt(4)
	v_add_f32_e32 v38, v38, v43
	ds_bpermute_b32 v43, v92, v35
	s_waitcnt lgkmcnt(4)
	v_add_f32_e32 v33, v33, v41
	ds_bpermute_b32 v41, v92, v38
	s_waitcnt lgkmcnt(4)
	v_add_f32_e32 v36, v36, v39
	ds_bpermute_b32 v39, v93, v33
	s_waitcnt lgkmcnt(4)
	v_add_f32_e32 v32, v32, v40
	s_waitcnt lgkmcnt(3)
	v_add_f32_e32 v0, v0, v42
	ds_bpermute_b32 v42, v93, v36
	s_waitcnt lgkmcnt(3)
	v_add_f32_e32 v35, v35, v43
	ds_bpermute_b32 v43, v93, v32
	s_waitcnt lgkmcnt(3)
	v_add_f32_e32 v38, v38, v41
	ds_bpermute_b32 v41, v93, v35
	ds_bpermute_b32 v40, v92, v37
	s_waitcnt lgkmcnt(4)
	v_add_f32_e32 v33, v33, v39
	ds_bpermute_b32 v39, v93, v38
	s_waitcnt lgkmcnt(4)
	v_add_f32_e32 v36, v36, v42
	ds_bpermute_b32 v42, v94, v33
	s_waitcnt lgkmcnt(4)
	v_add_f32_e32 v32, v32, v43
	s_waitcnt lgkmcnt(3)
	v_add_f32_e32 v35, v35, v41
	ds_bpermute_b32 v41, v94, v32
	s_waitcnt lgkmcnt(3)
	v_add_f32_e32 v37, v37, v40
	s_waitcnt lgkmcnt(2)
	v_add_f32_e32 v38, v38, v39
	ds_bpermute_b32 v39, v94, v35
	ds_bpermute_b32 v43, v93, v37
	s_waitcnt lgkmcnt(3)
	v_add_f32_e32 v33, v33, v42
	ds_bpermute_b32 v42, v94, v38
	s_waitcnt lgkmcnt(3)
	v_add_f32_e32 v32, v32, v41
	s_waitcnt lgkmcnt(2)
	v_add_f32_e32 v35, v35, v39
	ds_bpermute_b32 v39, v95, v32
	s_waitcnt lgkmcnt(2)
	v_add_f32_e32 v37, v37, v43
	ds_bpermute_b32 v40, v93, v34
	ds_bpermute_b32 v41, v94, v37
	s_waitcnt lgkmcnt(3)
	v_add_f32_e32 v38, v38, v42
	ds_bpermute_b32 v42, v95, v35
	s_waitcnt lgkmcnt(3)
	v_add_f32_e32 v32, v32, v39
	v_fmamk_f32 v32, v32, 0x3b800000, v220
	s_waitcnt lgkmcnt(2)
	v_add_f32_e32 v34, v34, v40
	ds_bpermute_b32 v40, v93, v0
	s_waitcnt lgkmcnt(2)
	v_add_f32_e32 v37, v37, v41
	s_waitcnt lgkmcnt(1)
; __device__ __forceinline__ unsigned cvt_pk_bf16(float lo, float hi) { unsigned r; asm volatile("v_cvt_pk_bf16_f32 %0, %1, %2" : "=v"(r) : "v"(lo), "v"(hi)); return r; }
; __device__ __forceinline__ float shx(float v, int m, int lane) { return __int_as_float(__builtin_amdgcn_ds_bpermute((lane ^ m) << 2, __float_as_int(v))); }
; __device__ __forceinline__ void gmlp_conv_item(const Params& p, int l, int hs, int chunk, LAS unsigned char* lds) {
;     ...
;           for (int st = 1; st < 64; st <<= 1)
; #pragma unroll
;               for (int i = 0; i < 8; ++i) qv[i] += shx(qv[i], st, lane);
; #pragma unroll
;           for (int i = 0; i < 8; ++i) { const float rstd = rsqrtf(qv[i] * (1.0f / 256) + EPS); const int pt = wid * 16 + hb * 8 + i;
; #pragma unroll
;               for (int e = 0; e < 4; ++e) { const float y = x[i][e] * rstd * g4[e] + b4[e]; vT[(4 * lane + e) * 136 + pt] = (bf16_t)(cvt_pk_bf16(y, 0.f) & 0xffffu); } }
	v_add_f32_e32 v35, v35, v42
	v_cmp_gt_f32_e32 vcc, s84, v32
	v_mul_f32_e32 v42, 0x4b800000, v32
	ds_bpermute_b32 v39, v95, v37
	v_cndmask_b32_e32 v32, v32, v42, vcc
	v_rsq_f32_e32 v32, v32
	s_waitcnt lgkmcnt(1)
	v_add_f32_e32 v0, v0, v40
	ds_bpermute_b32 v40, v94, v36
	s_waitcnt lgkmcnt(1)
	v_add_f32_e32 v37, v37, v39
	v_mul_f32_e32 v39, 0x45800000, v32
	v_cndmask_b32_e32 v32, v32, v39, vcc
	v_mul_f32_e32 v39, v84, v32
	v_fma_f32 v39, v2, v39, v6
	s_waitcnt lgkmcnt(0)
	v_add_f32_e32 v36, v36, v40
	ds_bpermute_b32 v40, v95, v33
	v_cvt_pk_bf16_f32 v39, v39, v1
	ds_write_b16 v96, v39 offset:16
	v_mul_f32_e32 v39, v85, v32
	v_fma_f32 v39, v3, v39, v7
	v_cvt_pk_bf16_f32 v39, v39, v1
	ds_write_b16 v96, v39 offset:288
	v_mul_f32_e32 v39, v81, v32
	s_waitcnt lgkmcnt(2)
	v_add_f32_e32 v33, v33, v40
	v_fma_f32 v39, v4, v39, v8
	v_cvt_pk_bf16_f32 v39, v39, v1
	v_fmamk_f32 v33, v33, 0x3b800000, v220
	ds_write_b16 v96, v39 offset:560
	v_cmp_gt_f32_e32 vcc, s84, v33
	v_mul_f32_e32 v39, 0x4b800000, v33
	v_mul_f32_e32 v32, v80, v32
	v_cndmask_b32_e32 v33, v33, v39, vcc
	v_rsq_f32_e32 v33, v33
	v_fma_f32 v32, v5, v32, v9
	ds_bpermute_b32 v43, v94, v34
	v_cvt_pk_bf16_f32 v32, v32, v1
	ds_write_b16 v96, v32 offset:832
	v_mul_f32_e32 v32, 0x45800000, v33
	v_cndmask_b32_e32 v32, v33, v32, vcc
	v_mul_f32_e32 v33, v76, v32
	v_fma_f32 v33, v2, v33, v6
	s_waitcnt lgkmcnt(1)
	v_add_f32_e32 v34, v34, v43
	v_cvt_pk_bf16_f32 v33, v33, v1
	ds_bpermute_b32 v41, v95, v34
	ds_write_b16 v96, v33 offset:18
	v_mul_f32_e32 v33, v77, v32
	v_fma_f32 v33, v3, v33, v7
	v_cvt_pk_bf16_f32 v33, v33, v1
	ds_write_b16 v96, v33 offset:290
	v_mul_f32_e32 v33, v75, v32
	v_fma_f32 v33, v4, v33, v8
	s_waitcnt lgkmcnt(2)
	v_add_f32_e32 v34, v34, v41
	v_cvt_pk_bf16_f32 v33, v33, v1
	ds_write_b16 v96, v33 offset:562
	v_fmamk_f32 v33, v34, 0x3b800000, v220
	v_cmp_gt_f32_e32 vcc, s84, v33
	v_mul_f32_e32 v34, 0x4b800000, v33
	v_mul_f32_e32 v32, v74, v32
	v_cndmask_b32_e32 v33, v33, v34, vcc
	v_rsq_f32_e32 v33, v33
	v_fma_f32 v32, v5, v32, v9
	v_cvt_pk_bf16_f32 v32, v32, v1
	ds_write_b16 v96, v32 offset:834
	v_mul_f32_e32 v32, 0x45800000, v33
	v_cndmask_b32_e32 v32, v33, v32, vcc
	v_mul_f32_e32 v33, v44, v32
	v_fma_f32 v33, v2, v33, v6
	v_cvt_pk_bf16_f32 v33, v33, v1
	ds_write_b16 v96, v33 offset:20
	v_mul_f32_e32 v33, v45, v32
	v_mul_f32_e32 v31, v31, v32
	v_fma_f32 v33, v3, v33, v7
	v_fma_f32 v31, v4, v31, v8
	v_cvt_pk_bf16_f32 v33, v33, v1
	ds_write_b16 v96, v33 offset:292
	v_cvt_pk_bf16_f32 v31, v31, v1
	ds_write_b16 v96, v31 offset:564
	v_fmamk_f32 v31, v35, 0x3b800000, v220
	v_mul_f32_e32 v30, v30, v32
	v_cmp_gt_f32_e32 vcc, s84, v31
	v_mul_f32_e32 v32, 0x4b800000, v31
	ds_bpermute_b32 v43, v94, v0
	v_cndmask_b32_e32 v31, v31, v32, vcc
	v_rsq_f32_e32 v31, v31
	v_fma_f32 v30, v5, v30, v9
	v_cvt_pk_bf16_f32 v30, v30, v1
	ds_write_b16 v96, v30 offset:836
	v_mul_f32_e32 v30, 0x45800000, v31
	v_cndmask_b32_e32 v30, v31, v30, vcc
	s_waitcnt lgkmcnt(1)
	v_add_f32_e32 v0, v0, v43
	ds_bpermute_b32 v43, v95, v36
	v_mul_f32_e32 v28, v28, v30
	v_fma_f32 v28, v2, v28, v6
	v_cvt_pk_bf16_f32 v28, v28, v1
	ds_write_b16 v96, v28 offset:22
	v_mul_f32_e32 v28, v29, v30
	v_mul_f32_e32 v27, v27, v30
	v_fma_f32 v28, v3, v28, v7
	v_fma_f32 v27, v4, v27, v8
	s_waitcnt lgkmcnt(1)
	v_add_f32_e32 v36, v36, v43
	v_cvt_pk_bf16_f32 v28, v28, v1
	ds_write_b16 v96, v28 offset:294
	v_cvt_pk_bf16_f32 v27, v27, v1
	ds_write_b16 v96, v27 offset:566
	v_fmamk_f32 v27, v36, 0x3b800000, v220
	v_cmp_gt_f32_e32 vcc, s84, v27
	v_mul_f32_e32 v28, 0x4b800000, v27
	v_mul_f32_e32 v26, v26, v30
	v_cndmask_b32_e32 v27, v27, v28, vcc
	v_rsq_f32_e32 v27, v27
	v_fma_f32 v26, v5, v26, v9
	v_cvt_pk_bf16_f32 v26, v26, v1
	ds_write_b16 v96, v26 offset:838
	v_mul_f32_e32 v26, 0x45800000, v27
	v_cndmask_b32_e32 v26, v27, v26, vcc
	v_mul_f32_e32 v24, v24, v26
	v_fma_f32 v24, v2, v24, v6
	v_cvt_pk_bf16_f32 v24, v24, v1
	ds_write_b16 v96, v24 offset:24
	v_mul_f32_e32 v24, v25, v26
	v_mul_f32_e32 v23, v23, v26
	v_fma_f32 v24, v3, v24, v7
	v_fma_f32 v23, v4, v23, v8
	v_cvt_pk_bf16_f32 v24, v24, v1
	ds_write_b16 v96, v24 offset:296
	v_cvt_pk_bf16_f32 v23, v23, v1
	ds_write_b16 v96, v23 offset:568
	v_fmamk_f32 v23, v37, 0x3b800000, v220
	v_cmp_gt_f32_e32 vcc, s84, v23
	v_mul_f32_e32 v24, 0x4b800000, v23
	v_mul_f32_e32 v22, v22, v26
	v_cndmask_b32_e32 v23, v23, v24, vcc
	v_rsq_f32_e32 v23, v23
	v_fma_f32 v22, v5, v22, v9
	v_cvt_pk_bf16_f32 v22, v22, v1
	ds_write_b16 v96, v22 offset:840
	v_mul_f32_e32 v22, 0x45800000, v23
	v_cndmask_b32_e32 v22, v23, v22, vcc
	ds_bpermute_b32 v40, v95, v38
	v_mul_f32_e32 v20, v20, v22
	v_fma_f32 v20, v2, v20, v6
	v_cvt_pk_bf16_f32 v20, v20, v1
	ds_write_b16 v96, v20 offset:26
	v_mul_f32_e32 v20, v21, v22
	v_mul_f32_e32 v19, v19, v22
	v_fma_f32 v20, v3, v20, v7
	v_fma_f32 v19, v4, v19, v8
	s_waitcnt lgkmcnt(1)
	v_add_f32_e32 v38, v38, v40
	v_cvt_pk_bf16_f32 v20, v20, v1
	ds_write_b16 v96, v20 offset:298
	v_cvt_pk_bf16_f32 v19, v19, v1
	ds_write_b16 v96, v19 offset:570
	v_fmamk_f32 v19, v38, 0x3b800000, v220
	v_cmp_gt_f32_e32 vcc, s84, v19
	v_mul_f32_e32 v20, 0x4b800000, v19
	v_mul_f32_e32 v18, v18, v22
	v_cndmask_b32_e32 v19, v19, v20, vcc
	v_rsq_f32_e32 v19, v19
	v_fma_f32 v18, v5, v18, v9
	v_cvt_pk_bf16_f32 v18, v18, v1
	ds_write_b16 v96, v18 offset:842
	v_mul_f32_e32 v18, 0x45800000, v19
	ds_bpermute_b32 v41, v95, v0
	v_cndmask_b32_e32 v18, v19, v18, vcc
	v_mul_f32_e32 v16, v16, v18
	v_fma_f32 v16, v2, v16, v6
	v_cvt_pk_bf16_f32 v16, v16, v1
	ds_write_b16 v96, v16 offset:28
	v_mul_f32_e32 v16, v17, v18
	v_mul_f32_e32 v15, v15, v18
	s_waitcnt lgkmcnt(1)
; #define LAS __attribute__((address_space(3)))
; __device__ __forceinline__ unsigned cvt_pk_bf16(float lo, float hi) { unsigned r; asm volatile("v_cvt_pk_bf16_f32 %0, %1, %2" : "=v"(r) : "v"(lo), "v"(hi)); return r; }
; __device__ __forceinline__ void gmlp_conv_item(const Params& p, int l, int hs, int chunk, LAS unsigned char* lds) {
;     ...
;           for (int i = 0; i < 8; ++i) { const float rstd = rsqrtf(qv[i] * (1.0f / 256) + EPS); const int pt = wid * 16 + hb * 8 + i;
; #pragma unroll
;               for (int e = 0; e < 4; ++e) { const float y = x[i][e] * rstd * g4[e] + b4[e]; vT[(4 * lane + e) * 136 + pt] = (bf16_t)(cvt_pk_bf16(y, 0.f) & 0xffffu); } }
;       } }
;     __syncthreads();
;     { const int g = wid >> 1, ph = wid & 1;
;       const bf16_t* wsb = (const bf16_t*)(p.ws + WS_WT) + (size_t)l * W_LAYER + W_GWS + (size_t)g * 128 * 128;
;       f32x4 acc[4][4];
; #pragma unroll
;       for (int a = 0; a < 4; ++a)
; #pragma unroll
;           for (int b = 0; b < 4; ++b) acc[a][b] = (f32x4){0.f, 0.f, 0.f, 0.f};
; #pragma unroll
;       for (int kk = 0; kk < 4; ++kk) {
;           bf16x8 af[4], bfr[4];
; #pragma unroll
;           for (int db = 0; db < 4; ++db) af[db] = *(const LAS bf16x8*)(vT + (g * 64 + db * 16 + fr) * 136 + kk * 32 + fq * 8);
; #pragma unroll
;           for (int pb = 0; pb < 4; ++pb) bfr[pb] = *(const bf16x8*)(wsb + (size_t)((ph * 4 + pb) * 16 + fr) * 128 + kk * 32 + fq * 8);
; #pragma unroll
;           for (int db = 0; db < 4; ++db)
; #pragma unroll
;               for (int pb = 0; pb < 4; ++pb) acc[db][pb] = __builtin_amdgcn_mfma_f32_16x16x32_bf16(af[db], bfr[pb], acc[db][pb], 0, 0, 0);
;       }
	v_add_f32_e32 v0, v0, v41
	v_fma_f32 v16, v3, v16, v7
	v_fma_f32 v15, v4, v15, v8
	v_cvt_pk_bf16_f32 v16, v16, v1
	ds_write_b16 v96, v16 offset:300
	v_cvt_pk_bf16_f32 v15, v15, v1
	v_fmamk_f32 v0, v0, 0x3b800000, v220
	ds_write_b16 v96, v15 offset:572
	v_cmp_gt_f32_e32 vcc, s84, v0
	v_mul_f32_e32 v15, 0x4b800000, v0
	v_mul_f32_e32 v14, v14, v18
	v_cndmask_b32_e32 v0, v0, v15, vcc
	v_rsq_f32_e32 v0, v0
	v_fma_f32 v14, v5, v14, v9
	v_cvt_pk_bf16_f32 v14, v14, v1
	ds_write_b16 v96, v14 offset:844
	v_mul_f32_e32 v14, 0x45800000, v0
	v_cndmask_b32_e32 v0, v0, v14, vcc
	v_mul_f32_e32 v12, v12, v0
	v_fma_f32 v2, v2, v12, v6
	v_cvt_pk_bf16_f32 v2, v2, v1
	ds_write_b16 v96, v2 offset:30
	v_mul_f32_e32 v2, v13, v0
	v_fma_f32 v2, v3, v2, v7
	v_cvt_pk_bf16_f32 v2, v2, v1
	ds_write_b16 v96, v2 offset:302
	v_mul_f32_e32 v2, v11, v0
	v_fma_f32 v2, v4, v2, v8
	v_ashrrev_i32_e32 v6, 7, v88
	v_cvt_pk_bf16_f32 v2, v2, v1
	v_mul_f32_e32 v0, v10, v0
	v_ashrrev_i32_e32 v7, 31, v6
	ds_write_b16 v96, v2 offset:574
	v_fmac_f32_e32 v9, v5, v0
	v_cvt_pk_bf16_f32 v0, v9, v1
	v_lshlrev_b64 v[2:3], 15, v[6:7]
	ds_write_b16 v96, v0 offset:846
	v_and_b32_e32 v69, 1, v89
	v_lshl_add_u64 v[2:3], s[16:17], 0, v[2:3]
	v_and_b32_e32 v8, 48, v88
	v_mov_b32_e32 v9, v1
	v_lshlrev_b32_e32 v0, 8, v86
	v_lshl_add_u64 v[14:15], v[2:3], 0, v[8:9]
	v_lshl_or_b32 v18, v69, 14, v0
	v_mov_b32_e32 v19, v1
	v_lshl_add_u64 v[26:27], v[14:15], 0, v[18:19]
	v_or_b32_e32 v20, 0x1000, v18
	v_mov_b32_e32 v21, v1
	v_or_b32_e32 v16, 0x2000, v18
	v_mov_b32_e32 v17, v1
	v_or_b32_e32 v18, 0x3000, v18
	v_lshl_add_u64 v[10:11], v[14:15], 0, v[20:21]
	v_lshl_add_u64 v[28:29], v[14:15], 0, v[16:17]
	v_lshl_add_u64 v[40:41], v[14:15], 0, v[18:19]
	s_waitcnt lgkmcnt(0)
	s_barrier
	s_waitcnt vmcnt(0)
	v_lshlrev_b32_e32 v68, 6, v6
	v_or_b32_e32 v0, v68, v86
	v_mul_lo_u32 v0, v0, s0
	v_add3_u32 v0, 0, v8, v0
	ds_read_b128 v[6:9], v0
	ds_read_b128 v[90:93], v0 offset:13056
	s_waitcnt lgkmcnt(1)
	v_mfma_f32_16x16x32_bf16 v[22:25], v[6:9], v[122:125], 0
	v_lshl_add_u64 v[64:65], v[14:15], 0, 64
	v_lshl_add_u64 v[94:95], v[64:65], 0, v[20:21]
	v_lshl_add_u64 v[98:99], v[64:65], 0, v[16:17]
	v_mfma_f32_16x16x32_bf16 v[32:35], v[6:9], v[126:129], 0
	v_lshl_add_u64 v[64:65], v[64:65], 0, v[18:19]
	s_mov_b64 s[0:1], 0xc0
	v_mfma_f32_16x16x32_bf16 v[36:39], v[6:9], v[130:133], 0
	s_nop 0
	v_mfma_f32_16x16x32_bf16 v[44:47], v[6:9], v[134:137], 0
	ds_read_b128 v[6:9], v0 offset:4352
	v_lshl_add_u64 v[64:65], v[14:15], 0, s[88:89]
	s_waitcnt lgkmcnt(0)
	v_mfma_f32_16x16x32_bf16 v[48:51], v[6:9], v[122:125], 0
	v_mfma_f32_16x16x32_bf16 v[52:55], v[6:9], v[126:129], 0
	v_mfma_f32_16x16x32_bf16 v[56:59], v[6:9], v[130:133], 0
	v_mfma_f32_16x16x32_bf16 v[60:63], v[6:9], v[134:137], 0
	ds_read_b128 v[6:9], v0 offset:8704
	s_waitcnt lgkmcnt(0)
	v_mfma_f32_16x16x32_bf16 v[70:73], v[6:9], v[122:125], 0
	v_mfma_f32_16x16x32_bf16 v[74:77], v[6:9], v[126:129], 0
	v_mfma_f32_16x16x32_bf16 v[78:81], v[6:9], v[130:133], 0
	v_mfma_f32_16x16x32_bf16 v[82:85], v[6:9], v[134:137], 0
	v_mfma_f32_16x16x32_bf16 v[6:9], v[90:93], v[126:129], 0
	v_mfma_f32_16x16x32_bf16 v[10:13], v[90:93], v[130:133], 0
	v_mfma_f32_16x16x32_bf16 v[2:5], v[90:93], v[122:125], 0
	v_mfma_f32_16x16x32_bf16 v[40:43], v[90:93], v[134:137], 0
	ds_read_b128 v[90:93], v0 offset:64
	s_waitcnt lgkmcnt(0)
	v_mfma_f32_16x16x32_bf16 v[22:25], v[90:93], v[150:153], v[22:25]
	v_mfma_f32_16x16x32_bf16 v[32:35], v[90:93], v[138:141], v[32:35]
	v_mfma_f32_16x16x32_bf16 v[36:39], v[90:93], v[142:145], v[36:39]
	v_mfma_f32_16x16x32_bf16 v[44:47], v[90:93], v[146:149], v[44:47]
	ds_read_b128 v[90:93], v0 offset:4416
	s_waitcnt lgkmcnt(0)
	v_mfma_f32_16x16x32_bf16 v[48:51], v[90:93], v[150:153], v[48:51]
	v_mfma_f32_16x16x32_bf16 v[52:55], v[90:93], v[138:141], v[52:55]
	v_mfma_f32_16x16x32_bf16 v[56:59], v[90:93], v[142:145], v[56:59]
	v_mfma_f32_16x16x32_bf16 v[60:63], v[90:93], v[146:149], v[60:63]
	ds_read_b128 v[90:93], v0 offset:8768
	s_waitcnt lgkmcnt(0)
	v_mfma_f32_16x16x32_bf16 v[70:73], v[90:93], v[150:153], v[70:73]
	v_mfma_f32_16x16x32_bf16 v[74:77], v[90:93], v[138:141], v[74:77]
	v_mfma_f32_16x16x32_bf16 v[78:81], v[90:93], v[142:145], v[78:81]
	v_mfma_f32_16x16x32_bf16 v[82:85], v[90:93], v[146:149], v[82:85]
	ds_read_b128 v[90:93], v0 offset:13120
	s_waitcnt lgkmcnt(0)
	v_mfma_f32_16x16x32_bf16 v[2:5], v[90:93], v[150:153], v[2:5]
	v_mfma_f32_16x16x32_bf16 v[6:9], v[90:93], v[138:141], v[6:9]
	v_mfma_f32_16x16x32_bf16 v[10:13], v[90:93], v[142:145], v[10:13]
	v_lshl_add_u64 v[98:99], v[64:65], 0, v[20:21]
	v_mfma_f32_16x16x32_bf16 v[40:43], v[90:93], v[146:149], v[40:43]
	ds_read_b128 v[90:93], v0 offset:128
	v_lshl_add_u64 v[102:103], v[64:65], 0, v[16:17]
	s_waitcnt lgkmcnt(0)
	v_mfma_f32_16x16x32_bf16 v[94:97], v[90:93], v[154:157], v[22:25]
	s_nop 2
	v_mfma_f32_16x16x32_bf16 v[98:101], v[90:93], v[162:165], v[32:35]
	s_nop 2
	v_lshl_add_u64 v[32:33], v[64:65], 0, v[18:19]
	ds_read_b128 v[32:35], v0 offset:4480
	v_mfma_f32_16x16x32_bf16 v[106:109], v[90:93], v[158:161], v[36:39]
	v_mfma_f32_16x16x32_bf16 v[90:93], v[90:93], v[166:169], v[44:47]
	s_nop 2
	ds_read_b128 v[44:47], v0 offset:13184
	s_waitcnt lgkmcnt(1)
	v_mfma_f32_16x16x32_bf16 v[114:117], v[32:35], v[154:157], v[48:51]
	v_mfma_f32_16x16x32_bf16 v[50:53], v[32:35], v[162:165], v[52:55]
	v_mfma_f32_16x16x32_bf16 v[54:57], v[32:35], v[158:161], v[56:59]
	v_mfma_f32_16x16x32_bf16 v[118:121], v[32:35], v[166:169], v[60:63]
	ds_read_b128 v[32:35], v0 offset:8832
	s_waitcnt lgkmcnt(0)
; __device__ __forceinline__ unsigned cvt_pk_bf16(float lo, float hi) { unsigned r; asm volatile("v_cvt_pk_bf16_f32 %0, %1, %2" : "=v"(r) : "v"(lo), "v"(hi)); return r; }
; __device__ __forceinline__ float bf_lo(unsigned w) { return __uint_as_float(w << 16); }
; __device__ __forceinline__ float bf_hi(unsigned w) { return __uint_as_float(w & 0xffff0000u); }
; __device__ __forceinline__ float gelu_tanh(float x) { const float z = 0.7978845608028654f * (x + 0.044715f * x * x * x); return x * sigmoidf_(2.0f * z); }
; __device__ __forceinline__ void gmlp_conv_item(const Params& p, int l, int hs, int chunk, LAS unsigned char* lds) {
;     ...
;           for (int pb = 0; pb < 4; ++pb) bfr[pb] = *(const bf16x8*)(wsb + (size_t)((ph * 4 + pb) * 16 + fr) * 128 + kk * 32 + fq * 8);
; #pragma unroll
;           for (int db = 0; db < 4; ++db)
; #pragma unroll
;               for (int pb = 0; pb < 4; ++pb) acc[db][pb] = __builtin_amdgcn_mfma_f32_16x16x32_bf16(af[db], bfr[pb], acc[db][pb], 0, 0, 0);
;       }
;       const float* bs = p.in[I_GBS] + (size_t)l * 512 + g * 128;
;       u32x2 uw[4][4]; float bias[4];
; #pragma unroll
;       for (int pb = 0; pb < 4; ++pb) { const int pt = (ph * 4 + pb) * 16 + fr; bias[pb] = bs[pt];
;           const bf16_t* up = P + (size_t)(v0 + pt) * PROJ + OFF_GU + g * 64 + fq * 4;
; #pragma unroll
;           for (int db = 0; db < 4; ++db) uw[pb][db] = *(const u32x2*)(up + db * 16); }
; #pragma unroll
;       for (int pb = 0; pb < 4; ++pb) { const int pt = (ph * 4 + pb) * 16 + fr;
;           bf16_t* yp = Y + (size_t)(v0 + pt) * D + 256 + g * 64 + fq * 4;
; #pragma unroll
;           for (int db = 0; db < 4; ++db) { const u32x2 w = uw[pb][db];
;               const float y0 = gelu_tanh(bf_lo(w.x)) * (acc[db][pb][0] + bias[pb]), y1 = gelu_tanh(bf_hi(w.x)) * (acc[db][pb][1] + bias[pb]);
;               const float y2 = gelu_tanh(bf_lo(w.y)) * (acc[db][pb][2] + bias[pb]), y3 = gelu_tanh(bf_hi(w.y)) * (acc[db][pb][3] + bias[pb]);
;               u32x2 ov; ov.x = cvt_pk_bf16(y0, y1); ov.y = cvt_pk_bf16(y2, y3); *(u32x2*)(yp + db * 16) = ov; } } }
	v_mfma_f32_16x16x32_bf16 v[74:77], v[32:35], v[162:165], v[74:77]
	v_mfma_f32_16x16x32_bf16 v[78:81], v[32:35], v[158:161], v[78:81]
	v_mfma_f32_16x16x32_bf16 v[22:25], v[44:47], v[162:165], v[6:9]
	v_mfma_f32_16x16x32_bf16 v[6:9], v[44:47], v[158:161], v[10:13]
	v_mfma_f32_16x16x32_bf16 v[70:73], v[32:35], v[154:157], v[70:73]
	s_nop 0
	v_lshl_add_u64 v[10:11], v[14:15], 0, s[0:1]
	v_lshl_add_u64 v[12:13], v[10:11], 0, v[20:21]
	v_mfma_f32_16x16x32_bf16 v[82:85], v[32:35], v[166:169], v[82:85]
	v_mfma_f32_16x16x32_bf16 v[34:37], v[44:47], v[154:157], v[2:5]
	s_nop 2
	ds_read_b128 v[2:5], v0 offset:192
	s_waitcnt lgkmcnt(0)
	v_mfma_f32_16x16x32_bf16 v[62:65], v[2:5], v[170:173], v[94:97]
	s_nop 2
	v_lshl_add_u64 v[12:13], v[10:11], 0, v[16:17]
	v_lshl_add_u64 v[10:11], v[10:11], 0, v[18:19]
	v_mfma_f32_16x16x32_bf16 v[110:113], v[44:47], v[166:169], v[40:43]
	v_mfma_f32_16x16x32_bf16 v[46:49], v[2:5], v[174:177], v[98:101]
	s_nop 2
	v_mfma_f32_16x16x32_bf16 v[30:33], v[2:5], v[178:181], v[106:109]
	s_nop 2
	v_mfma_f32_16x16x32_bf16 v[14:17], v[2:5], v[182:185], v[90:93]
	ds_read_b128 v[2:5], v0 offset:4544
	s_waitcnt lgkmcnt(0)
	v_mfma_f32_16x16x32_bf16 v[58:61], v[2:5], v[170:173], v[114:117]
	v_mfma_f32_16x16x32_bf16 v[42:45], v[2:5], v[174:177], v[50:53]
	v_mfma_f32_16x16x32_bf16 v[26:29], v[2:5], v[178:181], v[54:57]
	v_mfma_f32_16x16x32_bf16 v[10:13], v[2:5], v[182:185], v[118:121]
	ds_read_b128 v[2:5], v0 offset:8896
	s_waitcnt lgkmcnt(0)
	v_mfma_f32_16x16x32_bf16 v[54:57], v[2:5], v[170:173], v[70:73]
	s_nop 2
	ds_read_b128 v[70:73], v0 offset:13248
	v_lshrrev_b32_e32 v0, 1, v88
	v_and_b32_e32 v0, 24, v0
	v_mfma_f32_16x16x32_bf16 v[38:41], v[2:5], v[174:177], v[74:77]
	s_nop 2
	v_lshl_or_b32 v76, v69, 6, v86
	v_ashrrev_i32_e32 v69, 31, v68
	v_or_b32_e32 v114, s20, v76
	s_waitcnt lgkmcnt(0)
	v_mfma_f32_16x16x32_bf16 v[50:53], v[70:73], v[170:173], v[34:37]
	v_lshlrev_b64 v[74:75], 1, v[68:69]
	v_or_b32_e32 v86, 32, v114
	v_ashrrev_i32_e32 v115, 31, v114
	v_mfma_f32_16x16x32_bf16 v[34:37], v[70:73], v[174:177], v[22:25]
	v_or_b32_e32 v96, 16, v114
	s_nop 1
	v_mad_i64_i32 v[22:23], s[0:1], v114, s97, v[66:67]
	v_lshl_add_u64 v[22:23], v[22:23], 0, v[74:75]
	v_lshl_add_u64 v[68:69], v[22:23], 0, v[0:1]
	global_load_dwordx2 v[116:117], v[68:69], off offset:1536
	v_mfma_f32_16x16x32_bf16 v[22:25], v[70:73], v[178:181], v[6:9]
	s_waitcnt vmcnt(0)
	v_lshlrev_b32_e32 v105, 16, v116
	s_nop 0
	v_and_b32_e32 v6, 0xffffff80, v88
	v_ashrrev_i32_e32 v7, 31, v6
	v_lshl_add_u64 v[6:7], v[6:7], 2, s[18:19]
	v_lshlrev_b32_e32 v8, 2, v76
	v_mov_b32_e32 v9, v1
	v_mfma_f32_16x16x32_bf16 v[18:21], v[2:5], v[178:181], v[78:81]
	v_lshl_add_u64 v[100:101], v[6:7], 0, v[8:9]
	global_load_dword v97, v[100:101], off
	v_or_b32_e32 v76, 48, v114
	v_mfma_f32_16x16x32_bf16 v[2:5], v[2:5], v[182:185], v[82:85]
	s_waitcnt vmcnt(0)
	v_add_f32_e32 v62, v62, v97
	v_mfma_f32_16x16x32_bf16 v[6:9], v[70:73], v[182:185], v[110:113]
	global_load_dwordx2 v[106:107], v[68:69], off offset:1568
	global_load_dwordx2 v[102:103], v[68:69], off offset:1600
	global_load_dwordx2 v[98:99], v[68:69], off offset:1632
	global_load_dword v87, v[100:101], off offset:64
	v_mul_f32_e32 v108, 0x3d372713, v105
	v_and_b32_e32 v109, 0xffff0000, v116
	v_mul_f32_e32 v108, v108, v105
	v_mul_f32_e32 v110, 0x3d372713, v109
	v_fma_f32 v108, v108, v105, v105
	v_mul_f32_e32 v110, v110, v109
	v_mul_f32_e32 v108, 0x3f4c422a, v108
	v_fma_f32 v110, v110, v109, v109
	v_add_f32_e32 v108, v108, v108
	v_mul_f32_e32 v110, 0x3f4c422a, v110
	v_mul_f32_e32 v108, 0xbfb8aa3b, v108
	v_add_f32_e32 v110, v110, v110
	v_exp_f32_e32 v108, v108
	v_mul_f32_e32 v110, 0xbfb8aa3b, v110
	v_exp_f32_e32 v110, v110
	v_add_f32_e32 v63, v63, v97
	v_add_f32_e32 v108, 1.0, v108
	v_rcp_f32_e32 v108, v108
	v_add_f32_e32 v110, 1.0, v110
	v_rcp_f32_e32 v110, v110
	v_mad_i64_i32 v[68:69], s[0:1], v96, s97, v[66:67]
	v_mul_f32_e32 v105, v108, v105
	v_lshlrev_b32_e32 v108, 16, v117
	v_mul_f32_e32 v62, v62, v105
	v_mul_f32_e32 v105, v110, v109
	v_mul_f32_e32 v109, 0x3d372713, v108
	v_and_b32_e32 v110, 0xffff0000, v117
	v_mul_f32_e32 v109, v109, v108
	v_mul_f32_e32 v111, 0x3d372713, v110
	v_fma_f32 v109, v109, v108, v108
	v_mul_f32_e32 v111, v111, v110
	v_mul_f32_e32 v109, 0x3f4c422a, v109
	v_fma_f32 v111, v111, v110, v110
	v_add_f32_e32 v109, v109, v109
	v_mul_f32_e32 v111, 0x3f4c422a, v111
	v_mul_f32_e32 v109, 0xbfb8aa3b, v109
	v_add_f32_e32 v111, v111, v111
	v_exp_f32_e32 v109, v109
	v_mul_f32_e32 v111, 0xbfb8aa3b, v111
	v_exp_f32_e32 v111, v111
	v_mul_f32_e32 v63, v63, v105
	v_add_f32_e32 v109, 1.0, v109
	v_rcp_f32_e32 v109, v109
	v_add_f32_e32 v105, 1.0, v111
	v_lshl_add_u64 v[68:69], v[68:69], 0, v[74:75]
	v_rcp_f32_e32 v105, v105
	v_lshl_add_u64 v[68:69], v[68:69], 0, v[0:1]
	global_load_dwordx2 v[94:95], v[68:69], off offset:1536
	global_load_dwordx2 v[92:93], v[68:69], off offset:1568
	global_load_dwordx2 v[90:91], v[68:69], off offset:1600
	global_load_dwordx2 v[88:89], v[68:69], off offset:1632
	global_load_dword v77, v[100:101], off offset:128
	v_mad_i64_i32 v[68:69], s[0:1], v86, s97, v[66:67]
	v_mad_i64_i32 v[66:67], s[0:1], v76, s97, v[66:67]
	v_lshl_add_u64 v[68:69], v[68:69], 0, v[74:75]
	v_lshl_add_u64 v[66:67], v[66:67], 0, v[74:75]
	v_mul_f32_e32 v108, v109, v108
	v_add_f32_e32 v64, v64, v97
	v_lshl_add_u64 v[68:69], v[68:69], 0, v[0:1]
	v_lshl_add_u64 v[66:67], v[66:67], 0, v[0:1]
	v_mul_f32_e32 v64, v64, v108
	v_mul_f32_e32 v105, v105, v110
	v_add_f32_e32 v65, v65, v97
	global_load_dwordx2 v[84:85], v[68:69], off offset:1536
	global_load_dwordx2 v[82:83], v[68:69], off offset:1568
	global_load_dwordx2 v[80:81], v[68:69], off offset:1600
	global_load_dwordx2 v[78:79], v[68:69], off offset:1632
	global_load_dword v104, v[100:101], off offset:192
	global_load_dwordx2 v[72:73], v[66:67], off offset:1536
	global_load_dwordx2 v[70:71], v[66:67], off offset:1568
	s_nop 0
	global_load_dwordx2 v[68:69], v[66:67], off offset:1600
	s_nop 0
	global_load_dwordx2 v[66:67], v[66:67], off offset:1632
	v_mul_f32_e32 v65, v65, v105
	v_cvt_pk_bf16_f32 v62, v62, v63
	v_cvt_pk_bf16_f32 v63, v64, v65
	v_lshlrev_b64 v[100:101], 11, v[114:115]
	v_lshl_add_u64 v[100:101], s[6:7], 0, v[100:101]
	v_lshl_add_u64 v[100:101], v[100:101], 0, v[74:75]
	v_lshl_add_u64 v[100:101], v[100:101], 0, v[0:1]
	global_store_dwordx2 v[100:101], v[62:63], off offset:512
	v_add_f32_e32 v58, v58, v97
	v_add_f32_e32 v59, v59, v97
	v_add_f32_e32 v60, v60, v97
	v_add_f32_e32 v61, v61, v97
	s_waitcnt vmcnt(18)
; __device__ __forceinline__ unsigned cvt_pk_bf16(float lo, float hi) { unsigned r; asm volatile("v_cvt_pk_bf16_f32 %0, %1, %2" : "=v"(r) : "v"(lo), "v"(hi)); return r; }
; __device__ __forceinline__ float bf_lo(unsigned w) { return __uint_as_float(w << 16); }
; __device__ __forceinline__ float bf_hi(unsigned w) { return __uint_as_float(w & 0xffff0000u); }
; __device__ __forceinline__ float gelu_tanh(float x) { const float z = 0.7978845608028654f * (x + 0.044715f * x * x * x); return x * sigmoidf_(2.0f * z); }
; __device__ __forceinline__ void gmlp_conv_item(const Params& p, int l, int hs, int chunk, LAS unsigned char* lds) {
;     ...
;       for (int pb = 0; pb < 4; ++pb) { const int pt = (ph * 4 + pb) * 16 + fr;
;           bf16_t* yp = Y + (size_t)(v0 + pt) * D + 256 + g * 64 + fq * 4;
; #pragma unroll
;           for (int db = 0; db < 4; ++db) { const u32x2 w = uw[pb][db];
;               const float y0 = gelu_tanh(bf_lo(w.x)) * (acc[db][pb][0] + bias[pb]), y1 = gelu_tanh(bf_hi(w.x)) * (acc[db][pb][1] + bias[pb]);
;               const float y2 = gelu_tanh(bf_lo(w.y)) * (acc[db][pb][2] + bias[pb]), y3 = gelu_tanh(bf_hi(w.y)) * (acc[db][pb][3] + bias[pb]);
;               u32x2 ov; ov.x = cvt_pk_bf16(y0, y1); ov.y = cvt_pk_bf16(y2, y3); *(u32x2*)(yp + db * 16) = ov; } } }
	v_lshlrev_b32_e32 v64, 16, v106
	v_mul_f32_e32 v65, 0x3d372713, v64
	v_mul_f32_e32 v65, v65, v64
	v_fma_f32 v65, v65, v64, v64
	v_and_b32_e32 v105, 0xffff0000, v106
	v_mul_f32_e32 v65, 0x3f4c422a, v65
	v_mul_f32_e32 v106, 0x3d372713, v105
	v_add_f32_e32 v65, v65, v65
	v_mul_f32_e32 v106, v106, v105
	v_mul_f32_e32 v65, 0xbfb8aa3b, v65
	v_fma_f32 v106, v106, v105, v105
	v_exp_f32_e32 v65, v65
	v_mul_f32_e32 v106, 0x3f4c422a, v106
	v_add_f32_e32 v106, v106, v106
	v_mul_f32_e32 v106, 0xbfb8aa3b, v106
	v_exp_f32_e32 v106, v106
	v_add_f32_e32 v65, 1.0, v65
	v_rcp_f32_e32 v65, v65
	v_add_f32_e32 v54, v54, v97
	v_add_f32_e32 v62, 1.0, v106
	v_rcp_f32_e32 v62, v62
	v_mul_f32_e32 v63, v65, v64
	v_mul_f32_e32 v58, v58, v63
	v_lshlrev_b32_e32 v63, 16, v107
	v_mul_f32_e32 v64, 0x3d372713, v63
	v_and_b32_e32 v65, 0xffff0000, v107
	v_mul_f32_e32 v62, v62, v105
	v_mul_f32_e32 v64, v64, v63
	v_mul_f32_e32 v105, 0x3d372713, v65
	v_fma_f32 v64, v64, v63, v63
	v_mul_f32_e32 v105, v105, v65
	v_mul_f32_e32 v64, 0x3f4c422a, v64
	v_fma_f32 v105, v105, v65, v65
	v_add_f32_e32 v64, v64, v64
	v_mul_f32_e32 v105, 0x3f4c422a, v105
	v_mul_f32_e32 v64, 0xbfb8aa3b, v64
	v_add_f32_e32 v105, v105, v105
	v_exp_f32_e32 v64, v64
	v_mul_f32_e32 v105, 0xbfb8aa3b, v105
	v_exp_f32_e32 v105, v105
	v_mul_f32_e32 v59, v59, v62
	v_add_f32_e32 v64, 1.0, v64
	v_rcp_f32_e32 v64, v64
	v_add_f32_e32 v62, 1.0, v105
	v_rcp_f32_e32 v62, v62
	v_cvt_pk_bf16_f32 v58, v58, v59
	v_mul_f32_e32 v63, v64, v63
	v_mul_f32_e32 v60, v60, v63
	v_mul_f32_e32 v62, v62, v65
	v_mul_f32_e32 v61, v61, v62
	v_cvt_pk_bf16_f32 v59, v60, v61
	s_waitcnt vmcnt(17)
	v_lshlrev_b32_e32 v60, 16, v102
	v_mul_f32_e32 v61, 0x3d372713, v60
	v_mul_f32_e32 v61, v61, v60
	v_fma_f32 v61, v61, v60, v60
	v_and_b32_e32 v62, 0xffff0000, v102
	v_mul_f32_e32 v61, 0x3f4c422a, v61
	v_mul_f32_e32 v63, 0x3d372713, v62
	v_add_f32_e32 v61, v61, v61
	v_mul_f32_e32 v63, v63, v62
	v_mul_f32_e32 v61, 0xbfb8aa3b, v61
	v_fma_f32 v63, v63, v62, v62
	v_exp_f32_e32 v61, v61
	v_mul_f32_e32 v63, 0x3f4c422a, v63
	v_add_f32_e32 v63, v63, v63
	v_mul_f32_e32 v63, 0xbfb8aa3b, v63
	v_exp_f32_e32 v63, v63
	v_add_f32_e32 v61, 1.0, v61
	v_rcp_f32_e32 v61, v61
	global_store_dwordx2 v[100:101], v[58:59], off offset:544
	v_add_f32_e32 v58, 1.0, v63
	v_rcp_f32_e32 v58, v58
	v_mul_f32_e32 v59, v61, v60
	v_mul_f32_e32 v54, v54, v59
	v_lshlrev_b32_e32 v59, 16, v103
	v_mul_f32_e32 v60, 0x3d372713, v59
	v_and_b32_e32 v61, 0xffff0000, v103
	v_mul_f32_e32 v58, v58, v62
	v_mul_f32_e32 v60, v60, v59
	v_mul_f32_e32 v62, 0x3d372713, v61
	v_fma_f32 v60, v60, v59, v59
	v_mul_f32_e32 v62, v62, v61
	v_mul_f32_e32 v60, 0x3f4c422a, v60
	v_fma_f32 v62, v62, v61, v61
	v_add_f32_e32 v60, v60, v60
	v_mul_f32_e32 v62, 0x3f4c422a, v62
	v_mul_f32_e32 v60, 0xbfb8aa3b, v60
	v_add_f32_e32 v62, v62, v62
	v_exp_f32_e32 v60, v60
	v_mul_f32_e32 v62, 0xbfb8aa3b, v62
	v_exp_f32_e32 v62, v62
	v_add_f32_e32 v55, v55, v97
	v_add_f32_e32 v60, 1.0, v60
	v_rcp_f32_e32 v60, v60
	v_mul_f32_e32 v55, v55, v58
	v_add_f32_e32 v58, 1.0, v62
	v_rcp_f32_e32 v58, v58
	v_mul_f32_e32 v59, v60, v59
	v_add_f32_e32 v56, v56, v97
	v_mul_f32_e32 v56, v56, v59
	v_mul_f32_e32 v58, v58, v61
	v_add_f32_e32 v57, v57, v97
	v_mul_f32_e32 v57, v57, v58
	v_cvt_pk_bf16_f32 v54, v54, v55
	v_cvt_pk_bf16_f32 v55, v56, v57
	s_waitcnt vmcnt(17)
	v_lshlrev_b32_e32 v56, 16, v98
	v_mul_f32_e32 v57, 0x3d372713, v56
	v_mul_f32_e32 v57, v57, v56
	v_fma_f32 v57, v57, v56, v56
	v_and_b32_e32 v58, 0xffff0000, v98
	v_mul_f32_e32 v57, 0x3f4c422a, v57
	v_mul_f32_e32 v59, 0x3d372713, v58
	v_add_f32_e32 v57, v57, v57
	v_mul_f32_e32 v59, v59, v58
	v_mul_f32_e32 v57, 0xbfb8aa3b, v57
	v_fma_f32 v59, v59, v58, v58
	v_exp_f32_e32 v57, v57
	v_mul_f32_e32 v59, 0x3f4c422a, v59
	v_add_f32_e32 v59, v59, v59
	v_mul_f32_e32 v59, 0xbfb8aa3b, v59
	v_exp_f32_e32 v59, v59
	v_add_f32_e32 v57, 1.0, v57
	v_rcp_f32_e32 v57, v57
	global_store_dwordx2 v[100:101], v[54:55], off offset:576
	v_add_f32_e32 v54, 1.0, v59
	v_rcp_f32_e32 v54, v54
	v_mul_f32_e32 v55, v57, v56
	v_add_f32_e32 v50, v50, v97
	v_mul_f32_e32 v50, v50, v55
	v_lshlrev_b32_e32 v55, 16, v99
	v_mul_f32_e32 v56, 0x3d372713, v55
	v_and_b32_e32 v57, 0xffff0000, v99
	v_mul_f32_e32 v54, v54, v58
	v_mul_f32_e32 v56, v56, v55
	v_mul_f32_e32 v58, 0x3d372713, v57
	v_fma_f32 v56, v56, v55, v55
	v_mul_f32_e32 v58, v58, v57
	v_mul_f32_e32 v56, 0x3f4c422a, v56
	v_fma_f32 v58, v58, v57, v57
	v_add_f32_e32 v56, v56, v56
	v_mul_f32_e32 v58, 0x3f4c422a, v58
	v_mul_f32_e32 v56, 0xbfb8aa3b, v56
	v_add_f32_e32 v58, v58, v58
	v_exp_f32_e32 v56, v56
	v_mul_f32_e32 v58, 0xbfb8aa3b, v58
	v_exp_f32_e32 v58, v58
	v_add_f32_e32 v51, v51, v97
	v_add_f32_e32 v56, 1.0, v56
	v_rcp_f32_e32 v56, v56
	v_mul_f32_e32 v51, v51, v54
	v_add_f32_e32 v54, 1.0, v58
	v_rcp_f32_e32 v54, v54
	v_mul_f32_e32 v55, v56, v55
	v_add_f32_e32 v52, v52, v97
	v_mul_f32_e32 v52, v52, v55
	v_mul_f32_e32 v54, v54, v57
	v_add_f32_e32 v53, v53, v97
	v_mul_f32_e32 v53, v53, v54
	v_cvt_pk_bf16_f32 v50, v50, v51
	v_cvt_pk_bf16_f32 v51, v52, v53
	s_waitcnt vmcnt(16)
; __device__ __forceinline__ unsigned cvt_pk_bf16(float lo, float hi) { unsigned r; asm volatile("v_cvt_pk_bf16_f32 %0, %1, %2" : "=v"(r) : "v"(lo), "v"(hi)); return r; }
; __device__ __forceinline__ float bf_lo(unsigned w) { return __uint_as_float(w << 16); }
; __device__ __forceinline__ float bf_hi(unsigned w) { return __uint_as_float(w & 0xffff0000u); }
; __device__ __forceinline__ float gelu_tanh(float x) { const float z = 0.7978845608028654f * (x + 0.044715f * x * x * x); return x * sigmoidf_(2.0f * z); }
; __device__ __forceinline__ void gmlp_conv_item(const Params& p, int l, int hs, int chunk, LAS unsigned char* lds) {
;     ...
;       for (int pb = 0; pb < 4; ++pb) { const int pt = (ph * 4 + pb) * 16 + fr;
;           bf16_t* yp = Y + (size_t)(v0 + pt) * D + 256 + g * 64 + fq * 4;
; #pragma unroll
;           for (int db = 0; db < 4; ++db) { const u32x2 w = uw[pb][db];
;               const float y0 = gelu_tanh(bf_lo(w.x)) * (acc[db][pb][0] + bias[pb]), y1 = gelu_tanh(bf_hi(w.x)) * (acc[db][pb][1] + bias[pb]);
;               const float y2 = gelu_tanh(bf_lo(w.y)) * (acc[db][pb][2] + bias[pb]), y3 = gelu_tanh(bf_hi(w.y)) * (acc[db][pb][3] + bias[pb]);
;               u32x2 ov; ov.x = cvt_pk_bf16(y0, y1); ov.y = cvt_pk_bf16(y2, y3); *(u32x2*)(yp + db * 16) = ov; } } }
	v_lshlrev_b32_e32 v52, 16, v94
	v_mul_f32_e32 v53, 0x3d372713, v52
	v_and_b32_e32 v54, 0xffff0000, v94
	v_mul_f32_e32 v53, v53, v52
	v_mul_f32_e32 v55, 0x3d372713, v54
	v_fma_f32 v53, v53, v52, v52
	v_mul_f32_e32 v55, v55, v54
	v_mul_f32_e32 v53, 0x3f4c422a, v53
	v_fma_f32 v55, v55, v54, v54
	v_add_f32_e32 v53, v53, v53
	v_mul_f32_e32 v55, 0x3f4c422a, v55
	v_mul_f32_e32 v53, 0xbfb8aa3b, v53
	v_add_f32_e32 v55, v55, v55
	v_exp_f32_e32 v53, v53
	v_mul_f32_e32 v55, 0xbfb8aa3b, v55
	v_exp_f32_e32 v55, v55
	v_add_f32_e32 v46, v46, v87
	v_add_f32_e32 v53, 1.0, v53
	v_rcp_f32_e32 v53, v53
	v_add_f32_e32 v55, 1.0, v55
	v_rcp_f32_e32 v55, v55
	v_add_f32_e32 v47, v47, v87
	v_mul_f32_e32 v52, v53, v52
	v_lshlrev_b32_e32 v53, 16, v95
	v_mul_f32_e32 v46, v46, v52
	v_mul_f32_e32 v52, v55, v54
	v_mul_f32_e32 v54, 0x3d372713, v53
	v_and_b32_e32 v55, 0xffff0000, v95
	v_mul_f32_e32 v54, v54, v53
	v_mul_f32_e32 v56, 0x3d372713, v55
	v_fma_f32 v54, v54, v53, v53
	v_mul_f32_e32 v56, v56, v55
	v_mul_f32_e32 v54, 0x3f4c422a, v54
	v_fma_f32 v56, v56, v55, v55
	v_add_f32_e32 v54, v54, v54
	v_mul_f32_e32 v56, 0x3f4c422a, v56
	v_mul_f32_e32 v54, 0xbfb8aa3b, v54
	v_add_f32_e32 v56, v56, v56
	v_exp_f32_e32 v54, v54
	v_mul_f32_e32 v56, 0xbfb8aa3b, v56
	v_exp_f32_e32 v56, v56
	v_mul_f32_e32 v47, v47, v52
	v_add_f32_e32 v54, 1.0, v54
	v_rcp_f32_e32 v54, v54
	v_add_f32_e32 v52, 1.0, v56
	v_rcp_f32_e32 v52, v52
	v_add_f32_e32 v48, v48, v87
	v_mul_f32_e32 v53, v54, v53
	v_mul_f32_e32 v48, v48, v53
	v_mul_f32_e32 v52, v52, v55
	v_add_f32_e32 v49, v49, v87
	global_store_dwordx2 v[100:101], v[50:51], off offset:608
	v_mul_f32_e32 v49, v49, v52
	v_cvt_pk_bf16_f32 v46, v46, v47
	v_cvt_pk_bf16_f32 v47, v48, v49
	s_waitcnt vmcnt(16)
	v_lshlrev_b32_e32 v48, 16, v92
	v_mul_f32_e32 v49, 0x3d372713, v48
	v_mul_f32_e32 v49, v49, v48
	v_fma_f32 v49, v49, v48, v48
	v_and_b32_e32 v52, 0xffff0000, v92
	v_mul_f32_e32 v49, 0x3f4c422a, v49
	v_mul_f32_e32 v53, 0x3d372713, v52
	v_add_f32_e32 v49, v49, v49
	v_mul_f32_e32 v53, v53, v52
	v_mul_f32_e32 v49, 0xbfb8aa3b, v49
	v_fma_f32 v53, v53, v52, v52
	v_exp_f32_e32 v49, v49
	v_mul_f32_e32 v53, 0x3f4c422a, v53
	v_add_f32_e32 v53, v53, v53
	v_ashrrev_i32_e32 v97, 31, v96
	v_mul_f32_e32 v53, 0xbfb8aa3b, v53
	v_lshlrev_b64 v[50:51], 11, v[96:97]
	v_exp_f32_e32 v53, v53
	v_lshl_add_u64 v[50:51], s[6:7], 0, v[50:51]
	v_add_f32_e32 v49, 1.0, v49
	v_lshl_add_u64 v[50:51], v[50:51], 0, v[74:75]
	v_rcp_f32_e32 v49, v49
	v_lshl_add_u64 v[50:51], v[50:51], 0, v[0:1]
	global_store_dwordx2 v[50:51], v[46:47], off offset:512
	v_add_f32_e32 v46, 1.0, v53
	v_rcp_f32_e32 v46, v46
	v_mul_f32_e32 v47, v49, v48
	v_add_f32_e32 v42, v42, v87
	v_mul_f32_e32 v42, v42, v47
	v_lshlrev_b32_e32 v47, 16, v93
	v_mul_f32_e32 v48, 0x3d372713, v47
	v_and_b32_e32 v49, 0xffff0000, v93
	v_mul_f32_e32 v46, v46, v52
	v_mul_f32_e32 v48, v48, v47
	v_mul_f32_e32 v52, 0x3d372713, v49
	v_fma_f32 v48, v48, v47, v47
	v_mul_f32_e32 v52, v52, v49
	v_mul_f32_e32 v48, 0x3f4c422a, v48
	v_fma_f32 v52, v52, v49, v49
	v_add_f32_e32 v48, v48, v48
	v_mul_f32_e32 v52, 0x3f4c422a, v52
	v_mul_f32_e32 v48, 0xbfb8aa3b, v48
	v_add_f32_e32 v52, v52, v52
	v_exp_f32_e32 v48, v48
	v_mul_f32_e32 v52, 0xbfb8aa3b, v52
	v_exp_f32_e32 v52, v52
	v_add_f32_e32 v43, v43, v87
	v_add_f32_e32 v48, 1.0, v48
	v_rcp_f32_e32 v48, v48
	v_mul_f32_e32 v43, v43, v46
	v_add_f32_e32 v46, 1.0, v52
	v_rcp_f32_e32 v46, v46
	v_mul_f32_e32 v47, v48, v47
	v_add_f32_e32 v44, v44, v87
	v_mul_f32_e32 v44, v44, v47
	v_mul_f32_e32 v46, v46, v49
	v_add_f32_e32 v45, v45, v87
	v_mul_f32_e32 v45, v45, v46
	v_cvt_pk_bf16_f32 v42, v42, v43
	v_cvt_pk_bf16_f32 v43, v44, v45
	s_waitcnt vmcnt(16)
	v_lshlrev_b32_e32 v44, 16, v90
	v_mul_f32_e32 v45, 0x3d372713, v44
	v_mul_f32_e32 v45, v45, v44
	v_fma_f32 v45, v45, v44, v44
	v_and_b32_e32 v46, 0xffff0000, v90
	v_mul_f32_e32 v45, 0x3f4c422a, v45
	v_mul_f32_e32 v47, 0x3d372713, v46
	v_add_f32_e32 v45, v45, v45
	v_mul_f32_e32 v47, v47, v46
	v_mul_f32_e32 v45, 0xbfb8aa3b, v45
	v_fma_f32 v47, v47, v46, v46
	v_exp_f32_e32 v45, v45
	v_mul_f32_e32 v47, 0x3f4c422a, v47
	v_add_f32_e32 v47, v47, v47
	v_mul_f32_e32 v47, 0xbfb8aa3b, v47
	v_exp_f32_e32 v47, v47
	v_add_f32_e32 v45, 1.0, v45
	v_rcp_f32_e32 v45, v45
	global_store_dwordx2 v[50:51], v[42:43], off offset:544
	v_add_f32_e32 v42, 1.0, v47
	v_rcp_f32_e32 v42, v42
	v_mul_f32_e32 v43, v45, v44
	v_add_f32_e32 v38, v38, v87
	v_mul_f32_e32 v38, v38, v43
	v_lshlrev_b32_e32 v43, 16, v91
	v_mul_f32_e32 v44, 0x3d372713, v43
	v_and_b32_e32 v45, 0xffff0000, v91
	v_mul_f32_e32 v42, v42, v46
	v_mul_f32_e32 v44, v44, v43
	v_mul_f32_e32 v46, 0x3d372713, v45
	v_fma_f32 v44, v44, v43, v43
	v_mul_f32_e32 v46, v46, v45
	v_mul_f32_e32 v44, 0x3f4c422a, v44
	v_fma_f32 v46, v46, v45, v45
	v_add_f32_e32 v44, v44, v44
	v_mul_f32_e32 v46, 0x3f4c422a, v46
	v_mul_f32_e32 v44, 0xbfb8aa3b, v44
	v_add_f32_e32 v46, v46, v46
	v_exp_f32_e32 v44, v44
	v_mul_f32_e32 v46, 0xbfb8aa3b, v46
	v_exp_f32_e32 v46, v46
	v_add_f32_e32 v39, v39, v87
	v_add_f32_e32 v44, 1.0, v44
	v_rcp_f32_e32 v44, v44
	v_mul_f32_e32 v39, v39, v42
	v_add_f32_e32 v42, 1.0, v46
	v_rcp_f32_e32 v42, v42
	v_mul_f32_e32 v43, v44, v43
	v_add_f32_e32 v40, v40, v87
	v_mul_f32_e32 v40, v40, v43
	v_mul_f32_e32 v42, v42, v45
	v_add_f32_e32 v41, v41, v87
	v_mul_f32_e32 v41, v41, v42
	v_cvt_pk_bf16_f32 v38, v38, v39
	v_cvt_pk_bf16_f32 v39, v40, v41
	s_waitcnt vmcnt(16)
; __device__ __forceinline__ unsigned cvt_pk_bf16(float lo, float hi) { unsigned r; asm volatile("v_cvt_pk_bf16_f32 %0, %1, %2" : "=v"(r) : "v"(lo), "v"(hi)); return r; }
; __device__ __forceinline__ float bf_lo(unsigned w) { return __uint_as_float(w << 16); }
; __device__ __forceinline__ float bf_hi(unsigned w) { return __uint_as_float(w & 0xffff0000u); }
; __device__ __forceinline__ float gelu_tanh(float x) { const float z = 0.7978845608028654f * (x + 0.044715f * x * x * x); return x * sigmoidf_(2.0f * z); }
; __device__ __forceinline__ void gmlp_conv_item(const Params& p, int l, int hs, int chunk, LAS unsigned char* lds) {
;     ...
;       for (int pb = 0; pb < 4; ++pb) { const int pt = (ph * 4 + pb) * 16 + fr;
;           bf16_t* yp = Y + (size_t)(v0 + pt) * D + 256 + g * 64 + fq * 4;
; #pragma unroll
;           for (int db = 0; db < 4; ++db) { const u32x2 w = uw[pb][db];
;               const float y0 = gelu_tanh(bf_lo(w.x)) * (acc[db][pb][0] + bias[pb]), y1 = gelu_tanh(bf_hi(w.x)) * (acc[db][pb][1] + bias[pb]);
;               const float y2 = gelu_tanh(bf_lo(w.y)) * (acc[db][pb][2] + bias[pb]), y3 = gelu_tanh(bf_hi(w.y)) * (acc[db][pb][3] + bias[pb]);
;               u32x2 ov; ov.x = cvt_pk_bf16(y0, y1); ov.y = cvt_pk_bf16(y2, y3); *(u32x2*)(yp + db * 16) = ov; } } }
	v_lshlrev_b32_e32 v40, 16, v88
	v_mul_f32_e32 v41, 0x3d372713, v40
	v_mul_f32_e32 v41, v41, v40
	v_fma_f32 v41, v41, v40, v40
	v_and_b32_e32 v42, 0xffff0000, v88
	v_mul_f32_e32 v41, 0x3f4c422a, v41
	v_mul_f32_e32 v43, 0x3d372713, v42
	v_add_f32_e32 v41, v41, v41
	v_mul_f32_e32 v43, v43, v42
	v_mul_f32_e32 v41, 0xbfb8aa3b, v41
	v_fma_f32 v43, v43, v42, v42
	v_exp_f32_e32 v41, v41
	v_mul_f32_e32 v43, 0x3f4c422a, v43
	v_add_f32_e32 v43, v43, v43
	v_mul_f32_e32 v43, 0xbfb8aa3b, v43
	v_exp_f32_e32 v43, v43
	v_add_f32_e32 v41, 1.0, v41
	v_rcp_f32_e32 v41, v41
	global_store_dwordx2 v[50:51], v[38:39], off offset:576
	v_add_f32_e32 v38, 1.0, v43
	v_rcp_f32_e32 v38, v38
	v_mul_f32_e32 v39, v41, v40
	v_add_f32_e32 v34, v34, v87
	v_mul_f32_e32 v34, v34, v39
	v_lshlrev_b32_e32 v39, 16, v89
	v_mul_f32_e32 v40, 0x3d372713, v39
	v_and_b32_e32 v41, 0xffff0000, v89
	v_mul_f32_e32 v38, v38, v42
	v_mul_f32_e32 v40, v40, v39
	v_mul_f32_e32 v42, 0x3d372713, v41
	v_fma_f32 v40, v40, v39, v39
	v_mul_f32_e32 v42, v42, v41
	v_mul_f32_e32 v40, 0x3f4c422a, v40
	v_fma_f32 v42, v42, v41, v41
	v_add_f32_e32 v40, v40, v40
	v_mul_f32_e32 v42, 0x3f4c422a, v42
	v_mul_f32_e32 v40, 0xbfb8aa3b, v40
	v_add_f32_e32 v42, v42, v42
	v_exp_f32_e32 v40, v40
	v_mul_f32_e32 v42, 0xbfb8aa3b, v42
	v_exp_f32_e32 v42, v42
	v_add_f32_e32 v35, v35, v87
	v_add_f32_e32 v40, 1.0, v40
	v_rcp_f32_e32 v40, v40
	v_mul_f32_e32 v35, v35, v38
	v_add_f32_e32 v38, 1.0, v42
	v_rcp_f32_e32 v38, v38
	v_mul_f32_e32 v39, v40, v39
	v_add_f32_e32 v36, v36, v87
	v_mul_f32_e32 v36, v36, v39
	v_mul_f32_e32 v38, v38, v41
	v_add_f32_e32 v37, v37, v87
	v_mul_f32_e32 v37, v37, v38
	v_cvt_pk_bf16_f32 v34, v34, v35
	v_cvt_pk_bf16_f32 v35, v36, v37
	s_waitcnt vmcnt(15)
	v_lshlrev_b32_e32 v36, 16, v84
	v_mul_f32_e32 v37, 0x3d372713, v36
	v_and_b32_e32 v38, 0xffff0000, v84
	v_mul_f32_e32 v37, v37, v36
	v_mul_f32_e32 v39, 0x3d372713, v38
	v_fma_f32 v37, v37, v36, v36
	v_mul_f32_e32 v39, v39, v38
	v_mul_f32_e32 v37, 0x3f4c422a, v37
	v_fma_f32 v39, v39, v38, v38
	v_add_f32_e32 v37, v37, v37
	v_mul_f32_e32 v39, 0x3f4c422a, v39
	v_mul_f32_e32 v37, 0xbfb8aa3b, v37
	v_add_f32_e32 v39, v39, v39
	v_exp_f32_e32 v37, v37
	v_mul_f32_e32 v39, 0xbfb8aa3b, v39
	v_exp_f32_e32 v39, v39
	v_add_f32_e32 v30, v30, v77
	v_add_f32_e32 v37, 1.0, v37
	v_rcp_f32_e32 v37, v37
	v_add_f32_e32 v39, 1.0, v39
	v_rcp_f32_e32 v39, v39
	v_add_f32_e32 v31, v31, v77
	v_mul_f32_e32 v36, v37, v36
	v_lshlrev_b32_e32 v37, 16, v85
	v_mul_f32_e32 v30, v30, v36
	v_mul_f32_e32 v36, v39, v38
	v_mul_f32_e32 v38, 0x3d372713, v37
	v_and_b32_e32 v39, 0xffff0000, v85
	v_mul_f32_e32 v38, v38, v37
	v_mul_f32_e32 v40, 0x3d372713, v39
	v_fma_f32 v38, v38, v37, v37
	v_mul_f32_e32 v40, v40, v39
	v_mul_f32_e32 v38, 0x3f4c422a, v38
	v_fma_f32 v40, v40, v39, v39
	v_add_f32_e32 v38, v38, v38
	v_mul_f32_e32 v40, 0x3f4c422a, v40
	v_mul_f32_e32 v38, 0xbfb8aa3b, v38
	v_add_f32_e32 v40, v40, v40
	v_exp_f32_e32 v38, v38
	v_mul_f32_e32 v40, 0xbfb8aa3b, v40
	v_exp_f32_e32 v40, v40
	v_mul_f32_e32 v31, v31, v36
	v_add_f32_e32 v38, 1.0, v38
	v_rcp_f32_e32 v38, v38
	v_add_f32_e32 v36, 1.0, v40
	v_rcp_f32_e32 v36, v36
	v_add_f32_e32 v32, v32, v77
	v_mul_f32_e32 v37, v38, v37
	v_mul_f32_e32 v32, v32, v37
	v_mul_f32_e32 v36, v36, v39
	v_add_f32_e32 v33, v33, v77
	global_store_dwordx2 v[50:51], v[34:35], off offset:608
	v_mul_f32_e32 v33, v33, v36
	v_cvt_pk_bf16_f32 v30, v30, v31
	v_cvt_pk_bf16_f32 v31, v32, v33
	s_waitcnt vmcnt(15)
	v_lshlrev_b32_e32 v32, 16, v82
	v_mul_f32_e32 v33, 0x3d372713, v32
	v_mul_f32_e32 v33, v33, v32
	v_fma_f32 v33, v33, v32, v32
	v_and_b32_e32 v36, 0xffff0000, v82
	v_mul_f32_e32 v33, 0x3f4c422a, v33
	v_mul_f32_e32 v37, 0x3d372713, v36
	v_add_f32_e32 v33, v33, v33
	v_mul_f32_e32 v37, v37, v36
	v_mul_f32_e32 v33, 0xbfb8aa3b, v33
	v_fma_f32 v37, v37, v36, v36
	v_exp_f32_e32 v33, v33
	v_mul_f32_e32 v37, 0x3f4c422a, v37
	v_add_f32_e32 v37, v37, v37
	v_ashrrev_i32_e32 v87, 31, v86
	v_mul_f32_e32 v37, 0xbfb8aa3b, v37
	v_lshlrev_b64 v[34:35], 11, v[86:87]
	v_exp_f32_e32 v37, v37
	v_lshl_add_u64 v[34:35], s[6:7], 0, v[34:35]
	v_add_f32_e32 v33, 1.0, v33
	v_lshl_add_u64 v[34:35], v[34:35], 0, v[74:75]
	v_rcp_f32_e32 v33, v33
	v_lshl_add_u64 v[34:35], v[34:35], 0, v[0:1]
	global_store_dwordx2 v[34:35], v[30:31], off offset:512
	v_add_f32_e32 v30, 1.0, v37
	v_rcp_f32_e32 v30, v30
	v_mul_f32_e32 v31, v33, v32
	v_add_f32_e32 v26, v26, v77
	v_mul_f32_e32 v26, v26, v31
	v_lshlrev_b32_e32 v31, 16, v83
	v_mul_f32_e32 v32, 0x3d372713, v31
	v_and_b32_e32 v33, 0xffff0000, v83
	v_mul_f32_e32 v30, v30, v36
	v_mul_f32_e32 v32, v32, v31
	v_mul_f32_e32 v36, 0x3d372713, v33
	v_fma_f32 v32, v32, v31, v31
	v_mul_f32_e32 v36, v36, v33
	v_mul_f32_e32 v32, 0x3f4c422a, v32
	v_fma_f32 v36, v36, v33, v33
	v_add_f32_e32 v32, v32, v32
	v_mul_f32_e32 v36, 0x3f4c422a, v36
	v_mul_f32_e32 v32, 0xbfb8aa3b, v32
	v_add_f32_e32 v36, v36, v36
	v_exp_f32_e32 v32, v32
	v_mul_f32_e32 v36, 0xbfb8aa3b, v36
	v_exp_f32_e32 v36, v36
	v_add_f32_e32 v27, v27, v77
	v_add_f32_e32 v32, 1.0, v32
	v_rcp_f32_e32 v32, v32
	v_mul_f32_e32 v27, v27, v30
	v_add_f32_e32 v30, 1.0, v36
	v_rcp_f32_e32 v30, v30
	v_mul_f32_e32 v31, v32, v31
	v_add_f32_e32 v28, v28, v77
	v_mul_f32_e32 v28, v28, v31
	v_mul_f32_e32 v30, v30, v33
	v_add_f32_e32 v29, v29, v77
	v_mul_f32_e32 v29, v29, v30
	v_cvt_pk_bf16_f32 v26, v26, v27
	v_cvt_pk_bf16_f32 v27, v28, v29
	s_waitcnt vmcnt(15)
; __device__ __forceinline__ unsigned cvt_pk_bf16(float lo, float hi) { unsigned r; asm volatile("v_cvt_pk_bf16_f32 %0, %1, %2" : "=v"(r) : "v"(lo), "v"(hi)); return r; }
; __device__ __forceinline__ float bf_lo(unsigned w) { return __uint_as_float(w << 16); }
; __device__ __forceinline__ float bf_hi(unsigned w) { return __uint_as_float(w & 0xffff0000u); }
; __device__ __forceinline__ float gelu_tanh(float x) { const float z = 0.7978845608028654f * (x + 0.044715f * x * x * x); return x * sigmoidf_(2.0f * z); }
; __device__ __forceinline__ void gmlp_conv_item(const Params& p, int l, int hs, int chunk, LAS unsigned char* lds) {
;     ...
;       for (int pb = 0; pb < 4; ++pb) { const int pt = (ph * 4 + pb) * 16 + fr;
;           bf16_t* yp = Y + (size_t)(v0 + pt) * D + 256 + g * 64 + fq * 4;
; #pragma unroll
;           for (int db = 0; db < 4; ++db) { const u32x2 w = uw[pb][db];
;               const float y0 = gelu_tanh(bf_lo(w.x)) * (acc[db][pb][0] + bias[pb]), y1 = gelu_tanh(bf_hi(w.x)) * (acc[db][pb][1] + bias[pb]);
;               const float y2 = gelu_tanh(bf_lo(w.y)) * (acc[db][pb][2] + bias[pb]), y3 = gelu_tanh(bf_hi(w.y)) * (acc[db][pb][3] + bias[pb]);
;               u32x2 ov; ov.x = cvt_pk_bf16(y0, y1); ov.y = cvt_pk_bf16(y2, y3); *(u32x2*)(yp + db * 16) = ov; } } }
	v_lshlrev_b32_e32 v28, 16, v80
	v_mul_f32_e32 v29, 0x3d372713, v28
	v_mul_f32_e32 v29, v29, v28
	v_fma_f32 v29, v29, v28, v28
	v_and_b32_e32 v30, 0xffff0000, v80
	v_mul_f32_e32 v29, 0x3f4c422a, v29
	v_mul_f32_e32 v31, 0x3d372713, v30
	v_add_f32_e32 v29, v29, v29
	v_mul_f32_e32 v31, v31, v30
	v_mul_f32_e32 v29, 0xbfb8aa3b, v29
	v_fma_f32 v31, v31, v30, v30
	v_exp_f32_e32 v29, v29
	v_mul_f32_e32 v31, 0x3f4c422a, v31
	v_add_f32_e32 v31, v31, v31
	v_mul_f32_e32 v31, 0xbfb8aa3b, v31
	v_exp_f32_e32 v31, v31
	v_add_f32_e32 v29, 1.0, v29
	v_rcp_f32_e32 v29, v29
	global_store_dwordx2 v[34:35], v[26:27], off offset:544
	v_add_f32_e32 v26, 1.0, v31
	v_rcp_f32_e32 v26, v26
	v_mul_f32_e32 v27, v29, v28
	v_add_f32_e32 v18, v18, v77
	v_mul_f32_e32 v18, v18, v27
	v_lshlrev_b32_e32 v27, 16, v81
	v_mul_f32_e32 v28, 0x3d372713, v27
	v_and_b32_e32 v29, 0xffff0000, v81
	v_mul_f32_e32 v26, v26, v30
	v_mul_f32_e32 v28, v28, v27
	v_mul_f32_e32 v30, 0x3d372713, v29
	v_fma_f32 v28, v28, v27, v27
	v_mul_f32_e32 v30, v30, v29
	v_mul_f32_e32 v28, 0x3f4c422a, v28
	v_fma_f32 v30, v30, v29, v29
	v_add_f32_e32 v28, v28, v28
	v_mul_f32_e32 v30, 0x3f4c422a, v30
	v_mul_f32_e32 v28, 0xbfb8aa3b, v28
	v_add_f32_e32 v30, v30, v30
	v_exp_f32_e32 v28, v28
	v_mul_f32_e32 v30, 0xbfb8aa3b, v30
	v_exp_f32_e32 v30, v30
	v_add_f32_e32 v19, v19, v77
	v_add_f32_e32 v28, 1.0, v28
	v_rcp_f32_e32 v28, v28
	v_mul_f32_e32 v19, v19, v26
	v_add_f32_e32 v26, 1.0, v30
	v_rcp_f32_e32 v26, v26
	v_mul_f32_e32 v27, v28, v27
	v_add_f32_e32 v20, v20, v77
	v_mul_f32_e32 v20, v20, v27
	v_mul_f32_e32 v26, v26, v29
	v_add_f32_e32 v21, v21, v77
	v_mul_f32_e32 v21, v21, v26
	v_cvt_pk_bf16_f32 v18, v18, v19
	v_cvt_pk_bf16_f32 v19, v20, v21
	s_waitcnt vmcnt(15)
	v_lshlrev_b32_e32 v20, 16, v78
	v_mul_f32_e32 v21, 0x3d372713, v20
	v_mul_f32_e32 v21, v21, v20
	v_and_b32_e32 v26, 0xffff0000, v78
	v_fma_f32 v21, v21, v20, v20
	v_mul_f32_e32 v27, 0x3d372713, v26
	v_mul_f32_e32 v21, 0x3f4c422a, v21
	v_mul_f32_e32 v27, v27, v26
	v_add_f32_e32 v21, v21, v21
	v_fma_f32 v27, v27, v26, v26
	v_mul_f32_e32 v21, 0xbfb8aa3b, v21
	v_mul_f32_e32 v27, 0x3f4c422a, v27
	v_exp_f32_e32 v21, v21
	v_add_f32_e32 v27, v27, v27
	v_mul_f32_e32 v27, 0xbfb8aa3b, v27
	v_exp_f32_e32 v27, v27
	v_add_f32_e32 v21, 1.0, v21
	v_rcp_f32_e32 v21, v21
	global_store_dwordx2 v[34:35], v[18:19], off offset:576
	v_add_f32_e32 v18, 1.0, v27
	v_rcp_f32_e32 v18, v18
	v_mul_f32_e32 v19, v21, v20
	v_add_f32_e32 v20, v22, v77
	v_lshlrev_b32_e32 v21, 16, v79
	v_mul_f32_e32 v19, v20, v19
	v_add_f32_e32 v20, v23, v77
	v_mul_f32_e32 v22, 0x3d372713, v21
	v_and_b32_e32 v23, 0xffff0000, v79
	v_mul_f32_e32 v18, v18, v26
	v_mul_f32_e32 v22, v22, v21
	v_mul_f32_e32 v26, 0x3d372713, v23
	v_fma_f32 v22, v22, v21, v21
	v_mul_f32_e32 v26, v26, v23
	v_mul_f32_e32 v22, 0x3f4c422a, v22
	v_fma_f32 v26, v26, v23, v23
	v_add_f32_e32 v22, v22, v22
	v_mul_f32_e32 v26, 0x3f4c422a, v26
	v_mul_f32_e32 v22, 0xbfb8aa3b, v22
	v_add_f32_e32 v26, v26, v26
	v_exp_f32_e32 v22, v22
	v_mul_f32_e32 v26, 0xbfb8aa3b, v26
	v_exp_f32_e32 v26, v26
	v_mul_f32_e32 v18, v20, v18
	v_add_f32_e32 v22, 1.0, v22
	v_rcp_f32_e32 v22, v22
	v_add_f32_e32 v20, 1.0, v26
	v_rcp_f32_e32 v20, v20
	v_cvt_pk_bf16_f32 v18, v19, v18
	v_mul_f32_e32 v21, v22, v21
	v_add_f32_e32 v22, v24, v77
	v_mul_f32_e32 v21, v22, v21
	v_mul_f32_e32 v20, v20, v23
	v_add_f32_e32 v22, v25, v77
	v_mul_f32_e32 v20, v22, v20
	v_cvt_pk_bf16_f32 v19, v21, v20
	s_waitcnt vmcnt(14)
	v_lshlrev_b32_e32 v20, 16, v72
	v_mul_f32_e32 v21, 0x3d372713, v20
	v_and_b32_e32 v22, 0xffff0000, v72
	v_mul_f32_e32 v21, v21, v20
	v_mul_f32_e32 v23, 0x3d372713, v22
	v_fma_f32 v21, v21, v20, v20
	v_mul_f32_e32 v23, v23, v22
	v_mul_f32_e32 v21, 0x3f4c422a, v21
	v_fma_f32 v23, v23, v22, v22
	v_add_f32_e32 v21, v21, v21
	v_mul_f32_e32 v23, 0x3f4c422a, v23
	v_mul_f32_e32 v21, 0xbfb8aa3b, v21
	v_add_f32_e32 v23, v23, v23
	v_exp_f32_e32 v21, v21
	v_mul_f32_e32 v23, 0xbfb8aa3b, v23
	v_ashrrev_i32_e32 v77, 31, v76
	v_exp_f32_e32 v23, v23
	global_store_dwordx2 v[34:35], v[18:19], off offset:608
	v_lshlrev_b64 v[18:19], 11, v[76:77]
	v_lshl_add_u64 v[18:19], s[6:7], 0, v[18:19]
	v_lshl_add_u64 v[18:19], v[18:19], 0, v[74:75]
	v_add_f32_e32 v21, 1.0, v21
	v_rcp_f32_e32 v21, v21
	v_lshl_add_u64 v[18:19], v[18:19], 0, v[0:1]
	v_add_f32_e32 v0, 1.0, v23
	v_rcp_f32_e32 v0, v0
	v_mul_f32_e32 v20, v21, v20
	v_add_f32_e32 v14, v14, v104
	v_mul_f32_e32 v14, v14, v20
	v_mul_f32_e32 v0, v0, v22
	v_lshlrev_b32_e32 v20, 16, v73
	v_and_b32_e32 v22, 0xffff0000, v73
	v_mul_f32_e32 v21, 0x3d372713, v20
	v_mul_f32_e32 v23, 0x3d372713, v22
	v_mul_f32_e32 v21, v21, v20
	v_mul_f32_e32 v23, v23, v22
	v_fma_f32 v21, v21, v20, v20
	v_fma_f32 v23, v23, v22, v22
	v_mul_f32_e32 v21, 0x3f4c422a, v21
	v_mul_f32_e32 v23, 0x3f4c422a, v23
	v_add_f32_e32 v21, v21, v21
	v_add_f32_e32 v23, v23, v23
	v_mul_f32_e32 v21, 0xbfb8aa3b, v21
	v_mul_f32_e32 v23, 0xbfb8aa3b, v23
	v_exp_f32_e32 v21, v21
	v_exp_f32_e32 v23, v23
	v_add_f32_e32 v15, v15, v104
	v_mul_f32_e32 v0, v15, v0
	v_add_f32_e32 v21, 1.0, v21
	v_add_f32_e32 v15, 1.0, v23
	v_rcp_f32_e32 v21, v21
	v_rcp_f32_e32 v15, v15
	v_add_f32_e32 v16, v16, v104
	v_add_f32_e32 v17, v17, v104
	v_mul_f32_e32 v20, v21, v20
	v_mul_f32_e32 v15, v15, v22
	v_mul_f32_e32 v16, v16, v20
	v_mul_f32_e32 v15, v17, v15
	v_cvt_pk_bf16_f32 v14, v14, v0
	s_waitcnt vmcnt(14)
; __device__ __forceinline__ unsigned cvt_pk_bf16(float lo, float hi) { unsigned r; asm volatile("v_cvt_pk_bf16_f32 %0, %1, %2" : "=v"(r) : "v"(lo), "v"(hi)); return r; }
; __device__ __forceinline__ float bf_lo(unsigned w) { return __uint_as_float(w << 16); }
; __device__ __forceinline__ float bf_hi(unsigned w) { return __uint_as_float(w & 0xffff0000u); }
; __device__ __forceinline__ float gelu_tanh(float x) { const float z = 0.7978845608028654f * (x + 0.044715f * x * x * x); return x * sigmoidf_(2.0f * z); }
; __device__ __forceinline__ void gmlp_conv_item(const Params& p, int l, int hs, int chunk, LAS unsigned char* lds) {
;     ...
;       for (int pb = 0; pb < 4; ++pb) { const int pt = (ph * 4 + pb) * 16 + fr;
;           bf16_t* yp = Y + (size_t)(v0 + pt) * D + 256 + g * 64 + fq * 4;
; #pragma unroll
;           for (int db = 0; db < 4; ++db) { const u32x2 w = uw[pb][db];
;               const float y0 = gelu_tanh(bf_lo(w.x)) * (acc[db][pb][0] + bias[pb]), y1 = gelu_tanh(bf_hi(w.x)) * (acc[db][pb][1] + bias[pb]);
;               const float y2 = gelu_tanh(bf_lo(w.y)) * (acc[db][pb][2] + bias[pb]), y3 = gelu_tanh(bf_hi(w.y)) * (acc[db][pb][3] + bias[pb]);
;               u32x2 ov; ov.x = cvt_pk_bf16(y0, y1); ov.y = cvt_pk_bf16(y2, y3); *(u32x2*)(yp + db * 16) = ov; } } }
;     __syncthreads();
	v_lshlrev_b32_e32 v0, 16, v70
	v_cvt_pk_bf16_f32 v15, v16, v15
	v_mul_f32_e32 v16, 0x3d372713, v0
	v_and_b32_e32 v17, 0xffff0000, v70
	v_mul_f32_e32 v16, v16, v0
	v_mul_f32_e32 v20, 0x3d372713, v17
	v_fma_f32 v16, v16, v0, v0
	v_mul_f32_e32 v20, v20, v17
	v_mul_f32_e32 v16, 0x3f4c422a, v16
	v_fma_f32 v20, v20, v17, v17
	v_add_f32_e32 v16, v16, v16
	v_mul_f32_e32 v20, 0x3f4c422a, v20
	v_mul_f32_e32 v16, 0xbfb8aa3b, v16
	v_add_f32_e32 v20, v20, v20
	v_exp_f32_e32 v16, v16
	v_mul_f32_e32 v20, 0xbfb8aa3b, v20
	v_exp_f32_e32 v20, v20
	global_store_dwordx2 v[18:19], v[14:15], off offset:512
	v_add_f32_e32 v16, 1.0, v16
	v_rcp_f32_e32 v16, v16
	v_add_f32_e32 v14, 1.0, v20
	v_rcp_f32_e32 v14, v14
	v_add_f32_e32 v10, v10, v104
	v_mul_f32_e32 v0, v16, v0
	v_mul_f32_e32 v0, v10, v0
	v_mul_f32_e32 v10, v14, v17
	v_lshlrev_b32_e32 v14, 16, v71
	v_and_b32_e32 v16, 0xffff0000, v71
	v_mul_f32_e32 v15, 0x3d372713, v14
	v_mul_f32_e32 v17, 0x3d372713, v16
	v_mul_f32_e32 v15, v15, v14
	v_mul_f32_e32 v17, v17, v16
	v_fma_f32 v15, v15, v14, v14
	v_fma_f32 v17, v17, v16, v16
	v_mul_f32_e32 v15, 0x3f4c422a, v15
	v_mul_f32_e32 v17, 0x3f4c422a, v17
	v_add_f32_e32 v15, v15, v15
	v_add_f32_e32 v17, v17, v17
	v_mul_f32_e32 v15, 0xbfb8aa3b, v15
	v_mul_f32_e32 v17, 0xbfb8aa3b, v17
	v_exp_f32_e32 v15, v15
	v_exp_f32_e32 v17, v17
	v_add_f32_e32 v11, v11, v104
	v_mul_f32_e32 v10, v11, v10
	v_add_f32_e32 v15, 1.0, v15
	v_add_f32_e32 v11, 1.0, v17
	v_rcp_f32_e32 v15, v15
	v_rcp_f32_e32 v11, v11
	v_add_f32_e32 v12, v12, v104
	v_add_f32_e32 v13, v13, v104
	v_mul_f32_e32 v14, v15, v14
	v_mul_f32_e32 v11, v11, v16
	v_mul_f32_e32 v12, v12, v14
	v_mul_f32_e32 v11, v13, v11
	v_cvt_pk_bf16_f32 v10, v0, v10
	s_waitcnt vmcnt(14)
	v_lshlrev_b32_e32 v0, 16, v68
	v_cvt_pk_bf16_f32 v11, v12, v11
	v_mul_f32_e32 v12, 0x3d372713, v0
	v_and_b32_e32 v13, 0xffff0000, v68
	v_mul_f32_e32 v12, v12, v0
	v_mul_f32_e32 v14, 0x3d372713, v13
	v_fma_f32 v12, v12, v0, v0
	v_mul_f32_e32 v14, v14, v13
	v_mul_f32_e32 v12, 0x3f4c422a, v12
	v_fma_f32 v14, v14, v13, v13
	v_add_f32_e32 v12, v12, v12
	v_mul_f32_e32 v14, 0x3f4c422a, v14
	v_mul_f32_e32 v12, 0xbfb8aa3b, v12
	v_add_f32_e32 v14, v14, v14
	v_exp_f32_e32 v12, v12
	v_mul_f32_e32 v14, 0xbfb8aa3b, v14
	v_exp_f32_e32 v14, v14
	global_store_dwordx2 v[18:19], v[10:11], off offset:544
	v_add_f32_e32 v12, 1.0, v12
	v_rcp_f32_e32 v12, v12
	v_add_f32_e32 v10, 1.0, v14
	v_rcp_f32_e32 v10, v10
	v_add_f32_e32 v2, v2, v104
	v_mul_f32_e32 v0, v12, v0
	v_mul_f32_e32 v0, v2, v0
	v_mul_f32_e32 v2, v10, v13
	v_lshlrev_b32_e32 v10, 16, v69
	v_and_b32_e32 v12, 0xffff0000, v69
	v_mul_f32_e32 v11, 0x3d372713, v10
	v_mul_f32_e32 v13, 0x3d372713, v12
	v_mul_f32_e32 v11, v11, v10
	v_mul_f32_e32 v13, v13, v12
	v_fma_f32 v11, v11, v10, v10
	v_fma_f32 v13, v13, v12, v12
	v_mul_f32_e32 v11, 0x3f4c422a, v11
	v_mul_f32_e32 v13, 0x3f4c422a, v13
	v_add_f32_e32 v11, v11, v11
	v_add_f32_e32 v13, v13, v13
	v_mul_f32_e32 v11, 0xbfb8aa3b, v11
	v_mul_f32_e32 v13, 0xbfb8aa3b, v13
	v_exp_f32_e32 v11, v11
	v_exp_f32_e32 v13, v13
	v_add_f32_e32 v3, v3, v104
	v_mul_f32_e32 v2, v3, v2
	v_add_f32_e32 v11, 1.0, v11
	v_add_f32_e32 v3, 1.0, v13
	v_rcp_f32_e32 v11, v11
	v_rcp_f32_e32 v3, v3
	v_add_f32_e32 v4, v4, v104
	v_add_f32_e32 v5, v5, v104
	v_mul_f32_e32 v10, v11, v10
	v_mul_f32_e32 v3, v3, v12
	v_mul_f32_e32 v4, v4, v10
	v_mul_f32_e32 v3, v5, v3
	v_cvt_pk_bf16_f32 v2, v0, v2
	s_waitcnt vmcnt(14)
	v_lshlrev_b32_e32 v0, 16, v66
	v_cvt_pk_bf16_f32 v3, v4, v3
	v_mul_f32_e32 v4, 0x3d372713, v0
	v_and_b32_e32 v5, 0xffff0000, v66
	v_mul_f32_e32 v4, v4, v0
	v_mul_f32_e32 v10, 0x3d372713, v5
	v_fma_f32 v4, v4, v0, v0
	v_mul_f32_e32 v10, v10, v5
	v_mul_f32_e32 v4, 0x3f4c422a, v4
	v_fma_f32 v10, v10, v5, v5
	v_add_f32_e32 v4, v4, v4
	v_mul_f32_e32 v10, 0x3f4c422a, v10
	v_mul_f32_e32 v4, 0xbfb8aa3b, v4
	v_add_f32_e32 v10, v10, v10
	v_exp_f32_e32 v4, v4
	v_mul_f32_e32 v10, 0xbfb8aa3b, v10
	v_exp_f32_e32 v10, v10
	global_store_dwordx2 v[18:19], v[2:3], off offset:576
	v_add_f32_e32 v4, 1.0, v4
	v_rcp_f32_e32 v4, v4
	v_add_f32_e32 v2, 1.0, v10
	v_rcp_f32_e32 v2, v2
	v_add_f32_e32 v3, v6, v104
	v_mul_f32_e32 v0, v4, v0
	v_lshlrev_b32_e32 v4, 16, v67
	v_mul_f32_e32 v2, v2, v5
	v_mul_f32_e32 v5, 0x3d372713, v4
	v_and_b32_e32 v6, 0xffff0000, v67
	v_mul_f32_e32 v0, v3, v0
	v_add_f32_e32 v3, v7, v104
	v_mul_f32_e32 v5, v5, v4
	v_mul_f32_e32 v7, 0x3d372713, v6
	v_fma_f32 v5, v5, v4, v4
	v_mul_f32_e32 v7, v7, v6
	v_mul_f32_e32 v5, 0x3f4c422a, v5
	v_fma_f32 v7, v7, v6, v6
	v_add_f32_e32 v5, v5, v5
	v_mul_f32_e32 v7, 0x3f4c422a, v7
	v_mul_f32_e32 v5, 0xbfb8aa3b, v5
	v_add_f32_e32 v7, v7, v7
	v_exp_f32_e32 v5, v5
	v_mul_f32_e32 v7, 0xbfb8aa3b, v7
	v_exp_f32_e32 v7, v7
	v_mul_f32_e32 v2, v3, v2
	v_add_f32_e32 v5, 1.0, v5
	v_rcp_f32_e32 v5, v5
	v_add_f32_e32 v3, 1.0, v7
	v_rcp_f32_e32 v3, v3
	v_cvt_pk_bf16_f32 v2, v0, v2
	v_mul_f32_e32 v4, v5, v4
	v_add_f32_e32 v5, v8, v104
	v_mul_f32_e32 v4, v5, v4
	v_mul_f32_e32 v3, v3, v6
	v_add_f32_e32 v5, v9, v104
	v_mul_f32_e32 v3, v5, v3
	v_cvt_pk_bf16_f32 v3, v4, v3
	global_store_dwordx2 v[18:19], v[2:3], off offset:608
	s_barrier
	s_cbranch_scc1 .LBB0_184
